# replace IEEE f32 1/x division chains in silu/sigmoid epilogues with v_rcp_f32
# speedup vs baseline: 1.0212x; 1.0212x over previous
; DEV u32x2 pk4(f32x4 v) { u32x2 r = {pk_bf16(v[0], v[1]), pk_bf16(v[2], v[3])}; return r; }
; DEV float fsigmoid(float x) { return 1.f / (1.f + __expf(-x)); }
;   DEV void operator()(f32x4 (&acc)[2][2][4][2], int brow, int bcol, int wr, int wc, int fr, int fq) const {
;     ...
;             } else if (mode == 2) {
;               for (int j = 0; j < 4; ++j) v[j] = fsigmoid(v[j]);
;               tile_put4(rl, cl, pk4(v));
.LBB0_628:
	s_andn2_b64 vcc, exec, s[0:1]
	s_cbranch_vccnz .LBB0_630
	s_waitcnt vmcnt(0)
	v_mul_f32_e32 v128, 0xbfb8aa3b, v124
	v_mul_f32_e32 v129, 0xbfb8aa3b, v125
	v_exp_f32_e32 v128, v128
	v_exp_f32_e32 v129, v129
	s_nop 0
	v_pk_add_f32 v[128:129], v[128:129], 1.0 op_sel_hi:[1,0]
	s_nop 0
	s_nop 0
	v_rcp_f32_e32 v130, v129
	s_nop 0
	v_rcp_f32_e32 v131, v128
	v_mul_f32_e32 v128, 0xbfb8aa3b, v126
	v_mul_f32_e32 v129, 0xbfb8aa3b, v127
	v_exp_f32_e32 v128, v128
	v_exp_f32_e32 v129, v129
	s_nop 0
	v_pk_add_f32 v[128:129], v[128:129], 1.0 op_sel_hi:[1,0]
	s_nop 0
	s_nop 0
	v_rcp_f32_e32 v129, v129
	s_nop 0
	v_rcp_f32_e32 v133, v128
	v_cvt_pk_bf16_f32 v128, v131, v130
	v_lshrrev_b32_e32 v130, 3, v204
	v_xor_b32_e32 v130, v130, v202
	v_lshlrev_b32_e32 v131, 3, v137
	v_lshlrev_b32_e32 v130, 4, v130
	v_and_b32_e32 v131, 8, v131
	v_cvt_pk_bf16_f32 v129, v133, v129
	v_add3_u32 v130, v136, v130, v131
	ds_write_b64 v130, v[128:129]

; DEV u32x2 pk4(f32x4 v) { u32x2 r = {pk_bf16(v[0], v[1]), pk_bf16(v[2], v[3])}; return r; }
; DEV float fsigmoid(float x) { return 1.f / (1.f + __expf(-x)); }
;   DEV void operator()(f32x4 (&acc)[2][2][4][2], int brow, int bcol, int wr, int wc, int fr, int fq) const {
;     ...
;             } else if (mode == 1) {
;               for (int j = 0; j < 4; ++j) v[j] = v[j] * fsigmoid(v[j]);
;               tile_put4(rl, cl, pk4(v));
.LBB0_631:
	s_andn2_b64 vcc, exec, s[0:1]
	s_cbranch_vccnz .LBB0_633
	s_waitcnt vmcnt(0)
	v_mul_f32_e32 v128, 0xbfb8aa3b, v124
	v_mul_f32_e32 v129, 0xbfb8aa3b, v125
	v_exp_f32_e32 v128, v128
	v_exp_f32_e32 v129, v129
	s_nop 0
	v_pk_add_f32 v[128:129], v[128:129], 1.0 op_sel_hi:[1,0]
	s_nop 0
	s_nop 0
	v_rcp_f32_e32 v129, v129
	s_nop 0
	v_rcp_f32_e32 v128, v128
	v_mul_f32_e32 v130, 0xbfb8aa3b, v126
	v_mul_f32_e32 v131, 0xbfb8aa3b, v127
	v_exp_f32_e32 v130, v130
	v_exp_f32_e32 v131, v131
	v_pk_mul_f32 v[128:129], v[124:125], v[128:129]
	v_pk_add_f32 v[130:131], v[130:131], 1.0 op_sel_hi:[1,0]
	s_nop 0
	v_cvt_pk_bf16_f32 v128, v128, v129
	v_rcp_f32_e32 v131, v131
	s_nop 0
	v_rcp_f32_e32 v130, v130
	s_nop 0
	v_pk_mul_f32 v[130:131], v[126:127], v[130:131]
	s_nop 0
	v_cvt_pk_bf16_f32 v129, v130, v131
	v_lshrrev_b32_e32 v130, 3, v204
	v_xor_b32_e32 v130, v130, v202
	v_lshlrev_b32_e32 v131, 3, v137
	v_lshlrev_b32_e32 v130, 4, v130
	v_and_b32_e32 v131, 8, v131
	v_add3_u32 v130, v136, v130, v131
	ds_write_b64 v130, v[128:129]

; DEV u32x2 pk4(f32x4 v) { u32x2 r = {pk_bf16(v[0], v[1]), pk_bf16(v[2], v[3])}; return r; }
; DEV float fsigmoid(float x) { return 1.f / (1.f + __expf(-x)); }
;   DEV void operator()(f32x4 (&acc)[2][2][4][2], int brow, int bcol, int wr, int wc, int fr, int fq) const {
;     ...
;             } else if (mode == 2) {
;               for (int j = 0; j < 4; ++j) v[j] = fsigmoid(v[j]);
;               tile_put4(rl, cl, pk4(v));
.LBB0_644:
	s_andn2_b64 vcc, exec, s[0:1]
	s_cbranch_vccnz .LBB0_646
	s_waitcnt vmcnt(0)
	v_mul_f32_e32 v128, 0xbfb8aa3b, v120
	v_mul_f32_e32 v129, 0xbfb8aa3b, v121
	v_exp_f32_e32 v128, v128
	v_exp_f32_e32 v129, v129
	s_nop 0
	v_pk_add_f32 v[128:129], v[128:129], 1.0 op_sel_hi:[1,0]
	s_nop 0
	s_nop 0
	v_rcp_f32_e32 v130, v129
	s_nop 0
	v_rcp_f32_e32 v131, v128
	v_mul_f32_e32 v128, 0xbfb8aa3b, v122
	v_mul_f32_e32 v129, 0xbfb8aa3b, v123
	v_exp_f32_e32 v128, v128
	v_exp_f32_e32 v129, v129
	s_nop 0
	v_pk_add_f32 v[128:129], v[128:129], 1.0 op_sel_hi:[1,0]
	s_nop 0
	s_nop 0
	v_rcp_f32_e32 v129, v129
	s_nop 0
	v_rcp_f32_e32 v137, v128
	v_cvt_pk_bf16_f32 v128, v131, v130
	v_lshrrev_b32_e32 v130, 3, v146
	v_xor_b32_e32 v130, v130, v202
	v_lshlrev_b32_e32 v130, 4, v130
	v_cvt_pk_bf16_f32 v129, v137, v129
	v_add3_u32 v130, v136, v130, v133
	ds_write_b64 v130, v[128:129]

; DEV u32x2 pk4(f32x4 v) { u32x2 r = {pk_bf16(v[0], v[1]), pk_bf16(v[2], v[3])}; return r; }
; DEV float fsigmoid(float x) { return 1.f / (1.f + __expf(-x)); }
;   DEV void operator()(f32x4 (&acc)[2][2][4][2], int brow, int bcol, int wr, int wc, int fr, int fq) const {
;     ...
;             } else if (mode == 1) {
;               for (int j = 0; j < 4; ++j) v[j] = v[j] * fsigmoid(v[j]);
;               tile_put4(rl, cl, pk4(v));
.LBB0_647:
	s_andn2_b64 vcc, exec, s[0:1]
	s_cbranch_vccnz .LBB0_649
	s_waitcnt vmcnt(0)
	v_mul_f32_e32 v128, 0xbfb8aa3b, v120
	v_mul_f32_e32 v129, 0xbfb8aa3b, v121
	v_exp_f32_e32 v128, v128
	v_exp_f32_e32 v129, v129
	s_nop 0
	v_pk_add_f32 v[128:129], v[128:129], 1.0 op_sel_hi:[1,0]
	s_nop 0
	s_nop 0
	v_rcp_f32_e32 v129, v129
	s_nop 0
	v_rcp_f32_e32 v128, v128
	v_mul_f32_e32 v130, 0xbfb8aa3b, v122
	v_mul_f32_e32 v131, 0xbfb8aa3b, v123
	v_exp_f32_e32 v130, v130
	v_exp_f32_e32 v131, v131
	v_pk_mul_f32 v[128:129], v[120:121], v[128:129]
	v_pk_add_f32 v[130:131], v[130:131], 1.0 op_sel_hi:[1,0]
	s_nop 0
	v_cvt_pk_bf16_f32 v128, v128, v129
	v_rcp_f32_e32 v131, v131
	s_nop 0
	v_rcp_f32_e32 v130, v130
	s_nop 0
	v_pk_mul_f32 v[130:131], v[122:123], v[130:131]
	s_nop 0
	v_cvt_pk_bf16_f32 v129, v130, v131
	v_lshrrev_b32_e32 v130, 3, v146
	v_xor_b32_e32 v130, v130, v202
	v_lshlrev_b32_e32 v130, 4, v130
	v_add3_u32 v130, v136, v130, v133
	ds_write_b64 v130, v[128:129]

; DEV u32x2 pk4(f32x4 v) { u32x2 r = {pk_bf16(v[0], v[1]), pk_bf16(v[2], v[3])}; return r; }
; DEV float fsigmoid(float x) { return 1.f / (1.f + __expf(-x)); }
;   DEV void operator()(f32x4 (&acc)[2][2][4][2], int brow, int bcol, int wr, int wc, int fr, int fq) const {
;     ...
;             } else if (mode == 2) {
;               for (int j = 0; j < 4; ++j) v[j] = fsigmoid(v[j]);
;               tile_put4(rl, cl, pk4(v));
.LBB0_660:
	s_andn2_b64 vcc, exec, s[0:1]
	s_cbranch_vccnz .LBB0_662
	s_waitcnt vmcnt(0)
	v_mul_f32_e32 v128, 0xbfb8aa3b, v116
	v_mul_f32_e32 v129, 0xbfb8aa3b, v117
	v_exp_f32_e32 v128, v128
	v_exp_f32_e32 v129, v129
	s_nop 0
	v_pk_add_f32 v[128:129], v[128:129], 1.0 op_sel_hi:[1,0]
	s_nop 0
	s_nop 0
	v_rcp_f32_e32 v130, v129
	s_nop 0
	v_rcp_f32_e32 v131, v128
	v_mul_f32_e32 v128, 0xbfb8aa3b, v118
	v_mul_f32_e32 v129, 0xbfb8aa3b, v119
	v_exp_f32_e32 v128, v128
	v_exp_f32_e32 v129, v129
	s_nop 0
	v_pk_add_f32 v[128:129], v[128:129], 1.0 op_sel_hi:[1,0]
	s_nop 0
	s_nop 0
	v_rcp_f32_e32 v129, v129
	s_nop 0
	v_rcp_f32_e32 v137, v128
	v_cvt_pk_bf16_f32 v128, v131, v130
	v_lshrrev_b32_e32 v130, 3, v148
	v_xor_b32_e32 v130, v130, v202
	v_lshlrev_b32_e32 v130, 4, v130
	v_cvt_pk_bf16_f32 v129, v137, v129
	v_add3_u32 v130, v136, v130, v133
	ds_write_b64 v130, v[128:129]

; DEV u32x2 pk4(f32x4 v) { u32x2 r = {pk_bf16(v[0], v[1]), pk_bf16(v[2], v[3])}; return r; }
; DEV float fsigmoid(float x) { return 1.f / (1.f + __expf(-x)); }
;   DEV void operator()(f32x4 (&acc)[2][2][4][2], int brow, int bcol, int wr, int wc, int fr, int fq) const {
;     ...
;             } else if (mode == 1) {
;               for (int j = 0; j < 4; ++j) v[j] = v[j] * fsigmoid(v[j]);
;               tile_put4(rl, cl, pk4(v));
.LBB0_663:
	s_andn2_b64 vcc, exec, s[0:1]
	s_cbranch_vccnz .LBB0_665
	s_waitcnt vmcnt(0)
	v_mul_f32_e32 v128, 0xbfb8aa3b, v116
	v_mul_f32_e32 v129, 0xbfb8aa3b, v117
	v_exp_f32_e32 v128, v128
	v_exp_f32_e32 v129, v129
	s_nop 0
	v_pk_add_f32 v[128:129], v[128:129], 1.0 op_sel_hi:[1,0]
	s_nop 0
	s_nop 0
	v_rcp_f32_e32 v129, v129
	s_nop 0
	v_rcp_f32_e32 v128, v128
	v_mul_f32_e32 v130, 0xbfb8aa3b, v118
	v_mul_f32_e32 v131, 0xbfb8aa3b, v119
	v_exp_f32_e32 v130, v130
	v_exp_f32_e32 v131, v131
	v_pk_mul_f32 v[128:129], v[116:117], v[128:129]
	v_pk_add_f32 v[130:131], v[130:131], 1.0 op_sel_hi:[1,0]
	s_nop 0
	v_cvt_pk_bf16_f32 v128, v128, v129
	v_rcp_f32_e32 v131, v131
	s_nop 0
	v_rcp_f32_e32 v130, v130
	s_nop 0
	v_pk_mul_f32 v[130:131], v[118:119], v[130:131]
	s_nop 0
	v_cvt_pk_bf16_f32 v129, v130, v131
	v_lshrrev_b32_e32 v130, 3, v148
	v_xor_b32_e32 v130, v130, v202
	v_lshlrev_b32_e32 v130, 4, v130
	v_add3_u32 v130, v136, v130, v133
	ds_write_b64 v130, v[128:129]

; DEV u32x2 pk4(f32x4 v) { u32x2 r = {pk_bf16(v[0], v[1]), pk_bf16(v[2], v[3])}; return r; }
; DEV float fsigmoid(float x) { return 1.f / (1.f + __expf(-x)); }
;   DEV void operator()(f32x4 (&acc)[2][2][4][2], int brow, int bcol, int wr, int wc, int fr, int fq) const {
;     ...
;             } else if (mode == 2) {
;               for (int j = 0; j < 4; ++j) v[j] = fsigmoid(v[j]);
;               tile_put4(rl, cl, pk4(v));
.LBB0_676:
	s_andn2_b64 vcc, exec, s[0:1]
	s_cbranch_vccnz .LBB0_678
	s_waitcnt vmcnt(0)
	v_mul_f32_e32 v128, 0xbfb8aa3b, v112
	v_mul_f32_e32 v129, 0xbfb8aa3b, v113
	v_exp_f32_e32 v128, v128
	v_exp_f32_e32 v129, v129
	s_nop 0
	v_pk_add_f32 v[128:129], v[128:129], 1.0 op_sel_hi:[1,0]
	s_nop 0
	s_nop 0
	v_rcp_f32_e32 v130, v129
	s_nop 0
	v_rcp_f32_e32 v131, v128
	v_mul_f32_e32 v128, 0xbfb8aa3b, v114
	v_mul_f32_e32 v129, 0xbfb8aa3b, v115
	v_exp_f32_e32 v128, v128
	v_exp_f32_e32 v129, v129
	s_nop 0
	v_pk_add_f32 v[128:129], v[128:129], 1.0 op_sel_hi:[1,0]
	s_nop 0
	s_nop 0
	v_rcp_f32_e32 v129, v129
	s_nop 0
	v_rcp_f32_e32 v137, v128
	v_cvt_pk_bf16_f32 v128, v131, v130
	v_lshrrev_b32_e32 v130, 3, v149
	v_xor_b32_e32 v130, v130, v202
	v_lshlrev_b32_e32 v130, 4, v130
	v_cvt_pk_bf16_f32 v129, v137, v129
	v_add3_u32 v130, v136, v130, v133
	ds_write_b64 v130, v[128:129]

; DEV u32x2 pk4(f32x4 v) { u32x2 r = {pk_bf16(v[0], v[1]), pk_bf16(v[2], v[3])}; return r; }
; DEV float fsigmoid(float x) { return 1.f / (1.f + __expf(-x)); }
;   DEV void operator()(f32x4 (&acc)[2][2][4][2], int brow, int bcol, int wr, int wc, int fr, int fq) const {
;     ...
;             } else if (mode == 1) {
;               for (int j = 0; j < 4; ++j) v[j] = v[j] * fsigmoid(v[j]);
;               tile_put4(rl, cl, pk4(v));
.LBB0_679:
	s_andn2_b64 vcc, exec, s[0:1]
	s_cbranch_vccnz .LBB0_681
	s_waitcnt vmcnt(0)
	v_mul_f32_e32 v128, 0xbfb8aa3b, v112
	v_mul_f32_e32 v129, 0xbfb8aa3b, v113
	v_exp_f32_e32 v128, v128
	v_exp_f32_e32 v129, v129
	s_nop 0
	v_pk_add_f32 v[128:129], v[128:129], 1.0 op_sel_hi:[1,0]
	s_nop 0
	s_nop 0
	v_rcp_f32_e32 v129, v129
	s_nop 0
	v_rcp_f32_e32 v128, v128
	v_mul_f32_e32 v130, 0xbfb8aa3b, v114
	v_mul_f32_e32 v131, 0xbfb8aa3b, v115
	v_exp_f32_e32 v130, v130
	v_exp_f32_e32 v131, v131
	v_pk_mul_f32 v[128:129], v[112:113], v[128:129]
	v_pk_add_f32 v[130:131], v[130:131], 1.0 op_sel_hi:[1,0]
	s_nop 0
	v_cvt_pk_bf16_f32 v128, v128, v129
	v_rcp_f32_e32 v131, v131
	s_nop 0
	v_rcp_f32_e32 v130, v130
	s_nop 0
	v_pk_mul_f32 v[130:131], v[114:115], v[130:131]
	s_nop 0
	v_cvt_pk_bf16_f32 v129, v130, v131
	v_lshrrev_b32_e32 v130, 3, v149
	v_xor_b32_e32 v130, v130, v202
	v_lshlrev_b32_e32 v130, 4, v130
	v_add3_u32 v130, v136, v130, v133
	ds_write_b64 v130, v[128:129]

; DEV u32x2 pk4(f32x4 v) { u32x2 r = {pk_bf16(v[0], v[1]), pk_bf16(v[2], v[3])}; return r; }
; DEV float fsigmoid(float x) { return 1.f / (1.f + __expf(-x)); }
;   DEV void operator()(f32x4 (&acc)[2][2][4][2], int brow, int bcol, int wr, int wc, int fr, int fq) const {
;     ...
;             } else if (mode == 2) {
;               for (int j = 0; j < 4; ++j) v[j] = fsigmoid(v[j]);
;               tile_put4(rl, cl, pk4(v));
.LBB0_692:
	s_andn2_b64 vcc, exec, s[0:1]
	s_cbranch_vccnz .LBB0_694
	s_waitcnt vmcnt(0)
	v_mul_f32_e32 v128, 0xbfb8aa3b, v108
	v_mul_f32_e32 v129, 0xbfb8aa3b, v109
	v_exp_f32_e32 v128, v128
	v_exp_f32_e32 v129, v129
	s_nop 0
	v_pk_add_f32 v[128:129], v[128:129], 1.0 op_sel_hi:[1,0]
	s_nop 0
	s_nop 0
	v_rcp_f32_e32 v130, v129
	s_nop 0
	v_rcp_f32_e32 v131, v128
	v_mul_f32_e32 v128, 0xbfb8aa3b, v110
	v_mul_f32_e32 v129, 0xbfb8aa3b, v111
	v_exp_f32_e32 v128, v128
	v_exp_f32_e32 v129, v129
	s_nop 0
	v_pk_add_f32 v[128:129], v[128:129], 1.0 op_sel_hi:[1,0]
	s_nop 0
	s_nop 0
	v_rcp_f32_e32 v129, v129
	s_nop 0
	v_rcp_f32_e32 v160, v128
	v_cvt_pk_bf16_f32 v128, v131, v130
	v_xor_b32_e32 v130, v155, v150
	v_lshlrev_b32_e32 v130, 4, v130
	v_cvt_pk_bf16_f32 v129, v160, v129
	v_add3_u32 v130, v159, v130, v133
	ds_write_b64 v130, v[128:129]

; DEV u32x2 pk4(f32x4 v) { u32x2 r = {pk_bf16(v[0], v[1]), pk_bf16(v[2], v[3])}; return r; }
; DEV float fsigmoid(float x) { return 1.f / (1.f + __expf(-x)); }
;   DEV void operator()(f32x4 (&acc)[2][2][4][2], int brow, int bcol, int wr, int wc, int fr, int fq) const {
;     ...
;             } else if (mode == 1) {
;               for (int j = 0; j < 4; ++j) v[j] = v[j] * fsigmoid(v[j]);
;               tile_put4(rl, cl, pk4(v));
.LBB0_695:
	s_andn2_b64 vcc, exec, s[0:1]
	s_cbranch_vccnz .LBB0_697
	s_waitcnt vmcnt(0)
	v_mul_f32_e32 v128, 0xbfb8aa3b, v108
	v_mul_f32_e32 v129, 0xbfb8aa3b, v109
	v_exp_f32_e32 v128, v128
	v_exp_f32_e32 v129, v129
	s_nop 0
	v_pk_add_f32 v[128:129], v[128:129], 1.0 op_sel_hi:[1,0]
	s_nop 0
	s_nop 0
	v_rcp_f32_e32 v129, v129
	s_nop 0
	v_rcp_f32_e32 v128, v128
	v_mul_f32_e32 v130, 0xbfb8aa3b, v110
	v_mul_f32_e32 v131, 0xbfb8aa3b, v111
	v_exp_f32_e32 v130, v130
	v_exp_f32_e32 v131, v131
	v_pk_mul_f32 v[128:129], v[108:109], v[128:129]
	v_pk_add_f32 v[130:131], v[130:131], 1.0 op_sel_hi:[1,0]
	s_nop 0
	v_cvt_pk_bf16_f32 v128, v128, v129
	v_rcp_f32_e32 v131, v131
	s_nop 0
	v_rcp_f32_e32 v130, v130
	s_nop 0
	v_pk_mul_f32 v[130:131], v[110:111], v[130:131]
	s_nop 0
	v_cvt_pk_bf16_f32 v129, v130, v131
	v_xor_b32_e32 v130, v155, v150
	v_lshlrev_b32_e32 v130, 4, v130
	v_add3_u32 v130, v159, v130, v133
	ds_write_b64 v130, v[128:129]

; DEV u32x2 pk4(f32x4 v) { u32x2 r = {pk_bf16(v[0], v[1]), pk_bf16(v[2], v[3])}; return r; }
; DEV float fsigmoid(float x) { return 1.f / (1.f + __expf(-x)); }
;   DEV void operator()(f32x4 (&acc)[2][2][4][2], int brow, int bcol, int wr, int wc, int fr, int fq) const {
;     ...
;             } else if (mode == 2) {
;               for (int j = 0; j < 4; ++j) v[j] = fsigmoid(v[j]);
;               tile_put4(rl, cl, pk4(v));
.LBB0_706:
	s_andn2_b64 vcc, exec, s[0:1]
	s_cbranch_vccnz .LBB0_708
	s_waitcnt vmcnt(0)
	v_mul_f32_e32 v128, 0xbfb8aa3b, v104
	v_mul_f32_e32 v129, 0xbfb8aa3b, v105
	v_exp_f32_e32 v128, v128
	v_exp_f32_e32 v129, v129
	s_nop 0
	v_pk_add_f32 v[128:129], v[128:129], 1.0 op_sel_hi:[1,0]
	s_nop 0
	s_nop 0
	v_rcp_f32_e32 v130, v129
	s_nop 0
	v_rcp_f32_e32 v131, v128
	v_mul_f32_e32 v128, 0xbfb8aa3b, v106
	v_mul_f32_e32 v129, 0xbfb8aa3b, v107
	v_exp_f32_e32 v128, v128
	v_exp_f32_e32 v129, v129
	s_nop 0
	v_pk_add_f32 v[128:129], v[128:129], 1.0 op_sel_hi:[1,0]
	s_nop 0
	s_nop 0
	v_rcp_f32_e32 v129, v129
	s_nop 0
	v_rcp_f32_e32 v160, v128
	v_cvt_pk_bf16_f32 v128, v131, v130
	v_xor_b32_e32 v130, v156, v150
	v_lshlrev_b32_e32 v130, 4, v130
	v_cvt_pk_bf16_f32 v129, v160, v129
	v_add3_u32 v130, v159, v130, v133
	ds_write_b64 v130, v[128:129]

; DEV u32x2 pk4(f32x4 v) { u32x2 r = {pk_bf16(v[0], v[1]), pk_bf16(v[2], v[3])}; return r; }
; DEV float fsigmoid(float x) { return 1.f / (1.f + __expf(-x)); }
;   DEV void operator()(f32x4 (&acc)[2][2][4][2], int brow, int bcol, int wr, int wc, int fr, int fq) const {
;     ...
;             } else if (mode == 1) {
;               for (int j = 0; j < 4; ++j) v[j] = v[j] * fsigmoid(v[j]);
;               tile_put4(rl, cl, pk4(v));
.LBB0_709:
	s_andn2_b64 vcc, exec, s[0:1]
	s_cbranch_vccnz .LBB0_711
	s_waitcnt vmcnt(0)
	v_mul_f32_e32 v128, 0xbfb8aa3b, v104
	v_mul_f32_e32 v129, 0xbfb8aa3b, v105
	v_exp_f32_e32 v128, v128
	v_exp_f32_e32 v129, v129
	s_nop 0
	v_pk_add_f32 v[128:129], v[128:129], 1.0 op_sel_hi:[1,0]
	s_nop 0
	s_nop 0
	v_rcp_f32_e32 v129, v129
	s_nop 0
	v_rcp_f32_e32 v128, v128
	v_mul_f32_e32 v130, 0xbfb8aa3b, v106
	v_mul_f32_e32 v131, 0xbfb8aa3b, v107
	v_exp_f32_e32 v130, v130
	v_exp_f32_e32 v131, v131
	v_pk_mul_f32 v[128:129], v[104:105], v[128:129]
	v_pk_add_f32 v[130:131], v[130:131], 1.0 op_sel_hi:[1,0]
	s_nop 0
	v_cvt_pk_bf16_f32 v128, v128, v129
	v_rcp_f32_e32 v131, v131
	s_nop 0
	v_rcp_f32_e32 v130, v130
	s_nop 0
	v_pk_mul_f32 v[130:131], v[106:107], v[130:131]
	s_nop 0
	v_cvt_pk_bf16_f32 v129, v130, v131
	v_xor_b32_e32 v130, v156, v150
	v_lshlrev_b32_e32 v130, 4, v130
	v_add3_u32 v130, v159, v130, v133
	ds_write_b64 v130, v[128:129]

; DEV u32x2 pk4(f32x4 v) { u32x2 r = {pk_bf16(v[0], v[1]), pk_bf16(v[2], v[3])}; return r; }
; DEV float fsigmoid(float x) { return 1.f / (1.f + __expf(-x)); }
;   DEV void operator()(f32x4 (&acc)[2][2][4][2], int brow, int bcol, int wr, int wc, int fr, int fq) const {
;     ...
;             } else if (mode == 2) {
;               for (int j = 0; j < 4; ++j) v[j] = fsigmoid(v[j]);
;               tile_put4(rl, cl, pk4(v));
.LBB0_720:
	s_andn2_b64 vcc, exec, s[0:1]
	s_cbranch_vccnz .LBB0_722
	s_waitcnt vmcnt(0)
	v_mul_f32_e32 v128, 0xbfb8aa3b, v100
	v_mul_f32_e32 v129, 0xbfb8aa3b, v101
	v_exp_f32_e32 v128, v128
	v_exp_f32_e32 v129, v129
	s_nop 0
	v_pk_add_f32 v[128:129], v[128:129], 1.0 op_sel_hi:[1,0]
	s_nop 0
	s_nop 0
	v_rcp_f32_e32 v130, v129
	s_nop 0
	v_rcp_f32_e32 v131, v128
	v_mul_f32_e32 v128, 0xbfb8aa3b, v102
	v_mul_f32_e32 v129, 0xbfb8aa3b, v103
	v_exp_f32_e32 v128, v128
	v_exp_f32_e32 v129, v129
	s_nop 0
	v_pk_add_f32 v[128:129], v[128:129], 1.0 op_sel_hi:[1,0]
	s_nop 0
	s_nop 0
	v_rcp_f32_e32 v129, v129
	s_nop 0
	v_rcp_f32_e32 v160, v128
	v_cvt_pk_bf16_f32 v128, v131, v130
	v_xor_b32_e32 v130, v157, v150
	v_lshlrev_b32_e32 v130, 4, v130
	v_cvt_pk_bf16_f32 v129, v160, v129
	v_add3_u32 v130, v159, v130, v133
	ds_write_b64 v130, v[128:129]

; DEV u32x2 pk4(f32x4 v) { u32x2 r = {pk_bf16(v[0], v[1]), pk_bf16(v[2], v[3])}; return r; }
; DEV float fsigmoid(float x) { return 1.f / (1.f + __expf(-x)); }
;   DEV void operator()(f32x4 (&acc)[2][2][4][2], int brow, int bcol, int wr, int wc, int fr, int fq) const {
;     ...
;             } else if (mode == 1) {
;               for (int j = 0; j < 4; ++j) v[j] = v[j] * fsigmoid(v[j]);
;               tile_put4(rl, cl, pk4(v));
.LBB0_723:
	s_andn2_b64 vcc, exec, s[0:1]
	s_cbranch_vccnz .LBB0_725
	s_waitcnt vmcnt(0)
	v_mul_f32_e32 v128, 0xbfb8aa3b, v100
	v_mul_f32_e32 v129, 0xbfb8aa3b, v101
	v_exp_f32_e32 v128, v128
	v_exp_f32_e32 v129, v129
	s_nop 0
	v_pk_add_f32 v[128:129], v[128:129], 1.0 op_sel_hi:[1,0]
	s_nop 0
	s_nop 0
	v_rcp_f32_e32 v129, v129
	s_nop 0
	v_rcp_f32_e32 v128, v128
	v_mul_f32_e32 v130, 0xbfb8aa3b, v102
	v_mul_f32_e32 v131, 0xbfb8aa3b, v103
	v_exp_f32_e32 v130, v130
	v_exp_f32_e32 v131, v131
	v_pk_mul_f32 v[128:129], v[100:101], v[128:129]
	v_pk_add_f32 v[130:131], v[130:131], 1.0 op_sel_hi:[1,0]
	s_nop 0
	v_cvt_pk_bf16_f32 v128, v128, v129
	v_rcp_f32_e32 v131, v131
	s_nop 0
	v_rcp_f32_e32 v130, v130
	s_nop 0
	v_pk_mul_f32 v[130:131], v[102:103], v[130:131]
	s_nop 0
	v_cvt_pk_bf16_f32 v129, v130, v131
	v_xor_b32_e32 v130, v157, v150
	v_lshlrev_b32_e32 v130, 4, v130
	v_add3_u32 v130, v159, v130, v133
	ds_write_b64 v130, v[128:129]

; DEV u32x2 pk4(f32x4 v) { u32x2 r = {pk_bf16(v[0], v[1]), pk_bf16(v[2], v[3])}; return r; }
; DEV float fsigmoid(float x) { return 1.f / (1.f + __expf(-x)); }
;   DEV void operator()(f32x4 (&acc)[2][2][4][2], int brow, int bcol, int wr, int wc, int fr, int fq) const {
;     ...
;             } else if (mode == 2) {
;               for (int j = 0; j < 4; ++j) v[j] = fsigmoid(v[j]);
;               tile_put4(rl, cl, pk4(v));
.LBB0_734:
	s_andn2_b64 vcc, exec, s[0:1]
	s_cbranch_vccnz .LBB0_736
	s_waitcnt vmcnt(0)
	v_mul_f32_e32 v128, 0xbfb8aa3b, v96
	v_mul_f32_e32 v129, 0xbfb8aa3b, v97
	v_exp_f32_e32 v128, v128
	v_exp_f32_e32 v129, v129
	s_nop 0
	v_pk_add_f32 v[128:129], v[128:129], 1.0 op_sel_hi:[1,0]
	s_nop 0
	s_nop 0
	v_rcp_f32_e32 v130, v129
	s_nop 0
	v_rcp_f32_e32 v131, v128
	v_mul_f32_e32 v128, 0xbfb8aa3b, v98
	v_mul_f32_e32 v129, 0xbfb8aa3b, v99
	v_exp_f32_e32 v128, v128
	v_exp_f32_e32 v129, v129
	s_nop 0
	v_pk_add_f32 v[128:129], v[128:129], 1.0 op_sel_hi:[1,0]
	s_nop 0
	s_nop 0
	v_rcp_f32_e32 v129, v129
	s_nop 0
	v_rcp_f32_e32 v136, v128
	v_cvt_pk_bf16_f32 v128, v131, v130
	v_xor_b32_e32 v130, v158, v150
	v_lshlrev_b32_e32 v130, 4, v130
	v_cvt_pk_bf16_f32 v129, v136, v129
	v_add3_u32 v130, v159, v130, v133
	ds_write_b64 v130, v[128:129]

; DEV u32x2 pk4(f32x4 v) { u32x2 r = {pk_bf16(v[0], v[1]), pk_bf16(v[2], v[3])}; return r; }
; DEV float fsigmoid(float x) { return 1.f / (1.f + __expf(-x)); }
;   DEV void operator()(f32x4 (&acc)[2][2][4][2], int brow, int bcol, int wr, int wc, int fr, int fq) const {
;     ...
;             } else if (mode == 1) {
;               for (int j = 0; j < 4; ++j) v[j] = v[j] * fsigmoid(v[j]);
;               tile_put4(rl, cl, pk4(v));
.LBB0_737:
	s_andn2_b64 vcc, exec, s[0:1]
	s_cbranch_vccnz .LBB0_739
	s_waitcnt vmcnt(0)
	v_mul_f32_e32 v128, 0xbfb8aa3b, v96
	v_mul_f32_e32 v129, 0xbfb8aa3b, v97
	v_exp_f32_e32 v128, v128
	v_exp_f32_e32 v129, v129
	s_nop 0
	v_pk_add_f32 v[128:129], v[128:129], 1.0 op_sel_hi:[1,0]
	s_nop 0
	s_nop 0
	v_rcp_f32_e32 v129, v129
	s_nop 0
	v_rcp_f32_e32 v128, v128
	v_mul_f32_e32 v130, 0xbfb8aa3b, v98
	v_mul_f32_e32 v131, 0xbfb8aa3b, v99
	v_exp_f32_e32 v130, v130
	v_exp_f32_e32 v131, v131
	v_pk_mul_f32 v[128:129], v[96:97], v[128:129]
	v_pk_add_f32 v[130:131], v[130:131], 1.0 op_sel_hi:[1,0]
	s_nop 0
	v_cvt_pk_bf16_f32 v128, v128, v129
	v_rcp_f32_e32 v131, v131
	s_nop 0
	v_rcp_f32_e32 v130, v130
	s_nop 0
	v_pk_mul_f32 v[130:131], v[98:99], v[130:131]
	s_nop 0
	v_cvt_pk_bf16_f32 v129, v130, v131
	v_xor_b32_e32 v130, v158, v150
	v_lshlrev_b32_e32 v130, 4, v130
	v_add3_u32 v130, v159, v130, v133
	ds_write_b64 v130, v[128:129]

; DEV u32x2 pk4(f32x4 v) { u32x2 r = {pk_bf16(v[0], v[1]), pk_bf16(v[2], v[3])}; return r; }
; DEV float fsigmoid(float x) { return 1.f / (1.f + __expf(-x)); }
;   DEV void operator()(f32x4 (&acc)[2][2][4][2], int brow, int bcol, int wr, int wc, int fr, int fq) const {
;     ...
;             } else if (mode == 2) {
;               for (int j = 0; j < 4; ++j) v[j] = fsigmoid(v[j]);
;               tile_put4(rl, cl, pk4(v));
.LBB0_756:
	s_andn2_b64 vcc, exec, s[0:1]
	s_cbranch_vccnz .LBB0_758
	s_waitcnt vmcnt(0)
	v_mul_f32_e32 v128, 0xbfb8aa3b, v92
	v_mul_f32_e32 v129, 0xbfb8aa3b, v93
	v_exp_f32_e32 v128, v128
	v_exp_f32_e32 v129, v129
	s_nop 0
	v_pk_add_f32 v[128:129], v[128:129], 1.0 op_sel_hi:[1,0]
	s_nop 0
	s_nop 0
	v_rcp_f32_e32 v130, v129
	s_nop 0
	v_rcp_f32_e32 v131, v128
	v_mul_f32_e32 v128, 0xbfb8aa3b, v94
	v_mul_f32_e32 v129, 0xbfb8aa3b, v95
	v_exp_f32_e32 v128, v128
	v_exp_f32_e32 v129, v129
	s_nop 0
	v_pk_add_f32 v[128:129], v[128:129], 1.0 op_sel_hi:[1,0]
	s_nop 0
	s_nop 0
	v_rcp_f32_e32 v129, v129
	s_nop 0
	v_rcp_f32_e32 v160, v128
	v_cvt_pk_bf16_f32 v128, v131, v130
	v_lshlrev_b32_e32 v130, 4, v151
	v_cvt_pk_bf16_f32 v129, v160, v129
	v_add3_u32 v130, v159, v130, v133
	ds_write_b64 v130, v[128:129]

; DEV u32x2 pk4(f32x4 v) { u32x2 r = {pk_bf16(v[0], v[1]), pk_bf16(v[2], v[3])}; return r; }
; DEV float fsigmoid(float x) { return 1.f / (1.f + __expf(-x)); }
;   DEV void operator()(f32x4 (&acc)[2][2][4][2], int brow, int bcol, int wr, int wc, int fr, int fq) const {
;     ...
;             } else if (mode == 1) {
;               for (int j = 0; j < 4; ++j) v[j] = v[j] * fsigmoid(v[j]);
;               tile_put4(rl, cl, pk4(v));
.LBB0_759:
	s_andn2_b64 vcc, exec, s[0:1]
	s_cbranch_vccnz .LBB0_761
	s_waitcnt vmcnt(0)
	v_mul_f32_e32 v128, 0xbfb8aa3b, v92
	v_mul_f32_e32 v129, 0xbfb8aa3b, v93
	v_exp_f32_e32 v128, v128
	v_exp_f32_e32 v129, v129
	s_nop 0
	v_pk_add_f32 v[128:129], v[128:129], 1.0 op_sel_hi:[1,0]
	s_nop 0
	s_nop 0
	v_rcp_f32_e32 v129, v129
	s_nop 0
	v_rcp_f32_e32 v128, v128
	v_mul_f32_e32 v130, 0xbfb8aa3b, v94
	v_mul_f32_e32 v131, 0xbfb8aa3b, v95
	v_exp_f32_e32 v130, v130
	v_exp_f32_e32 v131, v131
	v_pk_mul_f32 v[128:129], v[92:93], v[128:129]
	v_pk_add_f32 v[130:131], v[130:131], 1.0 op_sel_hi:[1,0]
	s_nop 0
	v_cvt_pk_bf16_f32 v128, v128, v129
	v_rcp_f32_e32 v131, v131
	s_nop 0
	v_rcp_f32_e32 v130, v130
	s_nop 0
	v_pk_mul_f32 v[130:131], v[94:95], v[130:131]
	s_nop 0
	v_cvt_pk_bf16_f32 v129, v130, v131
	v_lshlrev_b32_e32 v130, 4, v151
	v_add3_u32 v130, v159, v130, v133
	ds_write_b64 v130, v[128:129]

; DEV u32x2 pk4(f32x4 v) { u32x2 r = {pk_bf16(v[0], v[1]), pk_bf16(v[2], v[3])}; return r; }
; DEV float fsigmoid(float x) { return 1.f / (1.f + __expf(-x)); }
;   DEV void operator()(f32x4 (&acc)[2][2][4][2], int brow, int bcol, int wr, int wc, int fr, int fq) const {
;     ...
;             } else if (mode == 2) {
;               for (int j = 0; j < 4; ++j) v[j] = fsigmoid(v[j]);
;               tile_put4(rl, cl, pk4(v));
.LBB0_770:
	s_andn2_b64 vcc, exec, s[0:1]
	s_cbranch_vccnz .LBB0_772
	s_waitcnt vmcnt(0)
	v_mul_f32_e32 v128, 0xbfb8aa3b, v88
	v_mul_f32_e32 v129, 0xbfb8aa3b, v89
	v_exp_f32_e32 v128, v128
	v_exp_f32_e32 v129, v129
	s_nop 0
	v_pk_add_f32 v[128:129], v[128:129], 1.0 op_sel_hi:[1,0]
	s_nop 0
	s_nop 0
	v_rcp_f32_e32 v130, v129
	s_nop 0
	v_rcp_f32_e32 v131, v128
	v_mul_f32_e32 v128, 0xbfb8aa3b, v90
	v_mul_f32_e32 v129, 0xbfb8aa3b, v91
	v_exp_f32_e32 v128, v128
	v_exp_f32_e32 v129, v129
	s_nop 0
	v_pk_add_f32 v[128:129], v[128:129], 1.0 op_sel_hi:[1,0]
	s_nop 0
	s_nop 0
	v_rcp_f32_e32 v129, v129
	s_nop 0
	v_rcp_f32_e32 v160, v128
	v_cvt_pk_bf16_f32 v128, v131, v130
	v_lshlrev_b32_e32 v130, 4, v152
	v_cvt_pk_bf16_f32 v129, v160, v129
	v_add3_u32 v130, v159, v130, v133
	ds_write_b64 v130, v[128:129]

; DEV u32x2 pk4(f32x4 v) { u32x2 r = {pk_bf16(v[0], v[1]), pk_bf16(v[2], v[3])}; return r; }
; DEV float fsigmoid(float x) { return 1.f / (1.f + __expf(-x)); }
;   DEV void operator()(f32x4 (&acc)[2][2][4][2], int brow, int bcol, int wr, int wc, int fr, int fq) const {
;     ...
;             } else if (mode == 1) {
;               for (int j = 0; j < 4; ++j) v[j] = v[j] * fsigmoid(v[j]);
;               tile_put4(rl, cl, pk4(v));
.LBB0_773:
	s_andn2_b64 vcc, exec, s[0:1]
	s_cbranch_vccnz .LBB0_775
	s_waitcnt vmcnt(0)
	v_mul_f32_e32 v128, 0xbfb8aa3b, v88
	v_mul_f32_e32 v129, 0xbfb8aa3b, v89
	v_exp_f32_e32 v128, v128
	v_exp_f32_e32 v129, v129
	s_nop 0
	v_pk_add_f32 v[128:129], v[128:129], 1.0 op_sel_hi:[1,0]
	s_nop 0
	s_nop 0
	v_rcp_f32_e32 v129, v129
	s_nop 0
	v_rcp_f32_e32 v128, v128
	v_mul_f32_e32 v130, 0xbfb8aa3b, v90
	v_mul_f32_e32 v131, 0xbfb8aa3b, v91
	v_exp_f32_e32 v130, v130
	v_exp_f32_e32 v131, v131
	v_pk_mul_f32 v[128:129], v[88:89], v[128:129]
	v_pk_add_f32 v[130:131], v[130:131], 1.0 op_sel_hi:[1,0]
	s_nop 0
	v_cvt_pk_bf16_f32 v128, v128, v129
	v_rcp_f32_e32 v131, v131
	s_nop 0
	v_rcp_f32_e32 v130, v130
	s_nop 0
	v_pk_mul_f32 v[130:131], v[90:91], v[130:131]
	s_nop 0
	v_cvt_pk_bf16_f32 v129, v130, v131
	v_lshlrev_b32_e32 v130, 4, v152
	v_add3_u32 v130, v159, v130, v133
	ds_write_b64 v130, v[128:129]

; DEV u32x2 pk4(f32x4 v) { u32x2 r = {pk_bf16(v[0], v[1]), pk_bf16(v[2], v[3])}; return r; }
; DEV float fsigmoid(float x) { return 1.f / (1.f + __expf(-x)); }
;   DEV void operator()(f32x4 (&acc)[2][2][4][2], int brow, int bcol, int wr, int wc, int fr, int fq) const {
;     ...
;             } else if (mode == 2) {
;               for (int j = 0; j < 4; ++j) v[j] = fsigmoid(v[j]);
;               tile_put4(rl, cl, pk4(v));
.LBB0_784:
	s_andn2_b64 vcc, exec, s[0:1]
	s_cbranch_vccnz .LBB0_786
	s_waitcnt vmcnt(0)
	v_mul_f32_e32 v128, 0xbfb8aa3b, v84
	v_mul_f32_e32 v129, 0xbfb8aa3b, v85
	v_exp_f32_e32 v128, v128
	v_exp_f32_e32 v129, v129
	s_nop 0
	v_pk_add_f32 v[128:129], v[128:129], 1.0 op_sel_hi:[1,0]
	s_nop 0
	s_nop 0
	v_rcp_f32_e32 v130, v129
	s_nop 0
	v_rcp_f32_e32 v131, v128
	v_mul_f32_e32 v128, 0xbfb8aa3b, v86
	v_mul_f32_e32 v129, 0xbfb8aa3b, v87
	v_exp_f32_e32 v128, v128
	v_exp_f32_e32 v129, v129
	s_nop 0
	v_pk_add_f32 v[128:129], v[128:129], 1.0 op_sel_hi:[1,0]
	s_nop 0
	s_nop 0
	v_rcp_f32_e32 v129, v129
	s_nop 0
	v_rcp_f32_e32 v160, v128
	v_cvt_pk_bf16_f32 v128, v131, v130
	v_lshlrev_b32_e32 v130, 4, v153
	v_cvt_pk_bf16_f32 v129, v160, v129
	v_add3_u32 v130, v159, v130, v133
	ds_write_b64 v130, v[128:129]

; DEV u32x2 pk4(f32x4 v) { u32x2 r = {pk_bf16(v[0], v[1]), pk_bf16(v[2], v[3])}; return r; }
; DEV float fsigmoid(float x) { return 1.f / (1.f + __expf(-x)); }
;   DEV void operator()(f32x4 (&acc)[2][2][4][2], int brow, int bcol, int wr, int wc, int fr, int fq) const {
;     ...
;             } else if (mode == 1) {
;               for (int j = 0; j < 4; ++j) v[j] = v[j] * fsigmoid(v[j]);
;               tile_put4(rl, cl, pk4(v));
.LBB0_787:
	s_andn2_b64 vcc, exec, s[0:1]
	s_cbranch_vccnz .LBB0_789
	s_waitcnt vmcnt(0)
	v_mul_f32_e32 v128, 0xbfb8aa3b, v84
	v_mul_f32_e32 v129, 0xbfb8aa3b, v85
	v_exp_f32_e32 v128, v128
	v_exp_f32_e32 v129, v129
	s_nop 0
	v_pk_add_f32 v[128:129], v[128:129], 1.0 op_sel_hi:[1,0]
	s_nop 0
	s_nop 0
	v_rcp_f32_e32 v129, v129
	s_nop 0
	v_rcp_f32_e32 v128, v128
	v_mul_f32_e32 v130, 0xbfb8aa3b, v86
	v_mul_f32_e32 v131, 0xbfb8aa3b, v87
	v_exp_f32_e32 v130, v130
	v_exp_f32_e32 v131, v131
	v_pk_mul_f32 v[128:129], v[84:85], v[128:129]
	v_pk_add_f32 v[130:131], v[130:131], 1.0 op_sel_hi:[1,0]
	s_nop 0
	v_cvt_pk_bf16_f32 v128, v128, v129
	v_rcp_f32_e32 v131, v131
	s_nop 0
	v_rcp_f32_e32 v130, v130
	s_nop 0
	v_pk_mul_f32 v[130:131], v[86:87], v[130:131]
	s_nop 0
	v_cvt_pk_bf16_f32 v129, v130, v131
	v_lshlrev_b32_e32 v130, 4, v153
	v_add3_u32 v130, v159, v130, v133
	ds_write_b64 v130, v[128:129]

; DEV u32x2 pk4(f32x4 v) { u32x2 r = {pk_bf16(v[0], v[1]), pk_bf16(v[2], v[3])}; return r; }
; DEV float fsigmoid(float x) { return 1.f / (1.f + __expf(-x)); }
;   DEV void operator()(f32x4 (&acc)[2][2][4][2], int brow, int bcol, int wr, int wc, int fr, int fq) const {
;     ...
;             } else if (mode == 2) {
;               for (int j = 0; j < 4; ++j) v[j] = fsigmoid(v[j]);
;               tile_put4(rl, cl, pk4(v));
.LBB0_798:
	s_andn2_b64 vcc, exec, s[0:1]
	s_cbranch_vccnz .LBB0_800
	s_waitcnt vmcnt(0)
	v_mul_f32_e32 v128, 0xbfb8aa3b, v80
	v_mul_f32_e32 v129, 0xbfb8aa3b, v81
	v_exp_f32_e32 v128, v128
	v_exp_f32_e32 v129, v129
	s_nop 0
	v_pk_add_f32 v[128:129], v[128:129], 1.0 op_sel_hi:[1,0]
	s_nop 0
	s_nop 0
	v_rcp_f32_e32 v130, v129
	s_nop 0
	v_rcp_f32_e32 v131, v128
	v_mul_f32_e32 v128, 0xbfb8aa3b, v82
	v_mul_f32_e32 v129, 0xbfb8aa3b, v83
	v_exp_f32_e32 v128, v128
	v_exp_f32_e32 v129, v129
	s_nop 0
	v_pk_add_f32 v[128:129], v[128:129], 1.0 op_sel_hi:[1,0]
	s_nop 0
	s_nop 0
	v_rcp_f32_e32 v129, v129
	s_nop 0
	v_rcp_f32_e32 v136, v128
	v_cvt_pk_bf16_f32 v128, v131, v130
	v_lshlrev_b32_e32 v130, 4, v154
	v_cvt_pk_bf16_f32 v129, v136, v129
	v_add3_u32 v130, v159, v130, v133
	ds_write_b64 v130, v[128:129]

; DEV u32x2 pk4(f32x4 v) { u32x2 r = {pk_bf16(v[0], v[1]), pk_bf16(v[2], v[3])}; return r; }
; DEV float fsigmoid(float x) { return 1.f / (1.f + __expf(-x)); }
;   DEV void operator()(f32x4 (&acc)[2][2][4][2], int brow, int bcol, int wr, int wc, int fr, int fq) const {
;     ...
;             } else if (mode == 1) {
;               for (int j = 0; j < 4; ++j) v[j] = v[j] * fsigmoid(v[j]);
;               tile_put4(rl, cl, pk4(v));
.LBB0_801:
	s_andn2_b64 vcc, exec, s[0:1]
	s_cbranch_vccnz .LBB0_803
	s_waitcnt vmcnt(0)
	v_mul_f32_e32 v128, 0xbfb8aa3b, v80
	v_mul_f32_e32 v129, 0xbfb8aa3b, v81
	v_exp_f32_e32 v128, v128
	v_exp_f32_e32 v129, v129
	s_nop 0
	v_pk_add_f32 v[128:129], v[128:129], 1.0 op_sel_hi:[1,0]
	s_nop 0
	s_nop 0
	v_rcp_f32_e32 v129, v129
	s_nop 0
	v_rcp_f32_e32 v128, v128
	v_mul_f32_e32 v130, 0xbfb8aa3b, v82
	v_mul_f32_e32 v131, 0xbfb8aa3b, v83
	v_exp_f32_e32 v130, v130
	v_exp_f32_e32 v131, v131
	v_pk_mul_f32 v[128:129], v[80:81], v[128:129]
	v_pk_add_f32 v[130:131], v[130:131], 1.0 op_sel_hi:[1,0]
	s_nop 0
	v_cvt_pk_bf16_f32 v128, v128, v129
	v_rcp_f32_e32 v131, v131
	s_nop 0
	v_rcp_f32_e32 v130, v130
	s_nop 0
	v_pk_mul_f32 v[130:131], v[82:83], v[130:131]
	s_nop 0
	v_cvt_pk_bf16_f32 v129, v130, v131
	v_lshlrev_b32_e32 v130, 4, v154
	v_add3_u32 v130, v159, v130, v133
	ds_write_b64 v130, v[128:129]

; DEV u32x2 pk4(f32x4 v) { u32x2 r = {pk_bf16(v[0], v[1]), pk_bf16(v[2], v[3])}; return r; }
; DEV float fsigmoid(float x) { return 1.f / (1.f + __expf(-x)); }
;   DEV void operator()(f32x4 (&acc)[2][2][4][2], int brow, int bcol, int wr, int wc, int fr, int fq) const {
;     ...
;             } else if (mode == 2) {
;               for (int j = 0; j < 4; ++j) v[j] = fsigmoid(v[j]);
;               tile_put4(rl, cl, pk4(v));
.LBB0_820:
	s_andn2_b64 vcc, exec, s[0:1]
	s_cbranch_vccnz .LBB0_822
	s_waitcnt vmcnt(0)
	v_mul_f32_e32 v128, 0xbfb8aa3b, v76
	v_mul_f32_e32 v129, 0xbfb8aa3b, v77
	v_exp_f32_e32 v128, v128
	v_exp_f32_e32 v129, v129
	s_nop 0
	v_pk_add_f32 v[128:129], v[128:129], 1.0 op_sel_hi:[1,0]
	s_nop 0
	s_nop 0
	v_rcp_f32_e32 v130, v129
	s_nop 0
	v_rcp_f32_e32 v131, v128
	v_mul_f32_e32 v128, 0xbfb8aa3b, v78
	v_mul_f32_e32 v129, 0xbfb8aa3b, v79
	v_exp_f32_e32 v128, v128
	v_exp_f32_e32 v129, v129
	s_nop 0
	v_pk_add_f32 v[128:129], v[128:129], 1.0 op_sel_hi:[1,0]
	s_nop 0
	s_nop 0
	v_rcp_f32_e32 v129, v129
	s_nop 0
	v_rcp_f32_e32 v160, v128
	v_cvt_pk_bf16_f32 v128, v131, v130
	v_lshlrev_b32_e32 v130, 4, v155
	v_cvt_pk_bf16_f32 v129, v160, v129
	v_add3_u32 v130, v159, v130, v133
	ds_write_b64 v130, v[128:129]

; DEV u32x2 pk4(f32x4 v) { u32x2 r = {pk_bf16(v[0], v[1]), pk_bf16(v[2], v[3])}; return r; }
; DEV float fsigmoid(float x) { return 1.f / (1.f + __expf(-x)); }
;   DEV void operator()(f32x4 (&acc)[2][2][4][2], int brow, int bcol, int wr, int wc, int fr, int fq) const {
;     ...
;             } else if (mode == 1) {
;               for (int j = 0; j < 4; ++j) v[j] = v[j] * fsigmoid(v[j]);
;               tile_put4(rl, cl, pk4(v));
.LBB0_823:
	s_andn2_b64 vcc, exec, s[0:1]
	s_cbranch_vccnz .LBB0_825
	s_waitcnt vmcnt(0)
	v_mul_f32_e32 v128, 0xbfb8aa3b, v76
	v_mul_f32_e32 v129, 0xbfb8aa3b, v77
	v_exp_f32_e32 v128, v128
	v_exp_f32_e32 v129, v129
	s_nop 0
	v_pk_add_f32 v[128:129], v[128:129], 1.0 op_sel_hi:[1,0]
	s_nop 0
	s_nop 0
	v_rcp_f32_e32 v129, v129
	s_nop 0
	v_rcp_f32_e32 v128, v128
	v_mul_f32_e32 v130, 0xbfb8aa3b, v78
	v_mul_f32_e32 v131, 0xbfb8aa3b, v79
	v_exp_f32_e32 v130, v130
	v_exp_f32_e32 v131, v131
	v_pk_mul_f32 v[128:129], v[76:77], v[128:129]
	v_pk_add_f32 v[130:131], v[130:131], 1.0 op_sel_hi:[1,0]
	s_nop 0
	v_cvt_pk_bf16_f32 v128, v128, v129
	v_rcp_f32_e32 v131, v131
	s_nop 0
	v_rcp_f32_e32 v130, v130
	s_nop 0
	v_pk_mul_f32 v[130:131], v[78:79], v[130:131]
	s_nop 0
	v_cvt_pk_bf16_f32 v129, v130, v131
	v_lshlrev_b32_e32 v130, 4, v155
	v_add3_u32 v130, v159, v130, v133
	ds_write_b64 v130, v[128:129]

; DEV u32x2 pk4(f32x4 v) { u32x2 r = {pk_bf16(v[0], v[1]), pk_bf16(v[2], v[3])}; return r; }
; DEV float fsigmoid(float x) { return 1.f / (1.f + __expf(-x)); }
;   DEV void operator()(f32x4 (&acc)[2][2][4][2], int brow, int bcol, int wr, int wc, int fr, int fq) const {
;     ...
;             } else if (mode == 2) {
;               for (int j = 0; j < 4; ++j) v[j] = fsigmoid(v[j]);
;               tile_put4(rl, cl, pk4(v));
.LBB0_834:
	s_andn2_b64 vcc, exec, s[0:1]
	s_cbranch_vccnz .LBB0_836
	s_waitcnt vmcnt(0)
	v_mul_f32_e32 v128, 0xbfb8aa3b, v72
	v_mul_f32_e32 v129, 0xbfb8aa3b, v73
	v_exp_f32_e32 v128, v128
	v_exp_f32_e32 v129, v129
	s_nop 0
	v_pk_add_f32 v[128:129], v[128:129], 1.0 op_sel_hi:[1,0]
	s_nop 0
	s_nop 0
	v_rcp_f32_e32 v130, v129
	s_nop 0
	v_rcp_f32_e32 v131, v128
	v_mul_f32_e32 v128, 0xbfb8aa3b, v74
	v_mul_f32_e32 v129, 0xbfb8aa3b, v75
	v_exp_f32_e32 v128, v128
	v_exp_f32_e32 v129, v129
	s_nop 0
	v_pk_add_f32 v[128:129], v[128:129], 1.0 op_sel_hi:[1,0]
	s_nop 0
	s_nop 0
	v_rcp_f32_e32 v129, v129
	s_nop 0
	v_rcp_f32_e32 v160, v128
	v_cvt_pk_bf16_f32 v128, v131, v130
	v_lshlrev_b32_e32 v130, 4, v156
	v_cvt_pk_bf16_f32 v129, v160, v129
	v_add3_u32 v130, v159, v130, v133
	ds_write_b64 v130, v[128:129]

; DEV u32x2 pk4(f32x4 v) { u32x2 r = {pk_bf16(v[0], v[1]), pk_bf16(v[2], v[3])}; return r; }
; DEV float fsigmoid(float x) { return 1.f / (1.f + __expf(-x)); }
;   DEV void operator()(f32x4 (&acc)[2][2][4][2], int brow, int bcol, int wr, int wc, int fr, int fq) const {
;     ...
;             } else if (mode == 1) {
;               for (int j = 0; j < 4; ++j) v[j] = v[j] * fsigmoid(v[j]);
;               tile_put4(rl, cl, pk4(v));
.LBB0_837:
	s_andn2_b64 vcc, exec, s[0:1]
	s_cbranch_vccnz .LBB0_839
	s_waitcnt vmcnt(0)
	v_mul_f32_e32 v128, 0xbfb8aa3b, v72
	v_mul_f32_e32 v129, 0xbfb8aa3b, v73
	v_exp_f32_e32 v128, v128
	v_exp_f32_e32 v129, v129
	s_nop 0
	v_pk_add_f32 v[128:129], v[128:129], 1.0 op_sel_hi:[1,0]
	s_nop 0
	s_nop 0
	v_rcp_f32_e32 v129, v129
	s_nop 0
	v_rcp_f32_e32 v128, v128
	v_mul_f32_e32 v130, 0xbfb8aa3b, v74
	v_mul_f32_e32 v131, 0xbfb8aa3b, v75
	v_exp_f32_e32 v130, v130
	v_exp_f32_e32 v131, v131
	v_pk_mul_f32 v[128:129], v[72:73], v[128:129]
	v_pk_add_f32 v[130:131], v[130:131], 1.0 op_sel_hi:[1,0]
	s_nop 0
	v_cvt_pk_bf16_f32 v128, v128, v129
	v_rcp_f32_e32 v131, v131
	s_nop 0
	v_rcp_f32_e32 v130, v130
	s_nop 0
	v_pk_mul_f32 v[130:131], v[74:75], v[130:131]
	s_nop 0
	v_cvt_pk_bf16_f32 v129, v130, v131
	v_lshlrev_b32_e32 v130, 4, v156
	v_add3_u32 v130, v159, v130, v133
	ds_write_b64 v130, v[128:129]

; DEV u32x2 pk4(f32x4 v) { u32x2 r = {pk_bf16(v[0], v[1]), pk_bf16(v[2], v[3])}; return r; }
; DEV float fsigmoid(float x) { return 1.f / (1.f + __expf(-x)); }
;   DEV void operator()(f32x4 (&acc)[2][2][4][2], int brow, int bcol, int wr, int wc, int fr, int fq) const {
;     ...
;             } else if (mode == 2) {
;               for (int j = 0; j < 4; ++j) v[j] = fsigmoid(v[j]);
;               tile_put4(rl, cl, pk4(v));
.LBB0_848:
	s_andn2_b64 vcc, exec, s[0:1]
	s_cbranch_vccnz .LBB0_850
	s_waitcnt vmcnt(0)
	v_mul_f32_e32 v128, 0xbfb8aa3b, v68
	v_mul_f32_e32 v129, 0xbfb8aa3b, v69
	v_exp_f32_e32 v128, v128
	v_exp_f32_e32 v129, v129
	s_nop 0
	v_pk_add_f32 v[128:129], v[128:129], 1.0 op_sel_hi:[1,0]
	s_nop 0
	s_nop 0
	v_rcp_f32_e32 v130, v129
	s_nop 0
	v_rcp_f32_e32 v131, v128
	v_mul_f32_e32 v128, 0xbfb8aa3b, v70
	v_mul_f32_e32 v129, 0xbfb8aa3b, v71
	v_exp_f32_e32 v128, v128
	v_exp_f32_e32 v129, v129
	s_nop 0
	v_pk_add_f32 v[128:129], v[128:129], 1.0 op_sel_hi:[1,0]
	s_nop 0
	s_nop 0
	v_rcp_f32_e32 v129, v129
	s_nop 0
	v_rcp_f32_e32 v160, v128
	v_cvt_pk_bf16_f32 v128, v131, v130
	v_lshlrev_b32_e32 v130, 4, v157
	v_cvt_pk_bf16_f32 v129, v160, v129
	v_add3_u32 v130, v159, v130, v133
	ds_write_b64 v130, v[128:129]

; DEV u32x2 pk4(f32x4 v) { u32x2 r = {pk_bf16(v[0], v[1]), pk_bf16(v[2], v[3])}; return r; }
; DEV float fsigmoid(float x) { return 1.f / (1.f + __expf(-x)); }
;   DEV void operator()(f32x4 (&acc)[2][2][4][2], int brow, int bcol, int wr, int wc, int fr, int fq) const {
;     ...
;             } else if (mode == 1) {
;               for (int j = 0; j < 4; ++j) v[j] = v[j] * fsigmoid(v[j]);
;               tile_put4(rl, cl, pk4(v));
.LBB0_851:
	s_andn2_b64 vcc, exec, s[0:1]
	s_cbranch_vccnz .LBB0_853
	s_waitcnt vmcnt(0)
	v_mul_f32_e32 v128, 0xbfb8aa3b, v68
	v_mul_f32_e32 v129, 0xbfb8aa3b, v69
	v_exp_f32_e32 v128, v128
	v_exp_f32_e32 v129, v129
	s_nop 0
	v_pk_add_f32 v[128:129], v[128:129], 1.0 op_sel_hi:[1,0]
	s_nop 0
	s_nop 0
	v_rcp_f32_e32 v129, v129
	s_nop 0
	v_rcp_f32_e32 v128, v128
	v_mul_f32_e32 v130, 0xbfb8aa3b, v70
	v_mul_f32_e32 v131, 0xbfb8aa3b, v71
	v_exp_f32_e32 v130, v130
	v_exp_f32_e32 v131, v131
	v_pk_mul_f32 v[128:129], v[68:69], v[128:129]
	v_pk_add_f32 v[130:131], v[130:131], 1.0 op_sel_hi:[1,0]
	s_nop 0
	v_cvt_pk_bf16_f32 v128, v128, v129
	v_rcp_f32_e32 v131, v131
	s_nop 0
	v_rcp_f32_e32 v130, v130
	s_nop 0
	v_pk_mul_f32 v[130:131], v[70:71], v[130:131]
	s_nop 0
	v_cvt_pk_bf16_f32 v129, v130, v131
	v_lshlrev_b32_e32 v130, 4, v157
	v_add3_u32 v130, v159, v130, v133
	ds_write_b64 v130, v[128:129]

; DEV u32x2 pk4(f32x4 v) { u32x2 r = {pk_bf16(v[0], v[1]), pk_bf16(v[2], v[3])}; return r; }
; DEV float fsigmoid(float x) { return 1.f / (1.f + __expf(-x)); }
;   DEV void operator()(f32x4 (&acc)[2][2][4][2], int brow, int bcol, int wr, int wc, int fr, int fq) const {
;     ...
;             } else if (mode == 2) {
;               for (int j = 0; j < 4; ++j) v[j] = fsigmoid(v[j]);
;               tile_put4(rl, cl, pk4(v));
.LBB0_862:
	s_andn2_b64 vcc, exec, s[0:1]
	s_cbranch_vccnz .LBB0_864
	s_waitcnt vmcnt(0)
	v_mul_f32_e32 v128, 0xbfb8aa3b, v64
	v_mul_f32_e32 v129, 0xbfb8aa3b, v65
	v_exp_f32_e32 v128, v128
	v_exp_f32_e32 v129, v129
	s_nop 0
	v_pk_add_f32 v[128:129], v[128:129], 1.0 op_sel_hi:[1,0]
	s_nop 0
	s_nop 0
	v_rcp_f32_e32 v130, v129
	s_nop 0
	v_rcp_f32_e32 v131, v128
	v_mul_f32_e32 v128, 0xbfb8aa3b, v66
	v_mul_f32_e32 v129, 0xbfb8aa3b, v67
	v_exp_f32_e32 v128, v128
	v_exp_f32_e32 v129, v129
	s_nop 0
	v_pk_add_f32 v[128:129], v[128:129], 1.0 op_sel_hi:[1,0]
	s_nop 0
	s_nop 0
	v_rcp_f32_e32 v129, v129
	s_nop 0
	v_rcp_f32_e32 v136, v128
	v_cvt_pk_bf16_f32 v128, v131, v130
	v_lshlrev_b32_e32 v130, 4, v158
	v_cvt_pk_bf16_f32 v129, v136, v129
	v_add3_u32 v130, v159, v130, v133
	ds_write_b64 v130, v[128:129]

; DEV u32x2 pk4(f32x4 v) { u32x2 r = {pk_bf16(v[0], v[1]), pk_bf16(v[2], v[3])}; return r; }
; DEV float fsigmoid(float x) { return 1.f / (1.f + __expf(-x)); }
;   DEV void operator()(f32x4 (&acc)[2][2][4][2], int brow, int bcol, int wr, int wc, int fr, int fq) const {
;     ...
;             } else if (mode == 1) {
;               for (int j = 0; j < 4; ++j) v[j] = v[j] * fsigmoid(v[j]);
;               tile_put4(rl, cl, pk4(v));
.LBB0_865:
	s_andn2_b64 vcc, exec, s[0:1]
	s_cbranch_vccnz .LBB0_867
	s_waitcnt vmcnt(0)
	v_mul_f32_e32 v128, 0xbfb8aa3b, v64
	v_mul_f32_e32 v129, 0xbfb8aa3b, v65
	v_exp_f32_e32 v128, v128
	v_exp_f32_e32 v129, v129
	s_nop 0
	v_pk_add_f32 v[128:129], v[128:129], 1.0 op_sel_hi:[1,0]
	s_nop 0
	s_nop 0
	v_rcp_f32_e32 v129, v129
	s_nop 0
	v_rcp_f32_e32 v128, v128
	v_mul_f32_e32 v130, 0xbfb8aa3b, v66
	v_mul_f32_e32 v131, 0xbfb8aa3b, v67
	v_exp_f32_e32 v130, v130
	v_exp_f32_e32 v131, v131
	v_pk_mul_f32 v[128:129], v[64:65], v[128:129]
	v_pk_add_f32 v[130:131], v[130:131], 1.0 op_sel_hi:[1,0]
	s_nop 0
	v_cvt_pk_bf16_f32 v128, v128, v129
	v_rcp_f32_e32 v131, v131
	s_nop 0
	v_rcp_f32_e32 v130, v130
	s_nop 0
	v_pk_mul_f32 v[130:131], v[66:67], v[130:131]
	s_nop 0
	v_cvt_pk_bf16_f32 v129, v130, v131
	v_lshlrev_b32_e32 v130, 4, v158
	v_add3_u32 v130, v159, v130, v133
	ds_write_b64 v130, v[128:129]

; DEV u32x2 pk4(f32x4 v) { u32x2 r = {pk_bf16(v[0], v[1]), pk_bf16(v[2], v[3])}; return r; }
; DEV float fsigmoid(float x) { return 1.f / (1.f + __expf(-x)); }
;   DEV void operator()(f32x4 (&acc)[2][2][4][2], int brow, int bcol, int wr, int wc, int fr, int fq) const {
;     ...
;             } else if (mode == 2) {
;               for (int j = 0; j < 4; ++j) v[j] = fsigmoid(v[j]);
;               tile_put4(rl, cl, pk4(v));
.LBB0_884:
	s_andn2_b64 vcc, exec, s[0:1]
	s_cbranch_vccnz .LBB0_886
	s_waitcnt vmcnt(0)
	v_mul_f32_e32 v128, 0xbfb8aa3b, v60
	v_mul_f32_e32 v129, 0xbfb8aa3b, v61
	v_exp_f32_e32 v128, v128
	v_exp_f32_e32 v129, v129
	s_nop 0
	v_pk_add_f32 v[128:129], v[128:129], 1.0 op_sel_hi:[1,0]
	s_nop 0
	s_nop 0
	v_rcp_f32_e32 v130, v129
	s_nop 0
	v_rcp_f32_e32 v131, v128
	v_mul_f32_e32 v128, 0xbfb8aa3b, v62
	v_mul_f32_e32 v129, 0xbfb8aa3b, v63
	v_exp_f32_e32 v128, v128
	v_exp_f32_e32 v129, v129
	s_nop 0
	v_pk_add_f32 v[128:129], v[128:129], 1.0 op_sel_hi:[1,0]
	s_nop 0
	s_nop 0
	v_rcp_f32_e32 v129, v129
	s_nop 0
	v_rcp_f32_e32 v160, v128
	v_cvt_pk_bf16_f32 v128, v131, v130
	v_lshlrev_b32_e32 v130, 4, v151
	v_cvt_pk_bf16_f32 v129, v160, v129
	v_add3_u32 v130, v159, v130, v133
	ds_write_b64 v130, v[128:129]

; DEV u32x2 pk4(f32x4 v) { u32x2 r = {pk_bf16(v[0], v[1]), pk_bf16(v[2], v[3])}; return r; }
; DEV float fsigmoid(float x) { return 1.f / (1.f + __expf(-x)); }
;   DEV void operator()(f32x4 (&acc)[2][2][4][2], int brow, int bcol, int wr, int wc, int fr, int fq) const {
;     ...
;             } else if (mode == 1) {
;               for (int j = 0; j < 4; ++j) v[j] = v[j] * fsigmoid(v[j]);
;               tile_put4(rl, cl, pk4(v));
.LBB0_887:
	s_andn2_b64 vcc, exec, s[0:1]
	s_cbranch_vccnz .LBB0_889
	s_waitcnt vmcnt(0)
	v_mul_f32_e32 v128, 0xbfb8aa3b, v60
	v_mul_f32_e32 v129, 0xbfb8aa3b, v61
	v_exp_f32_e32 v128, v128
	v_exp_f32_e32 v129, v129
	s_nop 0
	v_pk_add_f32 v[128:129], v[128:129], 1.0 op_sel_hi:[1,0]
	s_nop 0
	s_nop 0
	v_rcp_f32_e32 v129, v129
	s_nop 0
	v_rcp_f32_e32 v128, v128
	v_mul_f32_e32 v130, 0xbfb8aa3b, v62
	v_mul_f32_e32 v131, 0xbfb8aa3b, v63
	v_exp_f32_e32 v130, v130
	v_exp_f32_e32 v131, v131
	v_pk_mul_f32 v[128:129], v[60:61], v[128:129]
	v_pk_add_f32 v[130:131], v[130:131], 1.0 op_sel_hi:[1,0]
	s_nop 0
	v_cvt_pk_bf16_f32 v128, v128, v129
	v_rcp_f32_e32 v131, v131
	s_nop 0
	v_rcp_f32_e32 v130, v130
	s_nop 0
	v_pk_mul_f32 v[130:131], v[62:63], v[130:131]
	s_nop 0
	v_cvt_pk_bf16_f32 v129, v130, v131
	v_lshlrev_b32_e32 v130, 4, v151
	v_add3_u32 v130, v159, v130, v133
	ds_write_b64 v130, v[128:129]

; DEV u32x2 pk4(f32x4 v) { u32x2 r = {pk_bf16(v[0], v[1]), pk_bf16(v[2], v[3])}; return r; }
; DEV float fsigmoid(float x) { return 1.f / (1.f + __expf(-x)); }
;   DEV void operator()(f32x4 (&acc)[2][2][4][2], int brow, int bcol, int wr, int wc, int fr, int fq) const {
;     ...
;             } else if (mode == 2) {
;               for (int j = 0; j < 4; ++j) v[j] = fsigmoid(v[j]);
;               tile_put4(rl, cl, pk4(v));
.LBB0_898:
	s_andn2_b64 vcc, exec, s[0:1]
	s_cbranch_vccnz .LBB0_900
	s_waitcnt vmcnt(0)
	v_mul_f32_e32 v128, 0xbfb8aa3b, v56
	v_mul_f32_e32 v129, 0xbfb8aa3b, v57
	v_exp_f32_e32 v128, v128
	v_exp_f32_e32 v129, v129
	s_nop 0
	v_pk_add_f32 v[128:129], v[128:129], 1.0 op_sel_hi:[1,0]
	s_nop 0
	s_nop 0
	v_rcp_f32_e32 v130, v129
	s_nop 0
	v_rcp_f32_e32 v131, v128
	v_mul_f32_e32 v128, 0xbfb8aa3b, v58
	v_mul_f32_e32 v129, 0xbfb8aa3b, v59
	v_exp_f32_e32 v128, v128
	v_exp_f32_e32 v129, v129
	s_nop 0
	v_pk_add_f32 v[128:129], v[128:129], 1.0 op_sel_hi:[1,0]
	s_nop 0
	s_nop 0
	v_rcp_f32_e32 v129, v129
	s_nop 0
	v_rcp_f32_e32 v160, v128
	v_cvt_pk_bf16_f32 v128, v131, v130
	v_lshlrev_b32_e32 v130, 4, v152
	v_cvt_pk_bf16_f32 v129, v160, v129
	v_add3_u32 v130, v159, v130, v133
	ds_write_b64 v130, v[128:129]

; DEV u32x2 pk4(f32x4 v) { u32x2 r = {pk_bf16(v[0], v[1]), pk_bf16(v[2], v[3])}; return r; }
; DEV float fsigmoid(float x) { return 1.f / (1.f + __expf(-x)); }
;   DEV void operator()(f32x4 (&acc)[2][2][4][2], int brow, int bcol, int wr, int wc, int fr, int fq) const {
;     ...
;             } else if (mode == 1) {
;               for (int j = 0; j < 4; ++j) v[j] = v[j] * fsigmoid(v[j]);
;               tile_put4(rl, cl, pk4(v));
.LBB0_901:
	s_andn2_b64 vcc, exec, s[0:1]
	s_cbranch_vccnz .LBB0_903
	s_waitcnt vmcnt(0)
	v_mul_f32_e32 v128, 0xbfb8aa3b, v56
	v_mul_f32_e32 v129, 0xbfb8aa3b, v57
	v_exp_f32_e32 v128, v128
	v_exp_f32_e32 v129, v129
	s_nop 0
	v_pk_add_f32 v[128:129], v[128:129], 1.0 op_sel_hi:[1,0]
	s_nop 0
	s_nop 0
	v_rcp_f32_e32 v129, v129
	s_nop 0
	v_rcp_f32_e32 v128, v128
	v_mul_f32_e32 v130, 0xbfb8aa3b, v58
	v_mul_f32_e32 v131, 0xbfb8aa3b, v59
	v_exp_f32_e32 v130, v130
	v_exp_f32_e32 v131, v131
	v_pk_mul_f32 v[128:129], v[56:57], v[128:129]
	v_pk_add_f32 v[130:131], v[130:131], 1.0 op_sel_hi:[1,0]
	s_nop 0
	v_cvt_pk_bf16_f32 v128, v128, v129
	v_rcp_f32_e32 v131, v131
	s_nop 0
	v_rcp_f32_e32 v130, v130
	s_nop 0
	v_pk_mul_f32 v[130:131], v[58:59], v[130:131]
	s_nop 0
	v_cvt_pk_bf16_f32 v129, v130, v131
	v_lshlrev_b32_e32 v130, 4, v152
	v_add3_u32 v130, v159, v130, v133
	ds_write_b64 v130, v[128:129]

; DEV u32x2 pk4(f32x4 v) { u32x2 r = {pk_bf16(v[0], v[1]), pk_bf16(v[2], v[3])}; return r; }
; DEV float fsigmoid(float x) { return 1.f / (1.f + __expf(-x)); }
;   DEV void operator()(f32x4 (&acc)[2][2][4][2], int brow, int bcol, int wr, int wc, int fr, int fq) const {
;     ...
;             } else if (mode == 2) {
;               for (int j = 0; j < 4; ++j) v[j] = fsigmoid(v[j]);
;               tile_put4(rl, cl, pk4(v));
.LBB0_912:
	s_andn2_b64 vcc, exec, s[0:1]
	s_cbranch_vccnz .LBB0_914
	s_waitcnt vmcnt(0)
	v_mul_f32_e32 v128, 0xbfb8aa3b, v52
	v_mul_f32_e32 v129, 0xbfb8aa3b, v53
	v_exp_f32_e32 v128, v128
	v_exp_f32_e32 v129, v129
	s_nop 0
	v_pk_add_f32 v[128:129], v[128:129], 1.0 op_sel_hi:[1,0]
	s_nop 0
	s_nop 0
	v_rcp_f32_e32 v130, v129
	s_nop 0
	v_rcp_f32_e32 v131, v128
	v_mul_f32_e32 v128, 0xbfb8aa3b, v54
	v_mul_f32_e32 v129, 0xbfb8aa3b, v55
	v_exp_f32_e32 v128, v128
	v_exp_f32_e32 v129, v129
	s_nop 0
	v_pk_add_f32 v[128:129], v[128:129], 1.0 op_sel_hi:[1,0]
	s_nop 0
	s_nop 0
	v_rcp_f32_e32 v129, v129
	s_nop 0
	v_rcp_f32_e32 v160, v128
	v_cvt_pk_bf16_f32 v128, v131, v130
	v_lshlrev_b32_e32 v130, 4, v153
	v_cvt_pk_bf16_f32 v129, v160, v129
	v_add3_u32 v130, v159, v130, v133
	ds_write_b64 v130, v[128:129]

; DEV u32x2 pk4(f32x4 v) { u32x2 r = {pk_bf16(v[0], v[1]), pk_bf16(v[2], v[3])}; return r; }
; DEV float fsigmoid(float x) { return 1.f / (1.f + __expf(-x)); }
;   DEV void operator()(f32x4 (&acc)[2][2][4][2], int brow, int bcol, int wr, int wc, int fr, int fq) const {
;     ...
;             } else if (mode == 1) {
;               for (int j = 0; j < 4; ++j) v[j] = v[j] * fsigmoid(v[j]);
;               tile_put4(rl, cl, pk4(v));
.LBB0_915:
	s_andn2_b64 vcc, exec, s[0:1]
	s_cbranch_vccnz .LBB0_917
	s_waitcnt vmcnt(0)
	v_mul_f32_e32 v128, 0xbfb8aa3b, v52
	v_mul_f32_e32 v129, 0xbfb8aa3b, v53
	v_exp_f32_e32 v128, v128
	v_exp_f32_e32 v129, v129
	s_nop 0
	v_pk_add_f32 v[128:129], v[128:129], 1.0 op_sel_hi:[1,0]
	s_nop 0
	s_nop 0
	v_rcp_f32_e32 v129, v129
	s_nop 0
	v_rcp_f32_e32 v128, v128
	v_mul_f32_e32 v130, 0xbfb8aa3b, v54
	v_mul_f32_e32 v131, 0xbfb8aa3b, v55
	v_exp_f32_e32 v130, v130
	v_exp_f32_e32 v131, v131
	v_pk_mul_f32 v[128:129], v[52:53], v[128:129]
	v_pk_add_f32 v[130:131], v[130:131], 1.0 op_sel_hi:[1,0]
	s_nop 0
	v_cvt_pk_bf16_f32 v128, v128, v129
	v_rcp_f32_e32 v131, v131
	s_nop 0
	v_rcp_f32_e32 v130, v130
	s_nop 0
	v_pk_mul_f32 v[130:131], v[54:55], v[130:131]
	s_nop 0
	v_cvt_pk_bf16_f32 v129, v130, v131
	v_lshlrev_b32_e32 v130, 4, v153
	v_add3_u32 v130, v159, v130, v133
	ds_write_b64 v130, v[128:129]

; DEV u32x2 pk4(f32x4 v) { u32x2 r = {pk_bf16(v[0], v[1]), pk_bf16(v[2], v[3])}; return r; }
; DEV float fsigmoid(float x) { return 1.f / (1.f + __expf(-x)); }
;   DEV void operator()(f32x4 (&acc)[2][2][4][2], int brow, int bcol, int wr, int wc, int fr, int fq) const {
;     ...
;             } else if (mode == 2) {
;               for (int j = 0; j < 4; ++j) v[j] = fsigmoid(v[j]);
;               tile_put4(rl, cl, pk4(v));
.LBB0_926:
	s_andn2_b64 vcc, exec, s[0:1]
	s_cbranch_vccnz .LBB0_928
	s_waitcnt vmcnt(0)
	v_mul_f32_e32 v128, 0xbfb8aa3b, v48
	v_mul_f32_e32 v129, 0xbfb8aa3b, v49
	v_exp_f32_e32 v128, v128
	v_exp_f32_e32 v129, v129
	s_nop 0
	v_pk_add_f32 v[128:129], v[128:129], 1.0 op_sel_hi:[1,0]
	s_nop 0
	s_nop 0
	v_rcp_f32_e32 v130, v129
	s_nop 0
	v_rcp_f32_e32 v131, v128
	v_mul_f32_e32 v128, 0xbfb8aa3b, v50
	v_mul_f32_e32 v129, 0xbfb8aa3b, v51
	v_exp_f32_e32 v128, v128
	v_exp_f32_e32 v129, v129
	s_nop 0
	v_pk_add_f32 v[128:129], v[128:129], 1.0 op_sel_hi:[1,0]
	s_nop 0
	s_nop 0
	v_rcp_f32_e32 v129, v129
	s_nop 0
	v_rcp_f32_e32 v136, v128
	v_cvt_pk_bf16_f32 v128, v131, v130
	v_lshlrev_b32_e32 v130, 4, v154
	v_cvt_pk_bf16_f32 v129, v136, v129
	v_add3_u32 v130, v159, v130, v133
	ds_write_b64 v130, v[128:129]

; DEV u32x2 pk4(f32x4 v) { u32x2 r = {pk_bf16(v[0], v[1]), pk_bf16(v[2], v[3])}; return r; }
; DEV float fsigmoid(float x) { return 1.f / (1.f + __expf(-x)); }
;   DEV void operator()(f32x4 (&acc)[2][2][4][2], int brow, int bcol, int wr, int wc, int fr, int fq) const {
;     ...
;             } else if (mode == 1) {
;               for (int j = 0; j < 4; ++j) v[j] = v[j] * fsigmoid(v[j]);
;               tile_put4(rl, cl, pk4(v));
.LBB0_929:
	s_andn2_b64 vcc, exec, s[0:1]
	s_cbranch_vccnz .LBB0_931
	s_waitcnt vmcnt(0)
	v_mul_f32_e32 v128, 0xbfb8aa3b, v48
	v_mul_f32_e32 v129, 0xbfb8aa3b, v49
	v_exp_f32_e32 v128, v128
	v_exp_f32_e32 v129, v129
	s_nop 0
	v_pk_add_f32 v[128:129], v[128:129], 1.0 op_sel_hi:[1,0]
	s_nop 0
	s_nop 0
	v_rcp_f32_e32 v129, v129
	s_nop 0
	v_rcp_f32_e32 v128, v128
	v_mul_f32_e32 v130, 0xbfb8aa3b, v50
	v_mul_f32_e32 v131, 0xbfb8aa3b, v51
	v_exp_f32_e32 v130, v130
	v_exp_f32_e32 v131, v131
	v_pk_mul_f32 v[128:129], v[48:49], v[128:129]
	v_pk_add_f32 v[130:131], v[130:131], 1.0 op_sel_hi:[1,0]
	s_nop 0
	v_cvt_pk_bf16_f32 v128, v128, v129
	v_rcp_f32_e32 v131, v131
	s_nop 0
	v_rcp_f32_e32 v130, v130
	s_nop 0
	v_pk_mul_f32 v[130:131], v[50:51], v[130:131]
	s_nop 0
	v_cvt_pk_bf16_f32 v129, v130, v131
	v_lshlrev_b32_e32 v130, 4, v154
	v_add3_u32 v130, v159, v130, v133
	ds_write_b64 v130, v[128:129]

; DEV u32x2 pk4(f32x4 v) { u32x2 r = {pk_bf16(v[0], v[1]), pk_bf16(v[2], v[3])}; return r; }
; DEV float fsigmoid(float x) { return 1.f / (1.f + __expf(-x)); }
;   DEV void operator()(f32x4 (&acc)[2][2][4][2], int brow, int bcol, int wr, int wc, int fr, int fq) const {
;     ...
;             } else if (mode == 2) {
;               for (int j = 0; j < 4; ++j) v[j] = fsigmoid(v[j]);
;               tile_put4(rl, cl, pk4(v));
.LBB0_948:
	s_andn2_b64 vcc, exec, s[0:1]
	s_cbranch_vccnz .LBB0_950
	s_waitcnt vmcnt(0)
	v_mul_f32_e32 v128, 0xbfb8aa3b, v44
	v_mul_f32_e32 v129, 0xbfb8aa3b, v45
	v_exp_f32_e32 v128, v128
	v_exp_f32_e32 v129, v129
	s_nop 0
	v_pk_add_f32 v[128:129], v[128:129], 1.0 op_sel_hi:[1,0]
	s_nop 0
	s_nop 0
	v_rcp_f32_e32 v130, v129
	s_nop 0
	v_rcp_f32_e32 v131, v128
	v_mul_f32_e32 v128, 0xbfb8aa3b, v46
	v_mul_f32_e32 v129, 0xbfb8aa3b, v47
	v_exp_f32_e32 v128, v128
	v_exp_f32_e32 v129, v129
	s_nop 0
	v_pk_add_f32 v[128:129], v[128:129], 1.0 op_sel_hi:[1,0]
	s_nop 0
	s_nop 0
	v_rcp_f32_e32 v129, v129
	s_nop 0
	v_rcp_f32_e32 v160, v128
	v_cvt_pk_bf16_f32 v128, v131, v130
	v_lshlrev_b32_e32 v130, 4, v155
	v_cvt_pk_bf16_f32 v129, v160, v129
	v_add3_u32 v130, v159, v130, v133
	ds_write_b64 v130, v[128:129]

; DEV u32x2 pk4(f32x4 v) { u32x2 r = {pk_bf16(v[0], v[1]), pk_bf16(v[2], v[3])}; return r; }
; DEV float fsigmoid(float x) { return 1.f / (1.f + __expf(-x)); }
;   DEV void operator()(f32x4 (&acc)[2][2][4][2], int brow, int bcol, int wr, int wc, int fr, int fq) const {
;     ...
;             } else if (mode == 1) {
;               for (int j = 0; j < 4; ++j) v[j] = v[j] * fsigmoid(v[j]);
;               tile_put4(rl, cl, pk4(v));
.LBB0_951:
	s_andn2_b64 vcc, exec, s[0:1]
	s_cbranch_vccnz .LBB0_953
	s_waitcnt vmcnt(0)
	v_mul_f32_e32 v128, 0xbfb8aa3b, v44
	v_mul_f32_e32 v129, 0xbfb8aa3b, v45
	v_exp_f32_e32 v128, v128
	v_exp_f32_e32 v129, v129
	s_nop 0
	v_pk_add_f32 v[128:129], v[128:129], 1.0 op_sel_hi:[1,0]
	s_nop 0
	s_nop 0
	v_rcp_f32_e32 v129, v129
	s_nop 0
	v_rcp_f32_e32 v128, v128
	v_mul_f32_e32 v130, 0xbfb8aa3b, v46
	v_mul_f32_e32 v131, 0xbfb8aa3b, v47
	v_exp_f32_e32 v130, v130
	v_exp_f32_e32 v131, v131
	v_pk_mul_f32 v[128:129], v[44:45], v[128:129]
	v_pk_add_f32 v[130:131], v[130:131], 1.0 op_sel_hi:[1,0]
	s_nop 0
	v_cvt_pk_bf16_f32 v128, v128, v129
	v_rcp_f32_e32 v131, v131
	s_nop 0
	v_rcp_f32_e32 v130, v130
	s_nop 0
	v_pk_mul_f32 v[130:131], v[46:47], v[130:131]
	s_nop 0
	v_cvt_pk_bf16_f32 v129, v130, v131
	v_lshlrev_b32_e32 v130, 4, v155
	v_add3_u32 v130, v159, v130, v133
	ds_write_b64 v130, v[128:129]

; DEV u32x2 pk4(f32x4 v) { u32x2 r = {pk_bf16(v[0], v[1]), pk_bf16(v[2], v[3])}; return r; }
; DEV float fsigmoid(float x) { return 1.f / (1.f + __expf(-x)); }
;   DEV void operator()(f32x4 (&acc)[2][2][4][2], int brow, int bcol, int wr, int wc, int fr, int fq) const {
;     ...
;             } else if (mode == 2) {
;               for (int j = 0; j < 4; ++j) v[j] = fsigmoid(v[j]);
;               tile_put4(rl, cl, pk4(v));
.LBB0_962:
	s_andn2_b64 vcc, exec, s[0:1]
	s_cbranch_vccnz .LBB0_964
	s_waitcnt vmcnt(0)
	v_mul_f32_e32 v128, 0xbfb8aa3b, v40
	v_mul_f32_e32 v129, 0xbfb8aa3b, v41
	v_exp_f32_e32 v128, v128
	v_exp_f32_e32 v129, v129
	s_nop 0
	v_pk_add_f32 v[128:129], v[128:129], 1.0 op_sel_hi:[1,0]
	s_nop 0
	s_nop 0
	v_rcp_f32_e32 v130, v129
	s_nop 0
	v_rcp_f32_e32 v131, v128
	v_mul_f32_e32 v128, 0xbfb8aa3b, v42
	v_mul_f32_e32 v129, 0xbfb8aa3b, v43
	v_exp_f32_e32 v128, v128
	v_exp_f32_e32 v129, v129
	s_nop 0
	v_pk_add_f32 v[128:129], v[128:129], 1.0 op_sel_hi:[1,0]
	s_nop 0
	s_nop 0
	v_rcp_f32_e32 v129, v129
	s_nop 0
	v_rcp_f32_e32 v160, v128
	v_cvt_pk_bf16_f32 v128, v131, v130
	v_lshlrev_b32_e32 v130, 4, v156
	v_cvt_pk_bf16_f32 v129, v160, v129
	v_add3_u32 v130, v159, v130, v133
	ds_write_b64 v130, v[128:129]

; DEV u32x2 pk4(f32x4 v) { u32x2 r = {pk_bf16(v[0], v[1]), pk_bf16(v[2], v[3])}; return r; }
; DEV float fsigmoid(float x) { return 1.f / (1.f + __expf(-x)); }
;   DEV void operator()(f32x4 (&acc)[2][2][4][2], int brow, int bcol, int wr, int wc, int fr, int fq) const {
;     ...
;             } else if (mode == 1) {
;               for (int j = 0; j < 4; ++j) v[j] = v[j] * fsigmoid(v[j]);
;               tile_put4(rl, cl, pk4(v));
.LBB0_965:
	s_andn2_b64 vcc, exec, s[0:1]
	s_cbranch_vccnz .LBB0_967
	s_waitcnt vmcnt(0)
	v_mul_f32_e32 v128, 0xbfb8aa3b, v40
	v_mul_f32_e32 v129, 0xbfb8aa3b, v41
	v_exp_f32_e32 v128, v128
	v_exp_f32_e32 v129, v129
	s_nop 0
	v_pk_add_f32 v[128:129], v[128:129], 1.0 op_sel_hi:[1,0]
	s_nop 0
	s_nop 0
	v_rcp_f32_e32 v129, v129
	s_nop 0
	v_rcp_f32_e32 v128, v128
	v_mul_f32_e32 v130, 0xbfb8aa3b, v42
	v_mul_f32_e32 v131, 0xbfb8aa3b, v43
	v_exp_f32_e32 v130, v130
	v_exp_f32_e32 v131, v131
	v_pk_mul_f32 v[128:129], v[40:41], v[128:129]
	v_pk_add_f32 v[130:131], v[130:131], 1.0 op_sel_hi:[1,0]
	s_nop 0
	v_cvt_pk_bf16_f32 v128, v128, v129
	v_rcp_f32_e32 v131, v131
	s_nop 0
	v_rcp_f32_e32 v130, v130
	s_nop 0
	v_pk_mul_f32 v[130:131], v[42:43], v[130:131]
	s_nop 0
	v_cvt_pk_bf16_f32 v129, v130, v131
	v_lshlrev_b32_e32 v130, 4, v156
	v_add3_u32 v130, v159, v130, v133
	ds_write_b64 v130, v[128:129]

; DEV u32x2 pk4(f32x4 v) { u32x2 r = {pk_bf16(v[0], v[1]), pk_bf16(v[2], v[3])}; return r; }
; DEV float fsigmoid(float x) { return 1.f / (1.f + __expf(-x)); }
;   DEV void operator()(f32x4 (&acc)[2][2][4][2], int brow, int bcol, int wr, int wc, int fr, int fq) const {
;     ...
;             } else if (mode == 2) {
;               for (int j = 0; j < 4; ++j) v[j] = fsigmoid(v[j]);
;               tile_put4(rl, cl, pk4(v));
.LBB0_976:
	s_andn2_b64 vcc, exec, s[0:1]
	s_cbranch_vccnz .LBB0_978
	s_waitcnt vmcnt(0)
	v_mul_f32_e32 v128, 0xbfb8aa3b, v36
	v_mul_f32_e32 v129, 0xbfb8aa3b, v37
	v_exp_f32_e32 v128, v128
	v_exp_f32_e32 v129, v129
	s_nop 0
	v_pk_add_f32 v[128:129], v[128:129], 1.0 op_sel_hi:[1,0]
	s_nop 0
	s_nop 0
	v_rcp_f32_e32 v130, v129
	s_nop 0
	v_rcp_f32_e32 v131, v128
	v_mul_f32_e32 v128, 0xbfb8aa3b, v38
	v_mul_f32_e32 v129, 0xbfb8aa3b, v39
	v_exp_f32_e32 v128, v128
	v_exp_f32_e32 v129, v129
	s_nop 0
	v_pk_add_f32 v[128:129], v[128:129], 1.0 op_sel_hi:[1,0]
	s_nop 0
	s_nop 0
	v_rcp_f32_e32 v129, v129
	s_nop 0
	v_rcp_f32_e32 v160, v128
	v_cvt_pk_bf16_f32 v128, v131, v130
	v_lshlrev_b32_e32 v130, 4, v157
	v_cvt_pk_bf16_f32 v129, v160, v129
	v_add3_u32 v130, v159, v130, v133
	ds_write_b64 v130, v[128:129]

; DEV u32x2 pk4(f32x4 v) { u32x2 r = {pk_bf16(v[0], v[1]), pk_bf16(v[2], v[3])}; return r; }
; DEV float fsigmoid(float x) { return 1.f / (1.f + __expf(-x)); }
;   DEV void operator()(f32x4 (&acc)[2][2][4][2], int brow, int bcol, int wr, int wc, int fr, int fq) const {
;     ...
;             } else if (mode == 1) {
;               for (int j = 0; j < 4; ++j) v[j] = v[j] * fsigmoid(v[j]);
;               tile_put4(rl, cl, pk4(v));
.LBB0_979:
	s_andn2_b64 vcc, exec, s[0:1]
	s_cbranch_vccnz .LBB0_981
	s_waitcnt vmcnt(0)
	v_mul_f32_e32 v128, 0xbfb8aa3b, v36
	v_mul_f32_e32 v129, 0xbfb8aa3b, v37
	v_exp_f32_e32 v128, v128
	v_exp_f32_e32 v129, v129
	s_nop 0
	v_pk_add_f32 v[128:129], v[128:129], 1.0 op_sel_hi:[1,0]
	s_nop 0
	s_nop 0
	v_rcp_f32_e32 v129, v129
	s_nop 0
	v_rcp_f32_e32 v128, v128
	v_mul_f32_e32 v130, 0xbfb8aa3b, v38
	v_mul_f32_e32 v131, 0xbfb8aa3b, v39
	v_exp_f32_e32 v130, v130
	v_exp_f32_e32 v131, v131
	v_pk_mul_f32 v[128:129], v[36:37], v[128:129]
	v_pk_add_f32 v[130:131], v[130:131], 1.0 op_sel_hi:[1,0]
	s_nop 0
	v_cvt_pk_bf16_f32 v128, v128, v129
	v_rcp_f32_e32 v131, v131
	s_nop 0
	v_rcp_f32_e32 v130, v130
	s_nop 0
	v_pk_mul_f32 v[130:131], v[38:39], v[130:131]
	s_nop 0
	v_cvt_pk_bf16_f32 v129, v130, v131
	v_lshlrev_b32_e32 v130, 4, v157
	v_add3_u32 v130, v159, v130, v133
	ds_write_b64 v130, v[128:129]

; DEV u32x2 pk4(f32x4 v) { u32x2 r = {pk_bf16(v[0], v[1]), pk_bf16(v[2], v[3])}; return r; }
; DEV float fsigmoid(float x) { return 1.f / (1.f + __expf(-x)); }
;   DEV void operator()(f32x4 (&acc)[2][2][4][2], int brow, int bcol, int wr, int wc, int fr, int fq) const {
;     ...
;             } else if (mode == 2) {
;               for (int j = 0; j < 4; ++j) v[j] = fsigmoid(v[j]);
;               tile_put4(rl, cl, pk4(v));
.LBB0_990:
	s_andn2_b64 vcc, exec, s[0:1]
	s_cbranch_vccnz .LBB0_992
	s_waitcnt vmcnt(0)
	v_mul_f32_e32 v128, 0xbfb8aa3b, v32
	v_mul_f32_e32 v129, 0xbfb8aa3b, v33
	v_exp_f32_e32 v128, v128
	v_exp_f32_e32 v129, v129
	s_nop 0
	v_pk_add_f32 v[128:129], v[128:129], 1.0 op_sel_hi:[1,0]
	s_nop 0
	s_nop 0
	v_rcp_f32_e32 v130, v129
	s_nop 0
	v_rcp_f32_e32 v131, v128
	v_mul_f32_e32 v128, 0xbfb8aa3b, v34
	v_mul_f32_e32 v129, 0xbfb8aa3b, v35
	v_exp_f32_e32 v128, v128
	v_exp_f32_e32 v129, v129
	s_nop 0
	v_pk_add_f32 v[128:129], v[128:129], 1.0 op_sel_hi:[1,0]
	s_nop 0
	s_nop 0
	v_rcp_f32_e32 v129, v129
	s_nop 0
	v_rcp_f32_e32 v136, v128
	v_cvt_pk_bf16_f32 v128, v131, v130
	v_lshlrev_b32_e32 v130, 4, v158
	v_cvt_pk_bf16_f32 v129, v136, v129
	v_add3_u32 v130, v159, v130, v133
	ds_write_b64 v130, v[128:129]

; DEV u32x2 pk4(f32x4 v) { u32x2 r = {pk_bf16(v[0], v[1]), pk_bf16(v[2], v[3])}; return r; }
; DEV float fsigmoid(float x) { return 1.f / (1.f + __expf(-x)); }
;   DEV void operator()(f32x4 (&acc)[2][2][4][2], int brow, int bcol, int wr, int wc, int fr, int fq) const {
;     ...
;             } else if (mode == 1) {
;               for (int j = 0; j < 4; ++j) v[j] = v[j] * fsigmoid(v[j]);
;               tile_put4(rl, cl, pk4(v));
.LBB0_993:
	s_andn2_b64 vcc, exec, s[0:1]
	s_cbranch_vccnz .LBB0_995
	s_waitcnt vmcnt(0)
	v_mul_f32_e32 v128, 0xbfb8aa3b, v32
	v_mul_f32_e32 v129, 0xbfb8aa3b, v33
	v_exp_f32_e32 v128, v128
	v_exp_f32_e32 v129, v129
	s_nop 0
	v_pk_add_f32 v[128:129], v[128:129], 1.0 op_sel_hi:[1,0]
	s_nop 0
	s_nop 0
	v_rcp_f32_e32 v129, v129
	s_nop 0
	v_rcp_f32_e32 v128, v128
	v_mul_f32_e32 v130, 0xbfb8aa3b, v34
	v_mul_f32_e32 v131, 0xbfb8aa3b, v35
	v_exp_f32_e32 v130, v130
	v_exp_f32_e32 v131, v131
	v_pk_mul_f32 v[128:129], v[32:33], v[128:129]
	v_pk_add_f32 v[130:131], v[130:131], 1.0 op_sel_hi:[1,0]
	s_nop 0
	v_cvt_pk_bf16_f32 v128, v128, v129
	v_rcp_f32_e32 v131, v131
	s_nop 0
	v_rcp_f32_e32 v130, v130
	s_nop 0
	v_pk_mul_f32 v[130:131], v[34:35], v[130:131]
	s_nop 0
	v_cvt_pk_bf16_f32 v129, v130, v131
	v_lshlrev_b32_e32 v130, 4, v158
	v_add3_u32 v130, v159, v130, v133
	ds_write_b64 v130, v[128:129]

; DEV u32x2 pk4(f32x4 v) { u32x2 r = {pk_bf16(v[0], v[1]), pk_bf16(v[2], v[3])}; return r; }
; DEV float fsigmoid(float x) { return 1.f / (1.f + __expf(-x)); }
;   DEV void operator()(f32x4 (&acc)[2][2][4][2], int brow, int bcol, int wr, int wc, int fr, int fq) const {
;     ...
;             } else if (mode == 2) {
;               for (int j = 0; j < 4; ++j) v[j] = fsigmoid(v[j]);
;               tile_put4(rl, cl, pk4(v));
.LBB0_1012:
	s_andn2_b64 vcc, exec, s[0:1]
	s_cbranch_vccnz .LBB0_1014
	s_waitcnt vmcnt(0)
	v_mul_f32_e32 v128, 0xbfb8aa3b, v28
	v_mul_f32_e32 v129, 0xbfb8aa3b, v29
	v_exp_f32_e32 v128, v128
	v_exp_f32_e32 v129, v129
	s_nop 0
	v_pk_add_f32 v[128:129], v[128:129], 1.0 op_sel_hi:[1,0]
	s_nop 0
	s_nop 0
	v_rcp_f32_e32 v130, v129
	s_nop 0
	v_rcp_f32_e32 v131, v128
	v_mul_f32_e32 v128, 0xbfb8aa3b, v30
	v_mul_f32_e32 v129, 0xbfb8aa3b, v31
	v_exp_f32_e32 v128, v128
	v_exp_f32_e32 v129, v129
	s_nop 0
	v_pk_add_f32 v[128:129], v[128:129], 1.0 op_sel_hi:[1,0]
	s_nop 0
	s_nop 0
	v_rcp_f32_e32 v129, v129
	s_nop 0
	v_rcp_f32_e32 v160, v128
	v_cvt_pk_bf16_f32 v128, v131, v130
	v_lshlrev_b32_e32 v130, 4, v151
	v_cvt_pk_bf16_f32 v129, v160, v129
	v_add3_u32 v130, v159, v130, v133
	ds_write_b64 v130, v[128:129]

; DEV u32x2 pk4(f32x4 v) { u32x2 r = {pk_bf16(v[0], v[1]), pk_bf16(v[2], v[3])}; return r; }
; DEV float fsigmoid(float x) { return 1.f / (1.f + __expf(-x)); }
;   DEV void operator()(f32x4 (&acc)[2][2][4][2], int brow, int bcol, int wr, int wc, int fr, int fq) const {
;     ...
;             } else if (mode == 1) {
;               for (int j = 0; j < 4; ++j) v[j] = v[j] * fsigmoid(v[j]);
;               tile_put4(rl, cl, pk4(v));
.LBB0_1015:
	s_andn2_b64 vcc, exec, s[0:1]
	s_cbranch_vccnz .LBB0_1017
	s_waitcnt vmcnt(0)
	v_mul_f32_e32 v128, 0xbfb8aa3b, v28
	v_mul_f32_e32 v129, 0xbfb8aa3b, v29
	v_exp_f32_e32 v128, v128
	v_exp_f32_e32 v129, v129
	s_nop 0
	v_pk_add_f32 v[128:129], v[128:129], 1.0 op_sel_hi:[1,0]
	s_nop 0
	s_nop 0
	v_rcp_f32_e32 v129, v129
	s_nop 0
	v_rcp_f32_e32 v128, v128
	v_mul_f32_e32 v130, 0xbfb8aa3b, v30
	v_mul_f32_e32 v131, 0xbfb8aa3b, v31
	v_exp_f32_e32 v130, v130
	v_exp_f32_e32 v131, v131
	v_pk_mul_f32 v[128:129], v[28:29], v[128:129]
	v_pk_add_f32 v[130:131], v[130:131], 1.0 op_sel_hi:[1,0]
	s_nop 0
	v_cvt_pk_bf16_f32 v128, v128, v129
	v_rcp_f32_e32 v131, v131
	s_nop 0
	v_rcp_f32_e32 v130, v130
	s_nop 0
	v_pk_mul_f32 v[130:131], v[30:31], v[130:131]
	s_nop 0
	v_cvt_pk_bf16_f32 v129, v130, v131
	v_lshlrev_b32_e32 v130, 4, v151
	v_add3_u32 v130, v159, v130, v133
	ds_write_b64 v130, v[128:129]

; DEV u32x2 pk4(f32x4 v) { u32x2 r = {pk_bf16(v[0], v[1]), pk_bf16(v[2], v[3])}; return r; }
; DEV float fsigmoid(float x) { return 1.f / (1.f + __expf(-x)); }
;   DEV void operator()(f32x4 (&acc)[2][2][4][2], int brow, int bcol, int wr, int wc, int fr, int fq) const {
;     ...
;             } else if (mode == 2) {
;               for (int j = 0; j < 4; ++j) v[j] = fsigmoid(v[j]);
;               tile_put4(rl, cl, pk4(v));
.LBB0_1026:
	s_andn2_b64 vcc, exec, s[0:1]
	s_cbranch_vccnz .LBB0_1028
	s_waitcnt vmcnt(0)
	v_mul_f32_e32 v128, 0xbfb8aa3b, v24
	v_mul_f32_e32 v129, 0xbfb8aa3b, v25
	v_exp_f32_e32 v128, v128
	v_exp_f32_e32 v129, v129
	s_nop 0
	v_pk_add_f32 v[128:129], v[128:129], 1.0 op_sel_hi:[1,0]
	s_nop 0
	s_nop 0
	v_rcp_f32_e32 v130, v129
	s_nop 0
	v_rcp_f32_e32 v131, v128
	v_mul_f32_e32 v128, 0xbfb8aa3b, v26
	v_mul_f32_e32 v129, 0xbfb8aa3b, v27
	v_exp_f32_e32 v128, v128
	v_exp_f32_e32 v129, v129
	s_nop 0
	v_pk_add_f32 v[128:129], v[128:129], 1.0 op_sel_hi:[1,0]
	s_nop 0
	s_nop 0
	v_rcp_f32_e32 v129, v129
	s_nop 0
	v_rcp_f32_e32 v151, v128
	v_cvt_pk_bf16_f32 v128, v131, v130
	v_lshlrev_b32_e32 v130, 4, v152
	v_cvt_pk_bf16_f32 v129, v151, v129
	v_add3_u32 v130, v159, v130, v133
	ds_write_b64 v130, v[128:129]

; DEV u32x2 pk4(f32x4 v) { u32x2 r = {pk_bf16(v[0], v[1]), pk_bf16(v[2], v[3])}; return r; }
; DEV float fsigmoid(float x) { return 1.f / (1.f + __expf(-x)); }
;   DEV void operator()(f32x4 (&acc)[2][2][4][2], int brow, int bcol, int wr, int wc, int fr, int fq) const {
;     ...
;             } else if (mode == 1) {
;               for (int j = 0; j < 4; ++j) v[j] = v[j] * fsigmoid(v[j]);
;               tile_put4(rl, cl, pk4(v));
.LBB0_1029:
	s_andn2_b64 vcc, exec, s[0:1]
	s_cbranch_vccnz .LBB0_1031
	s_waitcnt vmcnt(0)
	v_mul_f32_e32 v128, 0xbfb8aa3b, v24
	v_mul_f32_e32 v129, 0xbfb8aa3b, v25
	v_exp_f32_e32 v128, v128
	v_exp_f32_e32 v129, v129
	s_nop 0
	v_pk_add_f32 v[128:129], v[128:129], 1.0 op_sel_hi:[1,0]
	s_nop 0
	s_nop 0
	v_rcp_f32_e32 v129, v129
	s_nop 0
	v_rcp_f32_e32 v128, v128
	v_mul_f32_e32 v130, 0xbfb8aa3b, v26
	v_mul_f32_e32 v131, 0xbfb8aa3b, v27
	v_exp_f32_e32 v130, v130
	v_exp_f32_e32 v131, v131
	v_pk_mul_f32 v[128:129], v[24:25], v[128:129]
	v_pk_add_f32 v[130:131], v[130:131], 1.0 op_sel_hi:[1,0]
	s_nop 0
	v_cvt_pk_bf16_f32 v128, v128, v129
	v_rcp_f32_e32 v131, v131
	s_nop 0
	v_rcp_f32_e32 v130, v130
	s_nop 0
	v_pk_mul_f32 v[130:131], v[26:27], v[130:131]
	s_nop 0
	v_cvt_pk_bf16_f32 v129, v130, v131
	v_lshlrev_b32_e32 v130, 4, v152
	v_add3_u32 v130, v159, v130, v133
	ds_write_b64 v130, v[128:129]

; DEV u32x2 pk4(f32x4 v) { u32x2 r = {pk_bf16(v[0], v[1]), pk_bf16(v[2], v[3])}; return r; }
; DEV float fsigmoid(float x) { return 1.f / (1.f + __expf(-x)); }
;   DEV void operator()(f32x4 (&acc)[2][2][4][2], int brow, int bcol, int wr, int wc, int fr, int fq) const {
;     ...
;             } else if (mode == 2) {
;               for (int j = 0; j < 4; ++j) v[j] = fsigmoid(v[j]);
;               tile_put4(rl, cl, pk4(v));
.LBB0_1040:
	s_andn2_b64 vcc, exec, s[0:1]
	s_cbranch_vccnz .LBB0_1042
	s_waitcnt vmcnt(0)
	v_mul_f32_e32 v128, 0xbfb8aa3b, v20
	v_mul_f32_e32 v129, 0xbfb8aa3b, v21
	v_exp_f32_e32 v128, v128
	v_exp_f32_e32 v129, v129
	s_nop 0
	v_pk_add_f32 v[128:129], v[128:129], 1.0 op_sel_hi:[1,0]
	s_nop 0
	s_nop 0
	v_rcp_f32_e32 v130, v129
	s_nop 0
	v_rcp_f32_e32 v131, v128
	v_mul_f32_e32 v128, 0xbfb8aa3b, v22
	v_mul_f32_e32 v129, 0xbfb8aa3b, v23
	v_exp_f32_e32 v128, v128
	v_exp_f32_e32 v129, v129
	s_nop 0
	v_pk_add_f32 v[128:129], v[128:129], 1.0 op_sel_hi:[1,0]
	s_nop 0
	s_nop 0
	v_rcp_f32_e32 v129, v129
	s_nop 0
	v_rcp_f32_e32 v151, v128
	v_cvt_pk_bf16_f32 v128, v131, v130
	v_lshlrev_b32_e32 v130, 4, v153
	v_cvt_pk_bf16_f32 v129, v151, v129
	v_add3_u32 v130, v159, v130, v133
	ds_write_b64 v130, v[128:129]

; DEV u32x2 pk4(f32x4 v) { u32x2 r = {pk_bf16(v[0], v[1]), pk_bf16(v[2], v[3])}; return r; }
; DEV float fsigmoid(float x) { return 1.f / (1.f + __expf(-x)); }
;   DEV void operator()(f32x4 (&acc)[2][2][4][2], int brow, int bcol, int wr, int wc, int fr, int fq) const {
;     ...
;             } else if (mode == 1) {
;               for (int j = 0; j < 4; ++j) v[j] = v[j] * fsigmoid(v[j]);
;               tile_put4(rl, cl, pk4(v));
.LBB0_1043:
	s_andn2_b64 vcc, exec, s[0:1]
	s_cbranch_vccnz .LBB0_1045
	s_waitcnt vmcnt(0)
	v_mul_f32_e32 v128, 0xbfb8aa3b, v20
	v_mul_f32_e32 v129, 0xbfb8aa3b, v21
	v_exp_f32_e32 v128, v128
	v_exp_f32_e32 v129, v129
	s_nop 0
	v_pk_add_f32 v[128:129], v[128:129], 1.0 op_sel_hi:[1,0]
	s_nop 0
	s_nop 0
	v_rcp_f32_e32 v129, v129
	s_nop 0
	v_rcp_f32_e32 v128, v128
	v_mul_f32_e32 v130, 0xbfb8aa3b, v22
	v_mul_f32_e32 v131, 0xbfb8aa3b, v23
	v_exp_f32_e32 v130, v130
	v_exp_f32_e32 v131, v131
	v_pk_mul_f32 v[128:129], v[20:21], v[128:129]
	v_pk_add_f32 v[130:131], v[130:131], 1.0 op_sel_hi:[1,0]
	s_nop 0
	v_cvt_pk_bf16_f32 v128, v128, v129
	v_rcp_f32_e32 v131, v131
	s_nop 0
	v_rcp_f32_e32 v130, v130
	s_nop 0
	v_pk_mul_f32 v[130:131], v[22:23], v[130:131]
	s_nop 0
	v_cvt_pk_bf16_f32 v129, v130, v131
	v_lshlrev_b32_e32 v130, 4, v153
	v_add3_u32 v130, v159, v130, v133
	ds_write_b64 v130, v[128:129]

; DEV u32x2 pk4(f32x4 v) { u32x2 r = {pk_bf16(v[0], v[1]), pk_bf16(v[2], v[3])}; return r; }
; DEV float fsigmoid(float x) { return 1.f / (1.f + __expf(-x)); }
;   DEV void operator()(f32x4 (&acc)[2][2][4][2], int brow, int bcol, int wr, int wc, int fr, int fq) const {
;     ...
;             } else if (mode == 2) {
;               for (int j = 0; j < 4; ++j) v[j] = fsigmoid(v[j]);
;               tile_put4(rl, cl, pk4(v));
.LBB0_1054:
	s_andn2_b64 vcc, exec, s[0:1]
	s_cbranch_vccnz .LBB0_1056
	s_waitcnt vmcnt(0)
	v_mul_f32_e32 v128, 0xbfb8aa3b, v16
	v_mul_f32_e32 v129, 0xbfb8aa3b, v17
	v_exp_f32_e32 v128, v128
	v_exp_f32_e32 v129, v129
	s_nop 0
	v_pk_add_f32 v[128:129], v[128:129], 1.0 op_sel_hi:[1,0]
	s_nop 0
	s_nop 0
	v_rcp_f32_e32 v130, v129
	s_nop 0
	v_rcp_f32_e32 v131, v128
	v_mul_f32_e32 v128, 0xbfb8aa3b, v18
	v_mul_f32_e32 v129, 0xbfb8aa3b, v19
	v_exp_f32_e32 v128, v128
	v_exp_f32_e32 v129, v129
	s_nop 0
	v_pk_add_f32 v[128:129], v[128:129], 1.0 op_sel_hi:[1,0]
	s_nop 0
	s_nop 0
	v_rcp_f32_e32 v129, v129
	s_nop 0
	v_rcp_f32_e32 v136, v128
	v_cvt_pk_bf16_f32 v128, v131, v130
	v_lshlrev_b32_e32 v130, 4, v154
	v_cvt_pk_bf16_f32 v129, v136, v129
	v_add3_u32 v130, v159, v130, v133
	ds_write_b64 v130, v[128:129]

; DEV u32x2 pk4(f32x4 v) { u32x2 r = {pk_bf16(v[0], v[1]), pk_bf16(v[2], v[3])}; return r; }
; DEV float fsigmoid(float x) { return 1.f / (1.f + __expf(-x)); }
;   DEV void operator()(f32x4 (&acc)[2][2][4][2], int brow, int bcol, int wr, int wc, int fr, int fq) const {
;     ...
;             } else if (mode == 1) {
;               for (int j = 0; j < 4; ++j) v[j] = v[j] * fsigmoid(v[j]);
;               tile_put4(rl, cl, pk4(v));
.LBB0_1057:
	s_andn2_b64 vcc, exec, s[0:1]
	s_cbranch_vccnz .LBB0_1059
	s_waitcnt vmcnt(0)
	v_mul_f32_e32 v128, 0xbfb8aa3b, v16
	v_mul_f32_e32 v129, 0xbfb8aa3b, v17
	v_exp_f32_e32 v128, v128
	v_exp_f32_e32 v129, v129
	s_nop 0
	v_pk_add_f32 v[128:129], v[128:129], 1.0 op_sel_hi:[1,0]
	s_nop 0
	s_nop 0
	v_rcp_f32_e32 v129, v129
	s_nop 0
	v_rcp_f32_e32 v128, v128
	v_mul_f32_e32 v130, 0xbfb8aa3b, v18
	v_mul_f32_e32 v131, 0xbfb8aa3b, v19
	v_exp_f32_e32 v130, v130
	v_exp_f32_e32 v131, v131
	v_pk_mul_f32 v[128:129], v[16:17], v[128:129]
	v_pk_add_f32 v[130:131], v[130:131], 1.0 op_sel_hi:[1,0]
	s_nop 0
	v_cvt_pk_bf16_f32 v128, v128, v129
	v_rcp_f32_e32 v131, v131
	s_nop 0
	v_rcp_f32_e32 v130, v130
	s_nop 0
	v_pk_mul_f32 v[130:131], v[18:19], v[130:131]
	s_nop 0
	v_cvt_pk_bf16_f32 v129, v130, v131
	v_lshlrev_b32_e32 v130, 4, v154
	v_add3_u32 v130, v159, v130, v133
	ds_write_b64 v130, v[128:129]

; DEV u32x2 pk4(f32x4 v) { u32x2 r = {pk_bf16(v[0], v[1]), pk_bf16(v[2], v[3])}; return r; }
; DEV float fsigmoid(float x) { return 1.f / (1.f + __expf(-x)); }
;   DEV void operator()(f32x4 (&acc)[2][2][4][2], int brow, int bcol, int wr, int wc, int fr, int fq) const {
;     ...
;             } else if (mode == 2) {
;               for (int j = 0; j < 4; ++j) v[j] = fsigmoid(v[j]);
;               tile_put4(rl, cl, pk4(v));
.LBB0_1076:
	s_andn2_b64 vcc, exec, s[0:1]
	s_cbranch_vccnz .LBB0_1078
	s_waitcnt vmcnt(0)
	v_mul_f32_e32 v128, 0xbfb8aa3b, v12
	v_mul_f32_e32 v129, 0xbfb8aa3b, v13
	v_exp_f32_e32 v128, v128
	v_exp_f32_e32 v129, v129
	s_nop 0
	v_pk_add_f32 v[128:129], v[128:129], 1.0 op_sel_hi:[1,0]
	s_nop 0
	s_nop 0
	v_rcp_f32_e32 v130, v129
	s_nop 0
	v_rcp_f32_e32 v131, v128
	v_mul_f32_e32 v128, 0xbfb8aa3b, v14
	v_mul_f32_e32 v129, 0xbfb8aa3b, v15
	v_exp_f32_e32 v128, v128
	v_exp_f32_e32 v129, v129
	s_nop 0
	v_pk_add_f32 v[128:129], v[128:129], 1.0 op_sel_hi:[1,0]
	s_nop 0
	s_nop 0
	v_rcp_f32_e32 v129, v129
	s_nop 0
	v_rcp_f32_e32 v142, v128
	v_cvt_pk_bf16_f32 v128, v131, v130
	v_lshlrev_b32_e32 v130, 4, v155
	v_cvt_pk_bf16_f32 v129, v142, v129
	v_add3_u32 v130, v144, v130, v133
	ds_write_b64 v130, v[128:129]

; DEV u32x2 pk4(f32x4 v) { u32x2 r = {pk_bf16(v[0], v[1]), pk_bf16(v[2], v[3])}; return r; }
; DEV float fsigmoid(float x) { return 1.f / (1.f + __expf(-x)); }
;   DEV void operator()(f32x4 (&acc)[2][2][4][2], int brow, int bcol, int wr, int wc, int fr, int fq) const {
;     ...
;             } else if (mode == 1) {
;               for (int j = 0; j < 4; ++j) v[j] = v[j] * fsigmoid(v[j]);
;               tile_put4(rl, cl, pk4(v));
.LBB0_1079:
	s_andn2_b64 vcc, exec, s[0:1]
	s_cbranch_vccnz .LBB0_1081
	s_waitcnt vmcnt(0)
	v_mul_f32_e32 v128, 0xbfb8aa3b, v12
	v_mul_f32_e32 v129, 0xbfb8aa3b, v13
	v_exp_f32_e32 v128, v128
	v_exp_f32_e32 v129, v129
	s_nop 0
	v_pk_add_f32 v[128:129], v[128:129], 1.0 op_sel_hi:[1,0]
	s_nop 0
	s_nop 0
	v_rcp_f32_e32 v129, v129
	s_nop 0
	v_rcp_f32_e32 v128, v128
	v_mul_f32_e32 v130, 0xbfb8aa3b, v14
	v_mul_f32_e32 v131, 0xbfb8aa3b, v15
	v_exp_f32_e32 v130, v130
	v_exp_f32_e32 v131, v131
	v_pk_mul_f32 v[128:129], v[12:13], v[128:129]
	v_pk_add_f32 v[130:131], v[130:131], 1.0 op_sel_hi:[1,0]
	s_nop 0
	v_cvt_pk_bf16_f32 v128, v128, v129
	v_rcp_f32_e32 v131, v131
	s_nop 0
	v_rcp_f32_e32 v130, v130
	s_nop 0
	v_pk_mul_f32 v[130:131], v[14:15], v[130:131]
	s_nop 0
	v_cvt_pk_bf16_f32 v129, v130, v131
	v_lshlrev_b32_e32 v130, 4, v155
	v_add3_u32 v130, v144, v130, v133
	ds_write_b64 v130, v[128:129]

; DEV u32x2 pk4(f32x4 v) { u32x2 r = {pk_bf16(v[0], v[1]), pk_bf16(v[2], v[3])}; return r; }
; DEV float fsigmoid(float x) { return 1.f / (1.f + __expf(-x)); }
;   DEV void operator()(f32x4 (&acc)[2][2][4][2], int brow, int bcol, int wr, int wc, int fr, int fq) const {
;     ...
;             } else if (mode == 2) {
;               for (int j = 0; j < 4; ++j) v[j] = fsigmoid(v[j]);
;               tile_put4(rl, cl, pk4(v));
.LBB0_1090:
	s_andn2_b64 vcc, exec, s[0:1]
	s_cbranch_vccnz .LBB0_1092
	s_waitcnt vmcnt(0)
	v_mul_f32_e32 v128, 0xbfb8aa3b, v8
	v_mul_f32_e32 v129, 0xbfb8aa3b, v9
	v_exp_f32_e32 v128, v128
	v_exp_f32_e32 v129, v129
	s_nop 0
	v_pk_add_f32 v[128:129], v[128:129], 1.0 op_sel_hi:[1,0]
	s_nop 0
	s_nop 0
	v_rcp_f32_e32 v130, v129
	s_nop 0
	v_rcp_f32_e32 v131, v128
	v_mul_f32_e32 v128, 0xbfb8aa3b, v10
	v_mul_f32_e32 v129, 0xbfb8aa3b, v11
	v_exp_f32_e32 v128, v128
	v_exp_f32_e32 v129, v129
	s_nop 0
	v_pk_add_f32 v[128:129], v[128:129], 1.0 op_sel_hi:[1,0]
	s_nop 0
	s_nop 0
	v_rcp_f32_e32 v129, v129
	s_nop 0
	v_rcp_f32_e32 v142, v128
	v_cvt_pk_bf16_f32 v128, v131, v130
	v_lshlrev_b32_e32 v130, 4, v156
	v_cvt_pk_bf16_f32 v129, v142, v129
	v_add3_u32 v130, v144, v130, v133
	ds_write_b64 v130, v[128:129]

; DEV u32x2 pk4(f32x4 v) { u32x2 r = {pk_bf16(v[0], v[1]), pk_bf16(v[2], v[3])}; return r; }
; DEV float fsigmoid(float x) { return 1.f / (1.f + __expf(-x)); }
;   DEV void operator()(f32x4 (&acc)[2][2][4][2], int brow, int bcol, int wr, int wc, int fr, int fq) const {
;     ...
;             } else if (mode == 1) {
;               for (int j = 0; j < 4; ++j) v[j] = v[j] * fsigmoid(v[j]);
;               tile_put4(rl, cl, pk4(v));
.LBB0_1093:
	s_andn2_b64 vcc, exec, s[0:1]
	s_cbranch_vccnz .LBB0_1095
	s_waitcnt vmcnt(0)
	v_mul_f32_e32 v128, 0xbfb8aa3b, v8
	v_mul_f32_e32 v129, 0xbfb8aa3b, v9
	v_exp_f32_e32 v128, v128
	v_exp_f32_e32 v129, v129
	s_nop 0
	v_pk_add_f32 v[128:129], v[128:129], 1.0 op_sel_hi:[1,0]
	s_nop 0
	s_nop 0
	v_rcp_f32_e32 v129, v129
	s_nop 0
	v_rcp_f32_e32 v128, v128
	v_mul_f32_e32 v130, 0xbfb8aa3b, v10
	v_mul_f32_e32 v131, 0xbfb8aa3b, v11
	v_exp_f32_e32 v130, v130
	v_exp_f32_e32 v131, v131
	v_pk_mul_f32 v[128:129], v[8:9], v[128:129]
	v_pk_add_f32 v[130:131], v[130:131], 1.0 op_sel_hi:[1,0]
	s_nop 0
	v_cvt_pk_bf16_f32 v128, v128, v129
	v_rcp_f32_e32 v131, v131
	s_nop 0
	v_rcp_f32_e32 v130, v130
	s_nop 0
	v_pk_mul_f32 v[130:131], v[10:11], v[130:131]
	s_nop 0
	v_cvt_pk_bf16_f32 v129, v130, v131
	v_lshlrev_b32_e32 v130, 4, v156
	v_add3_u32 v130, v144, v130, v133
	ds_write_b64 v130, v[128:129]

; DEV u32x2 pk4(f32x4 v) { u32x2 r = {pk_bf16(v[0], v[1]), pk_bf16(v[2], v[3])}; return r; }
; DEV float fsigmoid(float x) { return 1.f / (1.f + __expf(-x)); }
;   DEV void operator()(f32x4 (&acc)[2][2][4][2], int brow, int bcol, int wr, int wc, int fr, int fq) const {
;     ...
;             } else if (mode == 2) {
;               for (int j = 0; j < 4; ++j) v[j] = fsigmoid(v[j]);
;               tile_put4(rl, cl, pk4(v));
.LBB0_1104:
	s_andn2_b64 vcc, exec, s[0:1]
	s_cbranch_vccnz .LBB0_1106
	s_waitcnt vmcnt(0)
	v_mul_f32_e32 v128, 0xbfb8aa3b, v4
	v_mul_f32_e32 v129, 0xbfb8aa3b, v5
	v_exp_f32_e32 v128, v128
	v_exp_f32_e32 v129, v129
	s_nop 0
	v_pk_add_f32 v[128:129], v[128:129], 1.0 op_sel_hi:[1,0]
	s_nop 0
	s_nop 0
	v_rcp_f32_e32 v130, v129
	s_nop 0
	v_rcp_f32_e32 v131, v128
	v_mul_f32_e32 v128, 0xbfb8aa3b, v6
	v_mul_f32_e32 v129, 0xbfb8aa3b, v7
	v_exp_f32_e32 v128, v128
	v_exp_f32_e32 v129, v129
	s_nop 0
	v_pk_add_f32 v[128:129], v[128:129], 1.0 op_sel_hi:[1,0]
	s_nop 0
	s_nop 0
	v_rcp_f32_e32 v129, v129
	s_nop 0
	v_rcp_f32_e32 v142, v128
	v_cvt_pk_bf16_f32 v128, v131, v130
	v_lshlrev_b32_e32 v130, 4, v157
	v_cvt_pk_bf16_f32 v129, v142, v129
	v_add3_u32 v130, v144, v130, v133
	ds_write_b64 v130, v[128:129]

; DEV u32x2 pk4(f32x4 v) { u32x2 r = {pk_bf16(v[0], v[1]), pk_bf16(v[2], v[3])}; return r; }
; DEV float fsigmoid(float x) { return 1.f / (1.f + __expf(-x)); }
;   DEV void operator()(f32x4 (&acc)[2][2][4][2], int brow, int bcol, int wr, int wc, int fr, int fq) const {
;     ...
;             } else if (mode == 1) {
;               for (int j = 0; j < 4; ++j) v[j] = v[j] * fsigmoid(v[j]);
;               tile_put4(rl, cl, pk4(v));
.LBB0_1107:
	s_andn2_b64 vcc, exec, s[0:1]
	s_cbranch_vccnz .LBB0_1109
	s_waitcnt vmcnt(0)
	v_mul_f32_e32 v128, 0xbfb8aa3b, v4
	v_mul_f32_e32 v129, 0xbfb8aa3b, v5
	v_exp_f32_e32 v128, v128
	v_exp_f32_e32 v129, v129
	s_nop 0
	v_pk_add_f32 v[128:129], v[128:129], 1.0 op_sel_hi:[1,0]
	s_nop 0
	s_nop 0
	v_rcp_f32_e32 v129, v129
	s_nop 0
	v_rcp_f32_e32 v128, v128
	v_mul_f32_e32 v130, 0xbfb8aa3b, v6
	v_mul_f32_e32 v131, 0xbfb8aa3b, v7
	v_exp_f32_e32 v130, v130
	v_exp_f32_e32 v131, v131
	v_pk_mul_f32 v[128:129], v[4:5], v[128:129]
	v_pk_add_f32 v[130:131], v[130:131], 1.0 op_sel_hi:[1,0]
	s_nop 0
	v_cvt_pk_bf16_f32 v128, v128, v129
	v_rcp_f32_e32 v131, v131
	s_nop 0
	v_rcp_f32_e32 v130, v130
	s_nop 0
	v_pk_mul_f32 v[130:131], v[6:7], v[130:131]
	s_nop 0
	v_cvt_pk_bf16_f32 v129, v130, v131
	v_lshlrev_b32_e32 v130, 4, v157
	v_add3_u32 v130, v144, v130, v133
	ds_write_b64 v130, v[128:129]

; DEV u32x2 pk4(f32x4 v) { u32x2 r = {pk_bf16(v[0], v[1]), pk_bf16(v[2], v[3])}; return r; }
; DEV float fsigmoid(float x) { return 1.f / (1.f + __expf(-x)); }
;   DEV void operator()(f32x4 (&acc)[2][2][4][2], int brow, int bcol, int wr, int wc, int fr, int fq) const {
;     ...
;             } else if (mode == 2) {
;               for (int j = 0; j < 4; ++j) v[j] = fsigmoid(v[j]);
;               tile_put4(rl, cl, pk4(v));
.LBB0_1118:
	s_andn2_b64 vcc, exec, s[0:1]
	s_cbranch_vccnz .LBB0_1120
	s_waitcnt vmcnt(0)
	v_mul_f32_e32 v128, 0xbfb8aa3b, v0
	v_mul_f32_e32 v129, 0xbfb8aa3b, v1
	v_exp_f32_e32 v128, v128
	v_exp_f32_e32 v129, v129
	s_nop 0
	v_pk_add_f32 v[128:129], v[128:129], 1.0 op_sel_hi:[1,0]
	s_nop 0
	s_nop 0
	v_rcp_f32_e32 v130, v129
	s_nop 0
	v_rcp_f32_e32 v131, v128
	v_mul_f32_e32 v128, 0xbfb8aa3b, v2
	v_mul_f32_e32 v129, 0xbfb8aa3b, v3
	v_exp_f32_e32 v128, v128
	v_exp_f32_e32 v129, v129
	s_nop 0
	v_pk_add_f32 v[128:129], v[128:129], 1.0 op_sel_hi:[1,0]
	s_nop 0
	s_nop 0
	v_rcp_f32_e32 v129, v129
	s_nop 0
	v_rcp_f32_e32 v136, v128
	v_cvt_pk_bf16_f32 v128, v131, v130
	v_lshlrev_b32_e32 v130, 4, v158
	v_cvt_pk_bf16_f32 v129, v136, v129
	v_add3_u32 v130, v144, v130, v133
	ds_write_b64 v130, v[128:129]

; DEV u32x2 pk4(f32x4 v) { u32x2 r = {pk_bf16(v[0], v[1]), pk_bf16(v[2], v[3])}; return r; }
; DEV float fsigmoid(float x) { return 1.f / (1.f + __expf(-x)); }
;   DEV void operator()(f32x4 (&acc)[2][2][4][2], int brow, int bcol, int wr, int wc, int fr, int fq) const {
;     ...
;             } else if (mode == 1) {
;               for (int j = 0; j < 4; ++j) v[j] = v[j] * fsigmoid(v[j]);
;               tile_put4(rl, cl, pk4(v));
.LBB0_1121:
	s_andn2_b64 vcc, exec, s[0:1]
	s_cbranch_vccnz .LBB0_1123
	s_waitcnt vmcnt(0)
	v_mul_f32_e32 v128, 0xbfb8aa3b, v0
	v_mul_f32_e32 v129, 0xbfb8aa3b, v1
	v_exp_f32_e32 v128, v128
	v_exp_f32_e32 v129, v129
	s_nop 0
	v_pk_add_f32 v[128:129], v[128:129], 1.0 op_sel_hi:[1,0]
	s_nop 0
	s_nop 0
	v_rcp_f32_e32 v129, v129
	s_nop 0
	v_rcp_f32_e32 v128, v128
	v_mul_f32_e32 v130, 0xbfb8aa3b, v2
	v_mul_f32_e32 v131, 0xbfb8aa3b, v3
	v_exp_f32_e32 v130, v130
	v_exp_f32_e32 v131, v131
	v_pk_mul_f32 v[128:129], v[0:1], v[128:129]
	v_pk_add_f32 v[130:131], v[130:131], 1.0 op_sel_hi:[1,0]
	s_nop 0
	v_cvt_pk_bf16_f32 v128, v128, v129
	v_rcp_f32_e32 v131, v131
	s_nop 0
	v_rcp_f32_e32 v130, v130
	s_nop 0
	v_pk_mul_f32 v[130:131], v[2:3], v[130:131]
	s_nop 0
	v_cvt_pk_bf16_f32 v129, v130, v131
	v_lshlrev_b32_e32 v130, 4, v158
	v_add3_u32 v130, v144, v130, v133
	ds_write_b64 v130, v[128:129]

; DEV u32x2 pk4(f32x4 v) { u32x2 r = {pk_bf16(v[0], v[1]), pk_bf16(v[2], v[3])}; return r; }
; DEV float fsigmoid(float x) { return 1.f / (1.f + __expf(-x)); }
;   DEV void operator()(f32x4 (&acc)[2][2][4][2], int brow, int bcol, int wr, int wc, int fr, int fq) const {
;     ...
;             } else if (mode == 2) {
;               for (int j = 0; j < 4; ++j) v[j] = fsigmoid(v[j]);
;               tile_put4(rl, cl, pk4(v));
.LBB0_1588:
	s_andn2_b64 vcc, exec, s[20:21]
	s_cbranch_vccnz .LBB0_1590
	s_waitcnt vmcnt(0)
	v_mul_f32_e32 v128, 0xbfb8aa3b, v124
	v_mul_f32_e32 v129, 0xbfb8aa3b, v125
	v_exp_f32_e32 v128, v128
	v_exp_f32_e32 v129, v129
	s_nop 0
	v_pk_add_f32 v[128:129], v[128:129], 1.0 op_sel_hi:[1,0]
	s_nop 0
	s_nop 0
	v_rcp_f32_e32 v130, v129
	s_nop 0
	v_rcp_f32_e32 v131, v128
	v_mul_f32_e32 v128, 0xbfb8aa3b, v126
	v_mul_f32_e32 v129, 0xbfb8aa3b, v127
	v_exp_f32_e32 v128, v128
	v_exp_f32_e32 v129, v129
	s_nop 0
	v_pk_add_f32 v[128:129], v[128:129], 1.0 op_sel_hi:[1,0]
	s_nop 0
	s_nop 0
	v_rcp_f32_e32 v129, v129
	s_nop 0
	v_rcp_f32_e32 v133, v128
	v_cvt_pk_bf16_f32 v128, v131, v130
	v_lshrrev_b32_e32 v130, 3, v203
	v_xor_b32_e32 v130, v130, v201
	v_lshlrev_b32_e32 v131, 3, v137
	v_lshlrev_b32_e32 v130, 4, v130
	v_and_b32_e32 v131, 8, v131
	v_cvt_pk_bf16_f32 v129, v133, v129
	v_add3_u32 v130, v136, v130, v131
	ds_write_b64 v130, v[128:129]

; DEV u32x2 pk4(f32x4 v) { u32x2 r = {pk_bf16(v[0], v[1]), pk_bf16(v[2], v[3])}; return r; }
; DEV float fsigmoid(float x) { return 1.f / (1.f + __expf(-x)); }
;   DEV void operator()(f32x4 (&acc)[2][2][4][2], int brow, int bcol, int wr, int wc, int fr, int fq) const {
;     ...
;             } else if (mode == 1) {
;               for (int j = 0; j < 4; ++j) v[j] = v[j] * fsigmoid(v[j]);
;               tile_put4(rl, cl, pk4(v));
.LBB0_1591:
	s_andn2_b64 vcc, exec, s[20:21]
	s_cbranch_vccnz .LBB0_1593
	s_waitcnt vmcnt(0)
	v_mul_f32_e32 v128, 0xbfb8aa3b, v124
	v_mul_f32_e32 v129, 0xbfb8aa3b, v125
	v_exp_f32_e32 v128, v128
	v_exp_f32_e32 v129, v129
	s_nop 0
	v_pk_add_f32 v[128:129], v[128:129], 1.0 op_sel_hi:[1,0]
	s_nop 0
	s_nop 0
	v_rcp_f32_e32 v129, v129
	s_nop 0
	v_rcp_f32_e32 v128, v128
	v_mul_f32_e32 v130, 0xbfb8aa3b, v126
	v_mul_f32_e32 v131, 0xbfb8aa3b, v127
	v_exp_f32_e32 v130, v130
	v_exp_f32_e32 v131, v131
	v_pk_mul_f32 v[128:129], v[124:125], v[128:129]
	v_pk_add_f32 v[130:131], v[130:131], 1.0 op_sel_hi:[1,0]
	s_nop 0
	v_cvt_pk_bf16_f32 v128, v128, v129
	v_rcp_f32_e32 v131, v131
	s_nop 0
	v_rcp_f32_e32 v130, v130
	s_nop 0
	v_pk_mul_f32 v[130:131], v[126:127], v[130:131]
	s_nop 0
	v_cvt_pk_bf16_f32 v129, v130, v131
	v_lshrrev_b32_e32 v130, 3, v203
	v_xor_b32_e32 v130, v130, v201
	v_lshlrev_b32_e32 v131, 3, v137
	v_lshlrev_b32_e32 v130, 4, v130
	v_and_b32_e32 v131, 8, v131
	v_add3_u32 v130, v136, v130, v131
	ds_write_b64 v130, v[128:129]

; DEV u32x2 pk4(f32x4 v) { u32x2 r = {pk_bf16(v[0], v[1]), pk_bf16(v[2], v[3])}; return r; }
; DEV float fsigmoid(float x) { return 1.f / (1.f + __expf(-x)); }
;   DEV void operator()(f32x4 (&acc)[2][2][4][2], int brow, int bcol, int wr, int wc, int fr, int fq) const {
;     ...
;             } else if (mode == 2) {
;               for (int j = 0; j < 4; ++j) v[j] = fsigmoid(v[j]);
;               tile_put4(rl, cl, pk4(v));
.LBB0_1604:
	s_andn2_b64 vcc, exec, s[20:21]
	s_cbranch_vccnz .LBB0_1606
	s_waitcnt vmcnt(0)
	v_mul_f32_e32 v128, 0xbfb8aa3b, v120
	v_mul_f32_e32 v129, 0xbfb8aa3b, v121
	v_exp_f32_e32 v128, v128
	v_exp_f32_e32 v129, v129
	s_nop 0
	v_pk_add_f32 v[128:129], v[128:129], 1.0 op_sel_hi:[1,0]
	s_nop 0
	s_nop 0
	v_rcp_f32_e32 v130, v129
	s_nop 0
	v_rcp_f32_e32 v131, v128
	v_mul_f32_e32 v128, 0xbfb8aa3b, v122
	v_mul_f32_e32 v129, 0xbfb8aa3b, v123
	v_exp_f32_e32 v128, v128
	v_exp_f32_e32 v129, v129
	s_nop 0
	v_pk_add_f32 v[128:129], v[128:129], 1.0 op_sel_hi:[1,0]
	s_nop 0
	s_nop 0
	v_rcp_f32_e32 v129, v129
	s_nop 0
	v_rcp_f32_e32 v137, v128
	v_cvt_pk_bf16_f32 v128, v131, v130
	v_lshrrev_b32_e32 v130, 3, v146
	v_xor_b32_e32 v130, v130, v201
	v_lshlrev_b32_e32 v130, 4, v130
	v_cvt_pk_bf16_f32 v129, v137, v129
	v_add3_u32 v130, v136, v130, v133
	ds_write_b64 v130, v[128:129]

; DEV u32x2 pk4(f32x4 v) { u32x2 r = {pk_bf16(v[0], v[1]), pk_bf16(v[2], v[3])}; return r; }
; DEV float fsigmoid(float x) { return 1.f / (1.f + __expf(-x)); }
;   DEV void operator()(f32x4 (&acc)[2][2][4][2], int brow, int bcol, int wr, int wc, int fr, int fq) const {
;     ...
;             } else if (mode == 1) {
;               for (int j = 0; j < 4; ++j) v[j] = v[j] * fsigmoid(v[j]);
;               tile_put4(rl, cl, pk4(v));
.LBB0_1607:
	s_andn2_b64 vcc, exec, s[20:21]
	s_cbranch_vccnz .LBB0_1609
	s_waitcnt vmcnt(0)
	v_mul_f32_e32 v128, 0xbfb8aa3b, v120
	v_mul_f32_e32 v129, 0xbfb8aa3b, v121
	v_exp_f32_e32 v128, v128
	v_exp_f32_e32 v129, v129
	s_nop 0
	v_pk_add_f32 v[128:129], v[128:129], 1.0 op_sel_hi:[1,0]
	s_nop 0
	s_nop 0
	v_rcp_f32_e32 v129, v129
	s_nop 0
	v_rcp_f32_e32 v128, v128
	v_mul_f32_e32 v130, 0xbfb8aa3b, v122
	v_mul_f32_e32 v131, 0xbfb8aa3b, v123
	v_exp_f32_e32 v130, v130
	v_exp_f32_e32 v131, v131
	v_pk_mul_f32 v[128:129], v[120:121], v[128:129]
	v_pk_add_f32 v[130:131], v[130:131], 1.0 op_sel_hi:[1,0]
	s_nop 0
	v_cvt_pk_bf16_f32 v128, v128, v129
	v_rcp_f32_e32 v131, v131
	s_nop 0
	v_rcp_f32_e32 v130, v130
	s_nop 0
	v_pk_mul_f32 v[130:131], v[122:123], v[130:131]
	s_nop 0
	v_cvt_pk_bf16_f32 v129, v130, v131
	v_lshrrev_b32_e32 v130, 3, v146
	v_xor_b32_e32 v130, v130, v201
	v_lshlrev_b32_e32 v130, 4, v130
	v_add3_u32 v130, v136, v130, v133
	ds_write_b64 v130, v[128:129]

; DEV u32x2 pk4(f32x4 v) { u32x2 r = {pk_bf16(v[0], v[1]), pk_bf16(v[2], v[3])}; return r; }
; DEV float fsigmoid(float x) { return 1.f / (1.f + __expf(-x)); }
;   DEV void operator()(f32x4 (&acc)[2][2][4][2], int brow, int bcol, int wr, int wc, int fr, int fq) const {
;     ...
;             } else if (mode == 2) {
;               for (int j = 0; j < 4; ++j) v[j] = fsigmoid(v[j]);
;               tile_put4(rl, cl, pk4(v));
.LBB0_1620:
	s_andn2_b64 vcc, exec, s[20:21]
	s_cbranch_vccnz .LBB0_1622
	s_waitcnt vmcnt(0)
	v_mul_f32_e32 v128, 0xbfb8aa3b, v116
	v_mul_f32_e32 v129, 0xbfb8aa3b, v117
	v_exp_f32_e32 v128, v128
	v_exp_f32_e32 v129, v129
	s_nop 0
	v_pk_add_f32 v[128:129], v[128:129], 1.0 op_sel_hi:[1,0]
	s_nop 0
	s_nop 0
	v_rcp_f32_e32 v130, v129
	s_nop 0
	v_rcp_f32_e32 v131, v128
	v_mul_f32_e32 v128, 0xbfb8aa3b, v118
	v_mul_f32_e32 v129, 0xbfb8aa3b, v119
	v_exp_f32_e32 v128, v128
	v_exp_f32_e32 v129, v129
	s_nop 0
	v_pk_add_f32 v[128:129], v[128:129], 1.0 op_sel_hi:[1,0]
	s_nop 0
	s_nop 0
	v_rcp_f32_e32 v129, v129
	s_nop 0
	v_rcp_f32_e32 v137, v128
	v_cvt_pk_bf16_f32 v128, v131, v130
	v_lshrrev_b32_e32 v130, 3, v148
	v_xor_b32_e32 v130, v130, v201
	v_lshlrev_b32_e32 v130, 4, v130
	v_cvt_pk_bf16_f32 v129, v137, v129
	v_add3_u32 v130, v136, v130, v133
	ds_write_b64 v130, v[128:129]

; DEV u32x2 pk4(f32x4 v) { u32x2 r = {pk_bf16(v[0], v[1]), pk_bf16(v[2], v[3])}; return r; }
; DEV float fsigmoid(float x) { return 1.f / (1.f + __expf(-x)); }
;   DEV void operator()(f32x4 (&acc)[2][2][4][2], int brow, int bcol, int wr, int wc, int fr, int fq) const {
;     ...
;             } else if (mode == 1) {
;               for (int j = 0; j < 4; ++j) v[j] = v[j] * fsigmoid(v[j]);
;               tile_put4(rl, cl, pk4(v));
.LBB0_1623:
	s_andn2_b64 vcc, exec, s[20:21]
	s_cbranch_vccnz .LBB0_1625
	s_waitcnt vmcnt(0)
	v_mul_f32_e32 v128, 0xbfb8aa3b, v116
	v_mul_f32_e32 v129, 0xbfb8aa3b, v117
	v_exp_f32_e32 v128, v128
	v_exp_f32_e32 v129, v129
	s_nop 0
	v_pk_add_f32 v[128:129], v[128:129], 1.0 op_sel_hi:[1,0]
	s_nop 0
	s_nop 0
	v_rcp_f32_e32 v129, v129
	s_nop 0
	v_rcp_f32_e32 v128, v128
	v_mul_f32_e32 v130, 0xbfb8aa3b, v118
	v_mul_f32_e32 v131, 0xbfb8aa3b, v119
	v_exp_f32_e32 v130, v130
	v_exp_f32_e32 v131, v131
	v_pk_mul_f32 v[128:129], v[116:117], v[128:129]
	v_pk_add_f32 v[130:131], v[130:131], 1.0 op_sel_hi:[1,0]
	s_nop 0
	v_cvt_pk_bf16_f32 v128, v128, v129
	v_rcp_f32_e32 v131, v131
	s_nop 0
	v_rcp_f32_e32 v130, v130
	s_nop 0
	v_pk_mul_f32 v[130:131], v[118:119], v[130:131]
	s_nop 0
	v_cvt_pk_bf16_f32 v129, v130, v131
	v_lshrrev_b32_e32 v130, 3, v148
	v_xor_b32_e32 v130, v130, v201
	v_lshlrev_b32_e32 v130, 4, v130
	v_add3_u32 v130, v136, v130, v133
	ds_write_b64 v130, v[128:129]

; DEV u32x2 pk4(f32x4 v) { u32x2 r = {pk_bf16(v[0], v[1]), pk_bf16(v[2], v[3])}; return r; }
; DEV float fsigmoid(float x) { return 1.f / (1.f + __expf(-x)); }
;   DEV void operator()(f32x4 (&acc)[2][2][4][2], int brow, int bcol, int wr, int wc, int fr, int fq) const {
;     ...
;             } else if (mode == 2) {
;               for (int j = 0; j < 4; ++j) v[j] = fsigmoid(v[j]);
;               tile_put4(rl, cl, pk4(v));
.LBB0_1636:
	s_andn2_b64 vcc, exec, s[20:21]
	s_cbranch_vccnz .LBB0_1638
	s_waitcnt vmcnt(0)
	v_mul_f32_e32 v128, 0xbfb8aa3b, v112
	v_mul_f32_e32 v129, 0xbfb8aa3b, v113
	v_exp_f32_e32 v128, v128
	v_exp_f32_e32 v129, v129
	s_nop 0
	v_pk_add_f32 v[128:129], v[128:129], 1.0 op_sel_hi:[1,0]
	s_nop 0
	s_nop 0
	v_rcp_f32_e32 v130, v129
	s_nop 0
	v_rcp_f32_e32 v131, v128
	v_mul_f32_e32 v128, 0xbfb8aa3b, v114
	v_mul_f32_e32 v129, 0xbfb8aa3b, v115
	v_exp_f32_e32 v128, v128
	v_exp_f32_e32 v129, v129
	s_nop 0
	v_pk_add_f32 v[128:129], v[128:129], 1.0 op_sel_hi:[1,0]
	s_nop 0
	s_nop 0
	v_rcp_f32_e32 v129, v129
	s_nop 0
	v_rcp_f32_e32 v137, v128
	v_cvt_pk_bf16_f32 v128, v131, v130
	v_lshrrev_b32_e32 v130, 3, v149
	v_xor_b32_e32 v130, v130, v201
	v_lshlrev_b32_e32 v130, 4, v130
	v_cvt_pk_bf16_f32 v129, v137, v129
	v_add3_u32 v130, v136, v130, v133
	ds_write_b64 v130, v[128:129]

; DEV u32x2 pk4(f32x4 v) { u32x2 r = {pk_bf16(v[0], v[1]), pk_bf16(v[2], v[3])}; return r; }
; DEV float fsigmoid(float x) { return 1.f / (1.f + __expf(-x)); }
;   DEV void operator()(f32x4 (&acc)[2][2][4][2], int brow, int bcol, int wr, int wc, int fr, int fq) const {
;     ...
;             } else if (mode == 1) {
;               for (int j = 0; j < 4; ++j) v[j] = v[j] * fsigmoid(v[j]);
;               tile_put4(rl, cl, pk4(v));
.LBB0_1639:
	s_andn2_b64 vcc, exec, s[20:21]
	s_cbranch_vccnz .LBB0_1641
	s_waitcnt vmcnt(0)
	v_mul_f32_e32 v128, 0xbfb8aa3b, v112
	v_mul_f32_e32 v129, 0xbfb8aa3b, v113
	v_exp_f32_e32 v128, v128
	v_exp_f32_e32 v129, v129
	s_nop 0
	v_pk_add_f32 v[128:129], v[128:129], 1.0 op_sel_hi:[1,0]
	s_nop 0
	s_nop 0
	v_rcp_f32_e32 v129, v129
	s_nop 0
	v_rcp_f32_e32 v128, v128
	v_mul_f32_e32 v130, 0xbfb8aa3b, v114
	v_mul_f32_e32 v131, 0xbfb8aa3b, v115
	v_exp_f32_e32 v130, v130
	v_exp_f32_e32 v131, v131
	v_pk_mul_f32 v[128:129], v[112:113], v[128:129]
	v_pk_add_f32 v[130:131], v[130:131], 1.0 op_sel_hi:[1,0]
	s_nop 0
	v_cvt_pk_bf16_f32 v128, v128, v129
	v_rcp_f32_e32 v131, v131
	s_nop 0
	v_rcp_f32_e32 v130, v130
	s_nop 0
	v_pk_mul_f32 v[130:131], v[114:115], v[130:131]
	s_nop 0
	v_cvt_pk_bf16_f32 v129, v130, v131
	v_lshrrev_b32_e32 v130, 3, v149
	v_xor_b32_e32 v130, v130, v201
	v_lshlrev_b32_e32 v130, 4, v130
	v_add3_u32 v130, v136, v130, v133
	ds_write_b64 v130, v[128:129]

; DEV u32x2 pk4(f32x4 v) { u32x2 r = {pk_bf16(v[0], v[1]), pk_bf16(v[2], v[3])}; return r; }
; DEV float fsigmoid(float x) { return 1.f / (1.f + __expf(-x)); }
;   DEV void operator()(f32x4 (&acc)[2][2][4][2], int brow, int bcol, int wr, int wc, int fr, int fq) const {
;     ...
;             } else if (mode == 2) {
;               for (int j = 0; j < 4; ++j) v[j] = fsigmoid(v[j]);
;               tile_put4(rl, cl, pk4(v));
.LBB0_1652:
	s_andn2_b64 vcc, exec, s[20:21]
	s_cbranch_vccnz .LBB0_1654
	s_waitcnt vmcnt(0)
	v_mul_f32_e32 v128, 0xbfb8aa3b, v108
	v_mul_f32_e32 v129, 0xbfb8aa3b, v109
	v_exp_f32_e32 v128, v128
	v_exp_f32_e32 v129, v129
	s_nop 0
	v_pk_add_f32 v[128:129], v[128:129], 1.0 op_sel_hi:[1,0]
	s_nop 0
	s_nop 0
	v_rcp_f32_e32 v130, v129
	s_nop 0
	v_rcp_f32_e32 v131, v128
	v_mul_f32_e32 v128, 0xbfb8aa3b, v110
	v_mul_f32_e32 v129, 0xbfb8aa3b, v111
	v_exp_f32_e32 v128, v128
	v_exp_f32_e32 v129, v129
	s_nop 0
	v_pk_add_f32 v[128:129], v[128:129], 1.0 op_sel_hi:[1,0]
	s_nop 0
	s_nop 0
	v_rcp_f32_e32 v129, v129
	s_nop 0
	v_rcp_f32_e32 v160, v128
	v_cvt_pk_bf16_f32 v128, v131, v130
	v_xor_b32_e32 v130, v155, v150
	v_lshlrev_b32_e32 v130, 4, v130
	v_cvt_pk_bf16_f32 v129, v160, v129
	v_add3_u32 v130, v159, v130, v133
	ds_write_b64 v130, v[128:129]

; DEV u32x2 pk4(f32x4 v) { u32x2 r = {pk_bf16(v[0], v[1]), pk_bf16(v[2], v[3])}; return r; }
; DEV float fsigmoid(float x) { return 1.f / (1.f + __expf(-x)); }
;   DEV void operator()(f32x4 (&acc)[2][2][4][2], int brow, int bcol, int wr, int wc, int fr, int fq) const {
;     ...
;             } else if (mode == 1) {
;               for (int j = 0; j < 4; ++j) v[j] = v[j] * fsigmoid(v[j]);
;               tile_put4(rl, cl, pk4(v));
.LBB0_1655:
	s_andn2_b64 vcc, exec, s[20:21]
	s_cbranch_vccnz .LBB0_1657
	s_waitcnt vmcnt(0)
	v_mul_f32_e32 v128, 0xbfb8aa3b, v108
	v_mul_f32_e32 v129, 0xbfb8aa3b, v109
	v_exp_f32_e32 v128, v128
	v_exp_f32_e32 v129, v129
	s_nop 0
	v_pk_add_f32 v[128:129], v[128:129], 1.0 op_sel_hi:[1,0]
	s_nop 0
	s_nop 0
	v_rcp_f32_e32 v129, v129
	s_nop 0
	v_rcp_f32_e32 v128, v128
	v_mul_f32_e32 v130, 0xbfb8aa3b, v110
	v_mul_f32_e32 v131, 0xbfb8aa3b, v111
	v_exp_f32_e32 v130, v130
	v_exp_f32_e32 v131, v131
	v_pk_mul_f32 v[128:129], v[108:109], v[128:129]
	v_pk_add_f32 v[130:131], v[130:131], 1.0 op_sel_hi:[1,0]
	s_nop 0
	v_cvt_pk_bf16_f32 v128, v128, v129
	v_rcp_f32_e32 v131, v131
	s_nop 0
	v_rcp_f32_e32 v130, v130
	s_nop 0
	v_pk_mul_f32 v[130:131], v[110:111], v[130:131]
	s_nop 0
	v_cvt_pk_bf16_f32 v129, v130, v131
	v_xor_b32_e32 v130, v155, v150
	v_lshlrev_b32_e32 v130, 4, v130
	v_add3_u32 v130, v159, v130, v133
	ds_write_b64 v130, v[128:129]

; DEV u32x2 pk4(f32x4 v) { u32x2 r = {pk_bf16(v[0], v[1]), pk_bf16(v[2], v[3])}; return r; }
; DEV float fsigmoid(float x) { return 1.f / (1.f + __expf(-x)); }
;   DEV void operator()(f32x4 (&acc)[2][2][4][2], int brow, int bcol, int wr, int wc, int fr, int fq) const {
;     ...
;             } else if (mode == 2) {
;               for (int j = 0; j < 4; ++j) v[j] = fsigmoid(v[j]);
;               tile_put4(rl, cl, pk4(v));
.LBB0_1666:
	s_andn2_b64 vcc, exec, s[20:21]
	s_cbranch_vccnz .LBB0_1668
	s_waitcnt vmcnt(0)
	v_mul_f32_e32 v128, 0xbfb8aa3b, v104
	v_mul_f32_e32 v129, 0xbfb8aa3b, v105
	v_exp_f32_e32 v128, v128
	v_exp_f32_e32 v129, v129
	s_nop 0
	v_pk_add_f32 v[128:129], v[128:129], 1.0 op_sel_hi:[1,0]
	s_nop 0
	s_nop 0
	v_rcp_f32_e32 v130, v129
	s_nop 0
	v_rcp_f32_e32 v131, v128
	v_mul_f32_e32 v128, 0xbfb8aa3b, v106
	v_mul_f32_e32 v129, 0xbfb8aa3b, v107
	v_exp_f32_e32 v128, v128
	v_exp_f32_e32 v129, v129
	s_nop 0
	v_pk_add_f32 v[128:129], v[128:129], 1.0 op_sel_hi:[1,0]
	s_nop 0
	s_nop 0
	v_rcp_f32_e32 v129, v129
	s_nop 0
	v_rcp_f32_e32 v160, v128
	v_cvt_pk_bf16_f32 v128, v131, v130
	v_xor_b32_e32 v130, v156, v150
	v_lshlrev_b32_e32 v130, 4, v130
	v_cvt_pk_bf16_f32 v129, v160, v129
	v_add3_u32 v130, v159, v130, v133
	ds_write_b64 v130, v[128:129]

; DEV u32x2 pk4(f32x4 v) { u32x2 r = {pk_bf16(v[0], v[1]), pk_bf16(v[2], v[3])}; return r; }
; DEV float fsigmoid(float x) { return 1.f / (1.f + __expf(-x)); }
;   DEV void operator()(f32x4 (&acc)[2][2][4][2], int brow, int bcol, int wr, int wc, int fr, int fq) const {
;     ...
;             } else if (mode == 1) {
;               for (int j = 0; j < 4; ++j) v[j] = v[j] * fsigmoid(v[j]);
;               tile_put4(rl, cl, pk4(v));
.LBB0_1669:
	s_andn2_b64 vcc, exec, s[20:21]
	s_cbranch_vccnz .LBB0_1671
	s_waitcnt vmcnt(0)
	v_mul_f32_e32 v128, 0xbfb8aa3b, v104
	v_mul_f32_e32 v129, 0xbfb8aa3b, v105
	v_exp_f32_e32 v128, v128
	v_exp_f32_e32 v129, v129
	s_nop 0
	v_pk_add_f32 v[128:129], v[128:129], 1.0 op_sel_hi:[1,0]
	s_nop 0
	s_nop 0
	v_rcp_f32_e32 v129, v129
	s_nop 0
	v_rcp_f32_e32 v128, v128
	v_mul_f32_e32 v130, 0xbfb8aa3b, v106
	v_mul_f32_e32 v131, 0xbfb8aa3b, v107
	v_exp_f32_e32 v130, v130
	v_exp_f32_e32 v131, v131
	v_pk_mul_f32 v[128:129], v[104:105], v[128:129]
	v_pk_add_f32 v[130:131], v[130:131], 1.0 op_sel_hi:[1,0]
	s_nop 0
	v_cvt_pk_bf16_f32 v128, v128, v129
	v_rcp_f32_e32 v131, v131
	s_nop 0
	v_rcp_f32_e32 v130, v130
	s_nop 0
	v_pk_mul_f32 v[130:131], v[106:107], v[130:131]
	s_nop 0
	v_cvt_pk_bf16_f32 v129, v130, v131
	v_xor_b32_e32 v130, v156, v150
	v_lshlrev_b32_e32 v130, 4, v130
	v_add3_u32 v130, v159, v130, v133
	ds_write_b64 v130, v[128:129]

; DEV u32x2 pk4(f32x4 v) { u32x2 r = {pk_bf16(v[0], v[1]), pk_bf16(v[2], v[3])}; return r; }
; DEV float fsigmoid(float x) { return 1.f / (1.f + __expf(-x)); }
;   DEV void operator()(f32x4 (&acc)[2][2][4][2], int brow, int bcol, int wr, int wc, int fr, int fq) const {
;     ...
;             } else if (mode == 2) {
;               for (int j = 0; j < 4; ++j) v[j] = fsigmoid(v[j]);
;               tile_put4(rl, cl, pk4(v));
.LBB0_1680:
	s_andn2_b64 vcc, exec, s[20:21]
	s_cbranch_vccnz .LBB0_1682
	s_waitcnt vmcnt(0)
	v_mul_f32_e32 v128, 0xbfb8aa3b, v100
	v_mul_f32_e32 v129, 0xbfb8aa3b, v101
	v_exp_f32_e32 v128, v128
	v_exp_f32_e32 v129, v129
	s_nop 0
	v_pk_add_f32 v[128:129], v[128:129], 1.0 op_sel_hi:[1,0]
	s_nop 0
	s_nop 0
	v_rcp_f32_e32 v130, v129
	s_nop 0
	v_rcp_f32_e32 v131, v128
	v_mul_f32_e32 v128, 0xbfb8aa3b, v102
	v_mul_f32_e32 v129, 0xbfb8aa3b, v103
	v_exp_f32_e32 v128, v128
	v_exp_f32_e32 v129, v129
	s_nop 0
	v_pk_add_f32 v[128:129], v[128:129], 1.0 op_sel_hi:[1,0]
	s_nop 0
	s_nop 0
	v_rcp_f32_e32 v129, v129
	s_nop 0
	v_rcp_f32_e32 v160, v128
	v_cvt_pk_bf16_f32 v128, v131, v130
	v_xor_b32_e32 v130, v157, v150
	v_lshlrev_b32_e32 v130, 4, v130
	v_cvt_pk_bf16_f32 v129, v160, v129
	v_add3_u32 v130, v159, v130, v133
	ds_write_b64 v130, v[128:129]

; DEV u32x2 pk4(f32x4 v) { u32x2 r = {pk_bf16(v[0], v[1]), pk_bf16(v[2], v[3])}; return r; }
; DEV float fsigmoid(float x) { return 1.f / (1.f + __expf(-x)); }
;   DEV void operator()(f32x4 (&acc)[2][2][4][2], int brow, int bcol, int wr, int wc, int fr, int fq) const {
;     ...
;             } else if (mode == 1) {
;               for (int j = 0; j < 4; ++j) v[j] = v[j] * fsigmoid(v[j]);
;               tile_put4(rl, cl, pk4(v));
.LBB0_1683:
	s_andn2_b64 vcc, exec, s[20:21]
	s_cbranch_vccnz .LBB0_1685
	s_waitcnt vmcnt(0)
	v_mul_f32_e32 v128, 0xbfb8aa3b, v100
	v_mul_f32_e32 v129, 0xbfb8aa3b, v101
	v_exp_f32_e32 v128, v128
	v_exp_f32_e32 v129, v129
	s_nop 0
	v_pk_add_f32 v[128:129], v[128:129], 1.0 op_sel_hi:[1,0]
	s_nop 0
	s_nop 0
	v_rcp_f32_e32 v129, v129
	s_nop 0
	v_rcp_f32_e32 v128, v128
	v_mul_f32_e32 v130, 0xbfb8aa3b, v102
	v_mul_f32_e32 v131, 0xbfb8aa3b, v103
	v_exp_f32_e32 v130, v130
	v_exp_f32_e32 v131, v131
	v_pk_mul_f32 v[128:129], v[100:101], v[128:129]
	v_pk_add_f32 v[130:131], v[130:131], 1.0 op_sel_hi:[1,0]
	s_nop 0
	v_cvt_pk_bf16_f32 v128, v128, v129
	v_rcp_f32_e32 v131, v131
	s_nop 0
	v_rcp_f32_e32 v130, v130
	s_nop 0
	v_pk_mul_f32 v[130:131], v[102:103], v[130:131]
	s_nop 0
	v_cvt_pk_bf16_f32 v129, v130, v131
	v_xor_b32_e32 v130, v157, v150
	v_lshlrev_b32_e32 v130, 4, v130
	v_add3_u32 v130, v159, v130, v133
	ds_write_b64 v130, v[128:129]

; DEV u32x2 pk4(f32x4 v) { u32x2 r = {pk_bf16(v[0], v[1]), pk_bf16(v[2], v[3])}; return r; }
; DEV float fsigmoid(float x) { return 1.f / (1.f + __expf(-x)); }
;   DEV void operator()(f32x4 (&acc)[2][2][4][2], int brow, int bcol, int wr, int wc, int fr, int fq) const {
;     ...
;             } else if (mode == 2) {
;               for (int j = 0; j < 4; ++j) v[j] = fsigmoid(v[j]);
;               tile_put4(rl, cl, pk4(v));
.LBB0_1694:
	s_andn2_b64 vcc, exec, s[20:21]
	s_cbranch_vccnz .LBB0_1696
	s_waitcnt vmcnt(0)
	v_mul_f32_e32 v128, 0xbfb8aa3b, v96
	v_mul_f32_e32 v129, 0xbfb8aa3b, v97
	v_exp_f32_e32 v128, v128
	v_exp_f32_e32 v129, v129
	s_nop 0
	v_pk_add_f32 v[128:129], v[128:129], 1.0 op_sel_hi:[1,0]
	s_nop 0
	s_nop 0
	v_rcp_f32_e32 v130, v129
	s_nop 0
	v_rcp_f32_e32 v131, v128
	v_mul_f32_e32 v128, 0xbfb8aa3b, v98
	v_mul_f32_e32 v129, 0xbfb8aa3b, v99
	v_exp_f32_e32 v128, v128
	v_exp_f32_e32 v129, v129
	s_nop 0
	v_pk_add_f32 v[128:129], v[128:129], 1.0 op_sel_hi:[1,0]
	s_nop 0
	s_nop 0
	v_rcp_f32_e32 v129, v129
	s_nop 0
	v_rcp_f32_e32 v136, v128
	v_cvt_pk_bf16_f32 v128, v131, v130
	v_xor_b32_e32 v130, v158, v150
	v_lshlrev_b32_e32 v130, 4, v130
	v_cvt_pk_bf16_f32 v129, v136, v129
	v_add3_u32 v130, v159, v130, v133
	ds_write_b64 v130, v[128:129]

; DEV u32x2 pk4(f32x4 v) { u32x2 r = {pk_bf16(v[0], v[1]), pk_bf16(v[2], v[3])}; return r; }
; DEV float fsigmoid(float x) { return 1.f / (1.f + __expf(-x)); }
;   DEV void operator()(f32x4 (&acc)[2][2][4][2], int brow, int bcol, int wr, int wc, int fr, int fq) const {
;     ...
;             } else if (mode == 1) {
;               for (int j = 0; j < 4; ++j) v[j] = v[j] * fsigmoid(v[j]);
;               tile_put4(rl, cl, pk4(v));
.LBB0_1697:
	s_andn2_b64 vcc, exec, s[20:21]
	s_cbranch_vccnz .LBB0_1699
	s_waitcnt vmcnt(0)
	v_mul_f32_e32 v128, 0xbfb8aa3b, v96
	v_mul_f32_e32 v129, 0xbfb8aa3b, v97
	v_exp_f32_e32 v128, v128
	v_exp_f32_e32 v129, v129
	s_nop 0
	v_pk_add_f32 v[128:129], v[128:129], 1.0 op_sel_hi:[1,0]
	s_nop 0
	s_nop 0
	v_rcp_f32_e32 v129, v129
	s_nop 0
	v_rcp_f32_e32 v128, v128
	v_mul_f32_e32 v130, 0xbfb8aa3b, v98
	v_mul_f32_e32 v131, 0xbfb8aa3b, v99
	v_exp_f32_e32 v130, v130
	v_exp_f32_e32 v131, v131
	v_pk_mul_f32 v[128:129], v[96:97], v[128:129]
	v_pk_add_f32 v[130:131], v[130:131], 1.0 op_sel_hi:[1,0]
	s_nop 0
	v_cvt_pk_bf16_f32 v128, v128, v129
	v_rcp_f32_e32 v131, v131
	s_nop 0
	v_rcp_f32_e32 v130, v130
	s_nop 0
	v_pk_mul_f32 v[130:131], v[98:99], v[130:131]
	s_nop 0
	v_cvt_pk_bf16_f32 v129, v130, v131
	v_xor_b32_e32 v130, v158, v150
	v_lshlrev_b32_e32 v130, 4, v130
	v_add3_u32 v130, v159, v130, v133
	ds_write_b64 v130, v[128:129]

; DEV u32x2 pk4(f32x4 v) { u32x2 r = {pk_bf16(v[0], v[1]), pk_bf16(v[2], v[3])}; return r; }
; DEV float fsigmoid(float x) { return 1.f / (1.f + __expf(-x)); }
;   DEV void operator()(f32x4 (&acc)[2][2][4][2], int brow, int bcol, int wr, int wc, int fr, int fq) const {
;     ...
;             } else if (mode == 2) {
;               for (int j = 0; j < 4; ++j) v[j] = fsigmoid(v[j]);
;               tile_put4(rl, cl, pk4(v));
.LBB0_1716:
	s_andn2_b64 vcc, exec, s[20:21]
	s_cbranch_vccnz .LBB0_1718
	s_waitcnt vmcnt(0)
	v_mul_f32_e32 v128, 0xbfb8aa3b, v92
	v_mul_f32_e32 v129, 0xbfb8aa3b, v93
	v_exp_f32_e32 v128, v128
	v_exp_f32_e32 v129, v129
	s_nop 0
	v_pk_add_f32 v[128:129], v[128:129], 1.0 op_sel_hi:[1,0]
	s_nop 0
	s_nop 0
	v_rcp_f32_e32 v130, v129
	s_nop 0
	v_rcp_f32_e32 v131, v128
	v_mul_f32_e32 v128, 0xbfb8aa3b, v94
	v_mul_f32_e32 v129, 0xbfb8aa3b, v95
	v_exp_f32_e32 v128, v128
	v_exp_f32_e32 v129, v129
	s_nop 0
	v_pk_add_f32 v[128:129], v[128:129], 1.0 op_sel_hi:[1,0]
	s_nop 0
	s_nop 0
	v_rcp_f32_e32 v129, v129
	s_nop 0
	v_rcp_f32_e32 v160, v128
	v_cvt_pk_bf16_f32 v128, v131, v130
	v_lshlrev_b32_e32 v130, 4, v151
	v_cvt_pk_bf16_f32 v129, v160, v129
	v_add3_u32 v130, v159, v130, v133
	ds_write_b64 v130, v[128:129]

; DEV u32x2 pk4(f32x4 v) { u32x2 r = {pk_bf16(v[0], v[1]), pk_bf16(v[2], v[3])}; return r; }
; DEV float fsigmoid(float x) { return 1.f / (1.f + __expf(-x)); }
;   DEV void operator()(f32x4 (&acc)[2][2][4][2], int brow, int bcol, int wr, int wc, int fr, int fq) const {
;     ...
;             } else if (mode == 1) {
;               for (int j = 0; j < 4; ++j) v[j] = v[j] * fsigmoid(v[j]);
;               tile_put4(rl, cl, pk4(v));
.LBB0_1719:
	s_andn2_b64 vcc, exec, s[20:21]
	s_cbranch_vccnz .LBB0_1721
	s_waitcnt vmcnt(0)
	v_mul_f32_e32 v128, 0xbfb8aa3b, v92
	v_mul_f32_e32 v129, 0xbfb8aa3b, v93
	v_exp_f32_e32 v128, v128
	v_exp_f32_e32 v129, v129
	s_nop 0
	v_pk_add_f32 v[128:129], v[128:129], 1.0 op_sel_hi:[1,0]
	s_nop 0
	s_nop 0
	v_rcp_f32_e32 v129, v129
	s_nop 0
	v_rcp_f32_e32 v128, v128
	v_mul_f32_e32 v130, 0xbfb8aa3b, v94
	v_mul_f32_e32 v131, 0xbfb8aa3b, v95
	v_exp_f32_e32 v130, v130
	v_exp_f32_e32 v131, v131
	v_pk_mul_f32 v[128:129], v[92:93], v[128:129]
	v_pk_add_f32 v[130:131], v[130:131], 1.0 op_sel_hi:[1,0]
	s_nop 0
	v_cvt_pk_bf16_f32 v128, v128, v129
	v_rcp_f32_e32 v131, v131
	s_nop 0
	v_rcp_f32_e32 v130, v130
	s_nop 0
	v_pk_mul_f32 v[130:131], v[94:95], v[130:131]
	s_nop 0
	v_cvt_pk_bf16_f32 v129, v130, v131
	v_lshlrev_b32_e32 v130, 4, v151
	v_add3_u32 v130, v159, v130, v133
	ds_write_b64 v130, v[128:129]

; DEV u32x2 pk4(f32x4 v) { u32x2 r = {pk_bf16(v[0], v[1]), pk_bf16(v[2], v[3])}; return r; }
; DEV float fsigmoid(float x) { return 1.f / (1.f + __expf(-x)); }
;   DEV void operator()(f32x4 (&acc)[2][2][4][2], int brow, int bcol, int wr, int wc, int fr, int fq) const {
;     ...
;             } else if (mode == 2) {
;               for (int j = 0; j < 4; ++j) v[j] = fsigmoid(v[j]);
;               tile_put4(rl, cl, pk4(v));
.LBB0_1730:
	s_andn2_b64 vcc, exec, s[20:21]
	s_cbranch_vccnz .LBB0_1732
	s_waitcnt vmcnt(0)
	v_mul_f32_e32 v128, 0xbfb8aa3b, v88
	v_mul_f32_e32 v129, 0xbfb8aa3b, v89
	v_exp_f32_e32 v128, v128
	v_exp_f32_e32 v129, v129
	s_nop 0
	v_pk_add_f32 v[128:129], v[128:129], 1.0 op_sel_hi:[1,0]
	s_nop 0
	s_nop 0
	v_rcp_f32_e32 v130, v129
	s_nop 0
	v_rcp_f32_e32 v131, v128
	v_mul_f32_e32 v128, 0xbfb8aa3b, v90
	v_mul_f32_e32 v129, 0xbfb8aa3b, v91
	v_exp_f32_e32 v128, v128
	v_exp_f32_e32 v129, v129
	s_nop 0
	v_pk_add_f32 v[128:129], v[128:129], 1.0 op_sel_hi:[1,0]
	s_nop 0
	s_nop 0
	v_rcp_f32_e32 v129, v129
	s_nop 0
	v_rcp_f32_e32 v160, v128
	v_cvt_pk_bf16_f32 v128, v131, v130
	v_lshlrev_b32_e32 v130, 4, v152
	v_cvt_pk_bf16_f32 v129, v160, v129
	v_add3_u32 v130, v159, v130, v133
	ds_write_b64 v130, v[128:129]

; DEV u32x2 pk4(f32x4 v) { u32x2 r = {pk_bf16(v[0], v[1]), pk_bf16(v[2], v[3])}; return r; }
; DEV float fsigmoid(float x) { return 1.f / (1.f + __expf(-x)); }
;   DEV void operator()(f32x4 (&acc)[2][2][4][2], int brow, int bcol, int wr, int wc, int fr, int fq) const {
;     ...
;             } else if (mode == 1) {
;               for (int j = 0; j < 4; ++j) v[j] = v[j] * fsigmoid(v[j]);
;               tile_put4(rl, cl, pk4(v));
.LBB0_1733:
	s_andn2_b64 vcc, exec, s[20:21]
	s_cbranch_vccnz .LBB0_1735
	s_waitcnt vmcnt(0)
	v_mul_f32_e32 v128, 0xbfb8aa3b, v88
	v_mul_f32_e32 v129, 0xbfb8aa3b, v89
	v_exp_f32_e32 v128, v128
	v_exp_f32_e32 v129, v129
	s_nop 0
	v_pk_add_f32 v[128:129], v[128:129], 1.0 op_sel_hi:[1,0]
	s_nop 0
	s_nop 0
	v_rcp_f32_e32 v129, v129
	s_nop 0
	v_rcp_f32_e32 v128, v128
	v_mul_f32_e32 v130, 0xbfb8aa3b, v90
	v_mul_f32_e32 v131, 0xbfb8aa3b, v91
	v_exp_f32_e32 v130, v130
	v_exp_f32_e32 v131, v131
	v_pk_mul_f32 v[128:129], v[88:89], v[128:129]
	v_pk_add_f32 v[130:131], v[130:131], 1.0 op_sel_hi:[1,0]
	s_nop 0
	v_cvt_pk_bf16_f32 v128, v128, v129
	v_rcp_f32_e32 v131, v131
	s_nop 0
	v_rcp_f32_e32 v130, v130
	s_nop 0
	v_pk_mul_f32 v[130:131], v[90:91], v[130:131]
	s_nop 0
	v_cvt_pk_bf16_f32 v129, v130, v131
	v_lshlrev_b32_e32 v130, 4, v152
	v_add3_u32 v130, v159, v130, v133
	ds_write_b64 v130, v[128:129]

; DEV u32x2 pk4(f32x4 v) { u32x2 r = {pk_bf16(v[0], v[1]), pk_bf16(v[2], v[3])}; return r; }
; DEV float fsigmoid(float x) { return 1.f / (1.f + __expf(-x)); }
;   DEV void operator()(f32x4 (&acc)[2][2][4][2], int brow, int bcol, int wr, int wc, int fr, int fq) const {
;     ...
;             } else if (mode == 2) {
;               for (int j = 0; j < 4; ++j) v[j] = fsigmoid(v[j]);
;               tile_put4(rl, cl, pk4(v));
.LBB0_1744:
	s_andn2_b64 vcc, exec, s[20:21]
	s_cbranch_vccnz .LBB0_1746
	s_waitcnt vmcnt(0)
	v_mul_f32_e32 v128, 0xbfb8aa3b, v84
	v_mul_f32_e32 v129, 0xbfb8aa3b, v85
	v_exp_f32_e32 v128, v128
	v_exp_f32_e32 v129, v129
	s_nop 0
	v_pk_add_f32 v[128:129], v[128:129], 1.0 op_sel_hi:[1,0]
	s_nop 0
	s_nop 0
	v_rcp_f32_e32 v130, v129
	s_nop 0
	v_rcp_f32_e32 v131, v128
	v_mul_f32_e32 v128, 0xbfb8aa3b, v86
	v_mul_f32_e32 v129, 0xbfb8aa3b, v87
	v_exp_f32_e32 v128, v128
	v_exp_f32_e32 v129, v129
	s_nop 0
	v_pk_add_f32 v[128:129], v[128:129], 1.0 op_sel_hi:[1,0]
	s_nop 0
	s_nop 0
	v_rcp_f32_e32 v129, v129
	s_nop 0
	v_rcp_f32_e32 v160, v128
	v_cvt_pk_bf16_f32 v128, v131, v130
	v_lshlrev_b32_e32 v130, 4, v153
	v_cvt_pk_bf16_f32 v129, v160, v129
	v_add3_u32 v130, v159, v130, v133
	ds_write_b64 v130, v[128:129]

; DEV u32x2 pk4(f32x4 v) { u32x2 r = {pk_bf16(v[0], v[1]), pk_bf16(v[2], v[3])}; return r; }
; DEV float fsigmoid(float x) { return 1.f / (1.f + __expf(-x)); }
;   DEV void operator()(f32x4 (&acc)[2][2][4][2], int brow, int bcol, int wr, int wc, int fr, int fq) const {
;     ...
;             } else if (mode == 1) {
;               for (int j = 0; j < 4; ++j) v[j] = v[j] * fsigmoid(v[j]);
;               tile_put4(rl, cl, pk4(v));
.LBB0_1747:
	s_andn2_b64 vcc, exec, s[20:21]
	s_cbranch_vccnz .LBB0_1749
	s_waitcnt vmcnt(0)
	v_mul_f32_e32 v128, 0xbfb8aa3b, v84
	v_mul_f32_e32 v129, 0xbfb8aa3b, v85
	v_exp_f32_e32 v128, v128
	v_exp_f32_e32 v129, v129
	s_nop 0
	v_pk_add_f32 v[128:129], v[128:129], 1.0 op_sel_hi:[1,0]
	s_nop 0
	s_nop 0
	v_rcp_f32_e32 v129, v129
	s_nop 0
	v_rcp_f32_e32 v128, v128
	v_mul_f32_e32 v130, 0xbfb8aa3b, v86
	v_mul_f32_e32 v131, 0xbfb8aa3b, v87
	v_exp_f32_e32 v130, v130
	v_exp_f32_e32 v131, v131
	v_pk_mul_f32 v[128:129], v[84:85], v[128:129]
	v_pk_add_f32 v[130:131], v[130:131], 1.0 op_sel_hi:[1,0]
	s_nop 0
	v_cvt_pk_bf16_f32 v128, v128, v129
	v_rcp_f32_e32 v131, v131
	s_nop 0
	v_rcp_f32_e32 v130, v130
	s_nop 0
	v_pk_mul_f32 v[130:131], v[86:87], v[130:131]
	s_nop 0
	v_cvt_pk_bf16_f32 v129, v130, v131
	v_lshlrev_b32_e32 v130, 4, v153
	v_add3_u32 v130, v159, v130, v133
	ds_write_b64 v130, v[128:129]

; DEV u32x2 pk4(f32x4 v) { u32x2 r = {pk_bf16(v[0], v[1]), pk_bf16(v[2], v[3])}; return r; }
; DEV float fsigmoid(float x) { return 1.f / (1.f + __expf(-x)); }
;   DEV void operator()(f32x4 (&acc)[2][2][4][2], int brow, int bcol, int wr, int wc, int fr, int fq) const {
;     ...
;             } else if (mode == 2) {
;               for (int j = 0; j < 4; ++j) v[j] = fsigmoid(v[j]);
;               tile_put4(rl, cl, pk4(v));
.LBB0_1758:
	s_andn2_b64 vcc, exec, s[20:21]
	s_cbranch_vccnz .LBB0_1760
	s_waitcnt vmcnt(0)
	v_mul_f32_e32 v128, 0xbfb8aa3b, v80
	v_mul_f32_e32 v129, 0xbfb8aa3b, v81
	v_exp_f32_e32 v128, v128
	v_exp_f32_e32 v129, v129
	s_nop 0
	v_pk_add_f32 v[128:129], v[128:129], 1.0 op_sel_hi:[1,0]
	s_nop 0
	s_nop 0
	v_rcp_f32_e32 v130, v129
	s_nop 0
	v_rcp_f32_e32 v131, v128
	v_mul_f32_e32 v128, 0xbfb8aa3b, v82
	v_mul_f32_e32 v129, 0xbfb8aa3b, v83
	v_exp_f32_e32 v128, v128
	v_exp_f32_e32 v129, v129
	s_nop 0
	v_pk_add_f32 v[128:129], v[128:129], 1.0 op_sel_hi:[1,0]
	s_nop 0
	s_nop 0
	v_rcp_f32_e32 v129, v129
	s_nop 0
	v_rcp_f32_e32 v136, v128
	v_cvt_pk_bf16_f32 v128, v131, v130
	v_lshlrev_b32_e32 v130, 4, v154
	v_cvt_pk_bf16_f32 v129, v136, v129
	v_add3_u32 v130, v159, v130, v133
	ds_write_b64 v130, v[128:129]

; DEV u32x2 pk4(f32x4 v) { u32x2 r = {pk_bf16(v[0], v[1]), pk_bf16(v[2], v[3])}; return r; }
; DEV float fsigmoid(float x) { return 1.f / (1.f + __expf(-x)); }
;   DEV void operator()(f32x4 (&acc)[2][2][4][2], int brow, int bcol, int wr, int wc, int fr, int fq) const {
;     ...
;             } else if (mode == 1) {
;               for (int j = 0; j < 4; ++j) v[j] = v[j] * fsigmoid(v[j]);
;               tile_put4(rl, cl, pk4(v));
.LBB0_1761:
	s_andn2_b64 vcc, exec, s[20:21]
	s_cbranch_vccnz .LBB0_1763
	s_waitcnt vmcnt(0)
	v_mul_f32_e32 v128, 0xbfb8aa3b, v80
	v_mul_f32_e32 v129, 0xbfb8aa3b, v81
	v_exp_f32_e32 v128, v128
	v_exp_f32_e32 v129, v129
	s_nop 0
	v_pk_add_f32 v[128:129], v[128:129], 1.0 op_sel_hi:[1,0]
	s_nop 0
	s_nop 0
	v_rcp_f32_e32 v129, v129
	s_nop 0
	v_rcp_f32_e32 v128, v128
	v_mul_f32_e32 v130, 0xbfb8aa3b, v82
	v_mul_f32_e32 v131, 0xbfb8aa3b, v83
	v_exp_f32_e32 v130, v130
	v_exp_f32_e32 v131, v131
	v_pk_mul_f32 v[128:129], v[80:81], v[128:129]
	v_pk_add_f32 v[130:131], v[130:131], 1.0 op_sel_hi:[1,0]
	s_nop 0
	v_cvt_pk_bf16_f32 v128, v128, v129
	v_rcp_f32_e32 v131, v131
	s_nop 0
	v_rcp_f32_e32 v130, v130
	s_nop 0
	v_pk_mul_f32 v[130:131], v[82:83], v[130:131]
	s_nop 0
	v_cvt_pk_bf16_f32 v129, v130, v131
	v_lshlrev_b32_e32 v130, 4, v154
	v_add3_u32 v130, v159, v130, v133
	ds_write_b64 v130, v[128:129]

; DEV u32x2 pk4(f32x4 v) { u32x2 r = {pk_bf16(v[0], v[1]), pk_bf16(v[2], v[3])}; return r; }
; DEV float fsigmoid(float x) { return 1.f / (1.f + __expf(-x)); }
;   DEV void operator()(f32x4 (&acc)[2][2][4][2], int brow, int bcol, int wr, int wc, int fr, int fq) const {
;     ...
;             } else if (mode == 2) {
;               for (int j = 0; j < 4; ++j) v[j] = fsigmoid(v[j]);
;               tile_put4(rl, cl, pk4(v));
.LBB0_1780:
	s_andn2_b64 vcc, exec, s[20:21]
	s_cbranch_vccnz .LBB0_1782
	s_waitcnt vmcnt(0)
	v_mul_f32_e32 v128, 0xbfb8aa3b, v76
	v_mul_f32_e32 v129, 0xbfb8aa3b, v77
	v_exp_f32_e32 v128, v128
	v_exp_f32_e32 v129, v129
	s_nop 0
	v_pk_add_f32 v[128:129], v[128:129], 1.0 op_sel_hi:[1,0]
	s_nop 0
	s_nop 0
	v_rcp_f32_e32 v130, v129
	s_nop 0
	v_rcp_f32_e32 v131, v128
	v_mul_f32_e32 v128, 0xbfb8aa3b, v78
	v_mul_f32_e32 v129, 0xbfb8aa3b, v79
	v_exp_f32_e32 v128, v128
	v_exp_f32_e32 v129, v129
	s_nop 0
	v_pk_add_f32 v[128:129], v[128:129], 1.0 op_sel_hi:[1,0]
	s_nop 0
	s_nop 0
	v_rcp_f32_e32 v129, v129
	s_nop 0
	v_rcp_f32_e32 v160, v128
	v_cvt_pk_bf16_f32 v128, v131, v130
	v_lshlrev_b32_e32 v130, 4, v155
	v_cvt_pk_bf16_f32 v129, v160, v129
	v_add3_u32 v130, v159, v130, v133
	ds_write_b64 v130, v[128:129]

; DEV u32x2 pk4(f32x4 v) { u32x2 r = {pk_bf16(v[0], v[1]), pk_bf16(v[2], v[3])}; return r; }
; DEV float fsigmoid(float x) { return 1.f / (1.f + __expf(-x)); }
;   DEV void operator()(f32x4 (&acc)[2][2][4][2], int brow, int bcol, int wr, int wc, int fr, int fq) const {
;     ...
;             } else if (mode == 1) {
;               for (int j = 0; j < 4; ++j) v[j] = v[j] * fsigmoid(v[j]);
;               tile_put4(rl, cl, pk4(v));
.LBB0_1783:
	s_andn2_b64 vcc, exec, s[20:21]
	s_cbranch_vccnz .LBB0_1785
	s_waitcnt vmcnt(0)
	v_mul_f32_e32 v128, 0xbfb8aa3b, v76
	v_mul_f32_e32 v129, 0xbfb8aa3b, v77
	v_exp_f32_e32 v128, v128
	v_exp_f32_e32 v129, v129
	s_nop 0
	v_pk_add_f32 v[128:129], v[128:129], 1.0 op_sel_hi:[1,0]
	s_nop 0
	s_nop 0
	v_rcp_f32_e32 v129, v129
	s_nop 0
	v_rcp_f32_e32 v128, v128
	v_mul_f32_e32 v130, 0xbfb8aa3b, v78
	v_mul_f32_e32 v131, 0xbfb8aa3b, v79
	v_exp_f32_e32 v130, v130
	v_exp_f32_e32 v131, v131
	v_pk_mul_f32 v[128:129], v[76:77], v[128:129]
	v_pk_add_f32 v[130:131], v[130:131], 1.0 op_sel_hi:[1,0]
	s_nop 0
	v_cvt_pk_bf16_f32 v128, v128, v129
	v_rcp_f32_e32 v131, v131
	s_nop 0
	v_rcp_f32_e32 v130, v130
	s_nop 0
	v_pk_mul_f32 v[130:131], v[78:79], v[130:131]
	s_nop 0
	v_cvt_pk_bf16_f32 v129, v130, v131
	v_lshlrev_b32_e32 v130, 4, v155
	v_add3_u32 v130, v159, v130, v133
	ds_write_b64 v130, v[128:129]

; DEV u32x2 pk4(f32x4 v) { u32x2 r = {pk_bf16(v[0], v[1]), pk_bf16(v[2], v[3])}; return r; }
; DEV float fsigmoid(float x) { return 1.f / (1.f + __expf(-x)); }
;   DEV void operator()(f32x4 (&acc)[2][2][4][2], int brow, int bcol, int wr, int wc, int fr, int fq) const {
;     ...
;             } else if (mode == 2) {
;               for (int j = 0; j < 4; ++j) v[j] = fsigmoid(v[j]);
;               tile_put4(rl, cl, pk4(v));
.LBB0_1794:
	s_andn2_b64 vcc, exec, s[20:21]
	s_cbranch_vccnz .LBB0_1796
	s_waitcnt vmcnt(0)
	v_mul_f32_e32 v128, 0xbfb8aa3b, v72
	v_mul_f32_e32 v129, 0xbfb8aa3b, v73
	v_exp_f32_e32 v128, v128
	v_exp_f32_e32 v129, v129
	s_nop 0
	v_pk_add_f32 v[128:129], v[128:129], 1.0 op_sel_hi:[1,0]
	s_nop 0
	s_nop 0
	v_rcp_f32_e32 v130, v129
	s_nop 0
	v_rcp_f32_e32 v131, v128
	v_mul_f32_e32 v128, 0xbfb8aa3b, v74
	v_mul_f32_e32 v129, 0xbfb8aa3b, v75
	v_exp_f32_e32 v128, v128
	v_exp_f32_e32 v129, v129
	s_nop 0
	v_pk_add_f32 v[128:129], v[128:129], 1.0 op_sel_hi:[1,0]
	s_nop 0
	s_nop 0
	v_rcp_f32_e32 v129, v129
	s_nop 0
	v_rcp_f32_e32 v160, v128
	v_cvt_pk_bf16_f32 v128, v131, v130
	v_lshlrev_b32_e32 v130, 4, v156
	v_cvt_pk_bf16_f32 v129, v160, v129
	v_add3_u32 v130, v159, v130, v133
	ds_write_b64 v130, v[128:129]

; DEV u32x2 pk4(f32x4 v) { u32x2 r = {pk_bf16(v[0], v[1]), pk_bf16(v[2], v[3])}; return r; }
; DEV float fsigmoid(float x) { return 1.f / (1.f + __expf(-x)); }
;   DEV void operator()(f32x4 (&acc)[2][2][4][2], int brow, int bcol, int wr, int wc, int fr, int fq) const {
;     ...
;             } else if (mode == 1) {
;               for (int j = 0; j < 4; ++j) v[j] = v[j] * fsigmoid(v[j]);
;               tile_put4(rl, cl, pk4(v));
.LBB0_1797:
	s_andn2_b64 vcc, exec, s[20:21]
	s_cbranch_vccnz .LBB0_1799
	s_waitcnt vmcnt(0)
	v_mul_f32_e32 v128, 0xbfb8aa3b, v72
	v_mul_f32_e32 v129, 0xbfb8aa3b, v73
	v_exp_f32_e32 v128, v128
	v_exp_f32_e32 v129, v129
	s_nop 0
	v_pk_add_f32 v[128:129], v[128:129], 1.0 op_sel_hi:[1,0]
	s_nop 0
	s_nop 0
	v_rcp_f32_e32 v129, v129
	s_nop 0
	v_rcp_f32_e32 v128, v128
	v_mul_f32_e32 v130, 0xbfb8aa3b, v74
	v_mul_f32_e32 v131, 0xbfb8aa3b, v75
	v_exp_f32_e32 v130, v130
	v_exp_f32_e32 v131, v131
	v_pk_mul_f32 v[128:129], v[72:73], v[128:129]
	v_pk_add_f32 v[130:131], v[130:131], 1.0 op_sel_hi:[1,0]
	s_nop 0
	v_cvt_pk_bf16_f32 v128, v128, v129
	v_rcp_f32_e32 v131, v131
	s_nop 0
	v_rcp_f32_e32 v130, v130
	s_nop 0
	v_pk_mul_f32 v[130:131], v[74:75], v[130:131]
	s_nop 0
	v_cvt_pk_bf16_f32 v129, v130, v131
	v_lshlrev_b32_e32 v130, 4, v156
	v_add3_u32 v130, v159, v130, v133
	ds_write_b64 v130, v[128:129]

; DEV u32x2 pk4(f32x4 v) { u32x2 r = {pk_bf16(v[0], v[1]), pk_bf16(v[2], v[3])}; return r; }
; DEV float fsigmoid(float x) { return 1.f / (1.f + __expf(-x)); }
;   DEV void operator()(f32x4 (&acc)[2][2][4][2], int brow, int bcol, int wr, int wc, int fr, int fq) const {
;     ...
;             } else if (mode == 2) {
;               for (int j = 0; j < 4; ++j) v[j] = fsigmoid(v[j]);
;               tile_put4(rl, cl, pk4(v));
.LBB0_1808:
	s_andn2_b64 vcc, exec, s[20:21]
	s_cbranch_vccnz .LBB0_1810
	s_waitcnt vmcnt(0)
	v_mul_f32_e32 v128, 0xbfb8aa3b, v68
	v_mul_f32_e32 v129, 0xbfb8aa3b, v69
	v_exp_f32_e32 v128, v128
	v_exp_f32_e32 v129, v129
	s_nop 0
	v_pk_add_f32 v[128:129], v[128:129], 1.0 op_sel_hi:[1,0]
	s_nop 0
	s_nop 0
	v_rcp_f32_e32 v130, v129
	s_nop 0
	v_rcp_f32_e32 v131, v128
	v_mul_f32_e32 v128, 0xbfb8aa3b, v70
	v_mul_f32_e32 v129, 0xbfb8aa3b, v71
	v_exp_f32_e32 v128, v128
	v_exp_f32_e32 v129, v129
	s_nop 0
	v_pk_add_f32 v[128:129], v[128:129], 1.0 op_sel_hi:[1,0]
	s_nop 0
	s_nop 0
	v_rcp_f32_e32 v129, v129
	s_nop 0
	v_rcp_f32_e32 v160, v128
	v_cvt_pk_bf16_f32 v128, v131, v130
	v_lshlrev_b32_e32 v130, 4, v157
	v_cvt_pk_bf16_f32 v129, v160, v129
	v_add3_u32 v130, v159, v130, v133
	ds_write_b64 v130, v[128:129]

; DEV u32x2 pk4(f32x4 v) { u32x2 r = {pk_bf16(v[0], v[1]), pk_bf16(v[2], v[3])}; return r; }
; DEV float fsigmoid(float x) { return 1.f / (1.f + __expf(-x)); }
;   DEV void operator()(f32x4 (&acc)[2][2][4][2], int brow, int bcol, int wr, int wc, int fr, int fq) const {
;     ...
;             } else if (mode == 1) {
;               for (int j = 0; j < 4; ++j) v[j] = v[j] * fsigmoid(v[j]);
;               tile_put4(rl, cl, pk4(v));
.LBB0_1811:
	s_andn2_b64 vcc, exec, s[20:21]
	s_cbranch_vccnz .LBB0_1813
	s_waitcnt vmcnt(0)
	v_mul_f32_e32 v128, 0xbfb8aa3b, v68
	v_mul_f32_e32 v129, 0xbfb8aa3b, v69
	v_exp_f32_e32 v128, v128
	v_exp_f32_e32 v129, v129
	s_nop 0
	v_pk_add_f32 v[128:129], v[128:129], 1.0 op_sel_hi:[1,0]
	s_nop 0
	s_nop 0
	v_rcp_f32_e32 v129, v129
	s_nop 0
	v_rcp_f32_e32 v128, v128
	v_mul_f32_e32 v130, 0xbfb8aa3b, v70
	v_mul_f32_e32 v131, 0xbfb8aa3b, v71
	v_exp_f32_e32 v130, v130
	v_exp_f32_e32 v131, v131
	v_pk_mul_f32 v[128:129], v[68:69], v[128:129]
	v_pk_add_f32 v[130:131], v[130:131], 1.0 op_sel_hi:[1,0]
	s_nop 0
	v_cvt_pk_bf16_f32 v128, v128, v129
	v_rcp_f32_e32 v131, v131
	s_nop 0
	v_rcp_f32_e32 v130, v130
	s_nop 0
	v_pk_mul_f32 v[130:131], v[70:71], v[130:131]
	s_nop 0
	v_cvt_pk_bf16_f32 v129, v130, v131
	v_lshlrev_b32_e32 v130, 4, v157
	v_add3_u32 v130, v159, v130, v133
	ds_write_b64 v130, v[128:129]

; DEV u32x2 pk4(f32x4 v) { u32x2 r = {pk_bf16(v[0], v[1]), pk_bf16(v[2], v[3])}; return r; }
; DEV float fsigmoid(float x) { return 1.f / (1.f + __expf(-x)); }
;   DEV void operator()(f32x4 (&acc)[2][2][4][2], int brow, int bcol, int wr, int wc, int fr, int fq) const {
;     ...
;             } else if (mode == 2) {
;               for (int j = 0; j < 4; ++j) v[j] = fsigmoid(v[j]);
;               tile_put4(rl, cl, pk4(v));
.LBB0_1822:
	s_andn2_b64 vcc, exec, s[20:21]
	s_cbranch_vccnz .LBB0_1824
	s_waitcnt vmcnt(0)
	v_mul_f32_e32 v128, 0xbfb8aa3b, v64
	v_mul_f32_e32 v129, 0xbfb8aa3b, v65
	v_exp_f32_e32 v128, v128
	v_exp_f32_e32 v129, v129
	s_nop 0
	v_pk_add_f32 v[128:129], v[128:129], 1.0 op_sel_hi:[1,0]
	s_nop 0
	s_nop 0
	v_rcp_f32_e32 v130, v129
	s_nop 0
	v_rcp_f32_e32 v131, v128
	v_mul_f32_e32 v128, 0xbfb8aa3b, v66
	v_mul_f32_e32 v129, 0xbfb8aa3b, v67
	v_exp_f32_e32 v128, v128
	v_exp_f32_e32 v129, v129
	s_nop 0
	v_pk_add_f32 v[128:129], v[128:129], 1.0 op_sel_hi:[1,0]
	s_nop 0
	s_nop 0
	v_rcp_f32_e32 v129, v129
	s_nop 0
	v_rcp_f32_e32 v136, v128
	v_cvt_pk_bf16_f32 v128, v131, v130
	v_lshlrev_b32_e32 v130, 4, v158
	v_cvt_pk_bf16_f32 v129, v136, v129
	v_add3_u32 v130, v159, v130, v133
	ds_write_b64 v130, v[128:129]

; DEV u32x2 pk4(f32x4 v) { u32x2 r = {pk_bf16(v[0], v[1]), pk_bf16(v[2], v[3])}; return r; }
; DEV float fsigmoid(float x) { return 1.f / (1.f + __expf(-x)); }
;   DEV void operator()(f32x4 (&acc)[2][2][4][2], int brow, int bcol, int wr, int wc, int fr, int fq) const {
;     ...
;             } else if (mode == 1) {
;               for (int j = 0; j < 4; ++j) v[j] = v[j] * fsigmoid(v[j]);
;               tile_put4(rl, cl, pk4(v));
.LBB0_1825:
	s_andn2_b64 vcc, exec, s[20:21]
	s_cbranch_vccnz .LBB0_1827
	s_waitcnt vmcnt(0)
	v_mul_f32_e32 v128, 0xbfb8aa3b, v64
	v_mul_f32_e32 v129, 0xbfb8aa3b, v65
	v_exp_f32_e32 v128, v128
	v_exp_f32_e32 v129, v129
	s_nop 0
	v_pk_add_f32 v[128:129], v[128:129], 1.0 op_sel_hi:[1,0]
	s_nop 0
	s_nop 0
	v_rcp_f32_e32 v129, v129
	s_nop 0
	v_rcp_f32_e32 v128, v128
	v_mul_f32_e32 v130, 0xbfb8aa3b, v66
	v_mul_f32_e32 v131, 0xbfb8aa3b, v67
	v_exp_f32_e32 v130, v130
	v_exp_f32_e32 v131, v131
	v_pk_mul_f32 v[128:129], v[64:65], v[128:129]
	v_pk_add_f32 v[130:131], v[130:131], 1.0 op_sel_hi:[1,0]
	s_nop 0
	v_cvt_pk_bf16_f32 v128, v128, v129
	v_rcp_f32_e32 v131, v131
	s_nop 0
	v_rcp_f32_e32 v130, v130
	s_nop 0
	v_pk_mul_f32 v[130:131], v[66:67], v[130:131]
	s_nop 0
	v_cvt_pk_bf16_f32 v129, v130, v131
	v_lshlrev_b32_e32 v130, 4, v158
	v_add3_u32 v130, v159, v130, v133
	ds_write_b64 v130, v[128:129]

; DEV u32x2 pk4(f32x4 v) { u32x2 r = {pk_bf16(v[0], v[1]), pk_bf16(v[2], v[3])}; return r; }
; DEV float fsigmoid(float x) { return 1.f / (1.f + __expf(-x)); }
;   DEV void operator()(f32x4 (&acc)[2][2][4][2], int brow, int bcol, int wr, int wc, int fr, int fq) const {
;     ...
;             } else if (mode == 2) {
;               for (int j = 0; j < 4; ++j) v[j] = fsigmoid(v[j]);
;               tile_put4(rl, cl, pk4(v));
.LBB0_1844:
	s_andn2_b64 vcc, exec, s[20:21]
	s_cbranch_vccnz .LBB0_1846
	s_waitcnt vmcnt(0)
	v_mul_f32_e32 v128, 0xbfb8aa3b, v60
	v_mul_f32_e32 v129, 0xbfb8aa3b, v61
	v_exp_f32_e32 v128, v128
	v_exp_f32_e32 v129, v129
	s_nop 0
	v_pk_add_f32 v[128:129], v[128:129], 1.0 op_sel_hi:[1,0]
	s_nop 0
	s_nop 0
	v_rcp_f32_e32 v130, v129
	s_nop 0
	v_rcp_f32_e32 v131, v128
	v_mul_f32_e32 v128, 0xbfb8aa3b, v62
	v_mul_f32_e32 v129, 0xbfb8aa3b, v63
	v_exp_f32_e32 v128, v128
	v_exp_f32_e32 v129, v129
	s_nop 0
	v_pk_add_f32 v[128:129], v[128:129], 1.0 op_sel_hi:[1,0]
	s_nop 0
	s_nop 0
	v_rcp_f32_e32 v129, v129
	s_nop 0
	v_rcp_f32_e32 v160, v128
	v_cvt_pk_bf16_f32 v128, v131, v130
	v_lshlrev_b32_e32 v130, 4, v151
	v_cvt_pk_bf16_f32 v129, v160, v129
	v_add3_u32 v130, v159, v130, v133
	ds_write_b64 v130, v[128:129]

; DEV u32x2 pk4(f32x4 v) { u32x2 r = {pk_bf16(v[0], v[1]), pk_bf16(v[2], v[3])}; return r; }
; DEV float fsigmoid(float x) { return 1.f / (1.f + __expf(-x)); }
;   DEV void operator()(f32x4 (&acc)[2][2][4][2], int brow, int bcol, int wr, int wc, int fr, int fq) const {
;     ...
;             } else if (mode == 1) {
;               for (int j = 0; j < 4; ++j) v[j] = v[j] * fsigmoid(v[j]);
;               tile_put4(rl, cl, pk4(v));
.LBB0_1847:
	s_andn2_b64 vcc, exec, s[20:21]
	s_cbranch_vccnz .LBB0_1849
	s_waitcnt vmcnt(0)
	v_mul_f32_e32 v128, 0xbfb8aa3b, v60
	v_mul_f32_e32 v129, 0xbfb8aa3b, v61
	v_exp_f32_e32 v128, v128
	v_exp_f32_e32 v129, v129
	s_nop 0
	v_pk_add_f32 v[128:129], v[128:129], 1.0 op_sel_hi:[1,0]
	s_nop 0
	s_nop 0
	v_rcp_f32_e32 v129, v129
	s_nop 0
	v_rcp_f32_e32 v128, v128
	v_mul_f32_e32 v130, 0xbfb8aa3b, v62
	v_mul_f32_e32 v131, 0xbfb8aa3b, v63
	v_exp_f32_e32 v130, v130
	v_exp_f32_e32 v131, v131
	v_pk_mul_f32 v[128:129], v[60:61], v[128:129]
	v_pk_add_f32 v[130:131], v[130:131], 1.0 op_sel_hi:[1,0]
	s_nop 0
	v_cvt_pk_bf16_f32 v128, v128, v129
	v_rcp_f32_e32 v131, v131
	s_nop 0
	v_rcp_f32_e32 v130, v130
	s_nop 0
	v_pk_mul_f32 v[130:131], v[62:63], v[130:131]
	s_nop 0
	v_cvt_pk_bf16_f32 v129, v130, v131
	v_lshlrev_b32_e32 v130, 4, v151
	v_add3_u32 v130, v159, v130, v133
	ds_write_b64 v130, v[128:129]

; DEV u32x2 pk4(f32x4 v) { u32x2 r = {pk_bf16(v[0], v[1]), pk_bf16(v[2], v[3])}; return r; }
; DEV float fsigmoid(float x) { return 1.f / (1.f + __expf(-x)); }
;   DEV void operator()(f32x4 (&acc)[2][2][4][2], int brow, int bcol, int wr, int wc, int fr, int fq) const {
;     ...
;             } else if (mode == 2) {
;               for (int j = 0; j < 4; ++j) v[j] = fsigmoid(v[j]);
;               tile_put4(rl, cl, pk4(v));
.LBB0_1858:
	s_andn2_b64 vcc, exec, s[20:21]
	s_cbranch_vccnz .LBB0_1860
	s_waitcnt vmcnt(0)
	v_mul_f32_e32 v128, 0xbfb8aa3b, v56
	v_mul_f32_e32 v129, 0xbfb8aa3b, v57
	v_exp_f32_e32 v128, v128
	v_exp_f32_e32 v129, v129
	s_nop 0
	v_pk_add_f32 v[128:129], v[128:129], 1.0 op_sel_hi:[1,0]
	s_nop 0
	s_nop 0
	v_rcp_f32_e32 v130, v129
	s_nop 0
	v_rcp_f32_e32 v131, v128
	v_mul_f32_e32 v128, 0xbfb8aa3b, v58
	v_mul_f32_e32 v129, 0xbfb8aa3b, v59
	v_exp_f32_e32 v128, v128
	v_exp_f32_e32 v129, v129
	s_nop 0
	v_pk_add_f32 v[128:129], v[128:129], 1.0 op_sel_hi:[1,0]
	s_nop 0
	s_nop 0
	v_rcp_f32_e32 v129, v129
	s_nop 0
	v_rcp_f32_e32 v160, v128
	v_cvt_pk_bf16_f32 v128, v131, v130
	v_lshlrev_b32_e32 v130, 4, v152
	v_cvt_pk_bf16_f32 v129, v160, v129
	v_add3_u32 v130, v159, v130, v133
	ds_write_b64 v130, v[128:129]

; DEV u32x2 pk4(f32x4 v) { u32x2 r = {pk_bf16(v[0], v[1]), pk_bf16(v[2], v[3])}; return r; }
; DEV float fsigmoid(float x) { return 1.f / (1.f + __expf(-x)); }
;   DEV void operator()(f32x4 (&acc)[2][2][4][2], int brow, int bcol, int wr, int wc, int fr, int fq) const {
;     ...
;               for (int j = 0; j < 4; ++j) v[j] = v[j] * fsigmoid(v[j]);
;               tile_put4(rl, cl, pk4(v));
.LBB0_1861:
	s_andn2_b64 vcc, exec, s[20:21]
	s_cbranch_vccnz .LBB0_1863
	s_waitcnt vmcnt(0)
	v_mul_f32_e32 v128, 0xbfb8aa3b, v56
	v_mul_f32_e32 v129, 0xbfb8aa3b, v57
	v_exp_f32_e32 v128, v128
	v_exp_f32_e32 v129, v129
	s_nop 0
	v_pk_add_f32 v[128:129], v[128:129], 1.0 op_sel_hi:[1,0]
	s_nop 0
	s_nop 0
	v_rcp_f32_e32 v129, v129
	s_nop 0
	v_rcp_f32_e32 v128, v128
	v_mul_f32_e32 v130, 0xbfb8aa3b, v58
	v_mul_f32_e32 v131, 0xbfb8aa3b, v59
	v_exp_f32_e32 v130, v130
	v_exp_f32_e32 v131, v131
	v_pk_mul_f32 v[128:129], v[56:57], v[128:129]
	v_pk_add_f32 v[130:131], v[130:131], 1.0 op_sel_hi:[1,0]
	s_nop 0
	v_cvt_pk_bf16_f32 v128, v128, v129
	v_rcp_f32_e32 v131, v131
	s_nop 0
	v_rcp_f32_e32 v130, v130
	s_nop 0
	v_pk_mul_f32 v[130:131], v[58:59], v[130:131]
	s_nop 0
	v_cvt_pk_bf16_f32 v129, v130, v131
	v_lshlrev_b32_e32 v130, 4, v152
	v_add3_u32 v130, v159, v130, v133
	ds_write_b64 v130, v[128:129]

; DEV u32x2 pk4(f32x4 v) { u32x2 r = {pk_bf16(v[0], v[1]), pk_bf16(v[2], v[3])}; return r; }
; DEV float fsigmoid(float x) { return 1.f / (1.f + __expf(-x)); }
;   DEV void operator()(f32x4 (&acc)[2][2][4][2], int brow, int bcol, int wr, int wc, int fr, int fq) const {
;     ...
;               for (int j = 0; j < 4; ++j) v[j] = fsigmoid(v[j]);
;               tile_put4(rl, cl, pk4(v));
.LBB0_1872:
	s_andn2_b64 vcc, exec, s[20:21]
	s_cbranch_vccnz .LBB0_1874
	s_waitcnt vmcnt(0)
	v_mul_f32_e32 v128, 0xbfb8aa3b, v52
	v_mul_f32_e32 v129, 0xbfb8aa3b, v53
	v_exp_f32_e32 v128, v128
	v_exp_f32_e32 v129, v129
	s_nop 0
	v_pk_add_f32 v[128:129], v[128:129], 1.0 op_sel_hi:[1,0]
	s_nop 0
	s_nop 0
	v_rcp_f32_e32 v130, v129
	s_nop 0
	v_rcp_f32_e32 v131, v128
	v_mul_f32_e32 v128, 0xbfb8aa3b, v54
	v_mul_f32_e32 v129, 0xbfb8aa3b, v55
	v_exp_f32_e32 v128, v128
	v_exp_f32_e32 v129, v129
	s_nop 0
	v_pk_add_f32 v[128:129], v[128:129], 1.0 op_sel_hi:[1,0]
	s_nop 0
	s_nop 0
	v_rcp_f32_e32 v129, v129
	s_nop 0
	v_rcp_f32_e32 v160, v128
	v_cvt_pk_bf16_f32 v128, v131, v130
	v_lshlrev_b32_e32 v130, 4, v153
	v_cvt_pk_bf16_f32 v129, v160, v129
	v_add3_u32 v130, v159, v130, v133
	ds_write_b64 v130, v[128:129]

; DEV u32x2 pk4(f32x4 v) { u32x2 r = {pk_bf16(v[0], v[1]), pk_bf16(v[2], v[3])}; return r; }
; DEV float fsigmoid(float x) { return 1.f / (1.f + __expf(-x)); }
;   DEV void operator()(f32x4 (&acc)[2][2][4][2], int brow, int bcol, int wr, int wc, int fr, int fq) const {
;     ...
;               for (int j = 0; j < 4; ++j) v[j] = v[j] * fsigmoid(v[j]);
;               tile_put4(rl, cl, pk4(v));
.LBB0_1875:
	s_andn2_b64 vcc, exec, s[20:21]
	s_cbranch_vccnz .LBB0_1877
	s_waitcnt vmcnt(0)
	v_mul_f32_e32 v128, 0xbfb8aa3b, v52
	v_mul_f32_e32 v129, 0xbfb8aa3b, v53
	v_exp_f32_e32 v128, v128
	v_exp_f32_e32 v129, v129
	s_nop 0
	v_pk_add_f32 v[128:129], v[128:129], 1.0 op_sel_hi:[1,0]
	s_nop 0
	s_nop 0
	v_rcp_f32_e32 v129, v129
	s_nop 0
	v_rcp_f32_e32 v128, v128
	v_mul_f32_e32 v130, 0xbfb8aa3b, v54
	v_mul_f32_e32 v131, 0xbfb8aa3b, v55
	v_exp_f32_e32 v130, v130
	v_exp_f32_e32 v131, v131
	v_pk_mul_f32 v[128:129], v[52:53], v[128:129]
	v_pk_add_f32 v[130:131], v[130:131], 1.0 op_sel_hi:[1,0]
	s_nop 0
	v_cvt_pk_bf16_f32 v128, v128, v129
	v_rcp_f32_e32 v131, v131
	s_nop 0
	v_rcp_f32_e32 v130, v130
	s_nop 0
	v_pk_mul_f32 v[130:131], v[54:55], v[130:131]
	s_nop 0
	v_cvt_pk_bf16_f32 v129, v130, v131
	v_lshlrev_b32_e32 v130, 4, v153
	v_add3_u32 v130, v159, v130, v133
	ds_write_b64 v130, v[128:129]

; DEV u32x2 pk4(f32x4 v) { u32x2 r = {pk_bf16(v[0], v[1]), pk_bf16(v[2], v[3])}; return r; }
; DEV float fsigmoid(float x) { return 1.f / (1.f + __expf(-x)); }
;   DEV void operator()(f32x4 (&acc)[2][2][4][2], int brow, int bcol, int wr, int wc, int fr, int fq) const {
;     ...
;               for (int j = 0; j < 4; ++j) v[j] = fsigmoid(v[j]);
;               tile_put4(rl, cl, pk4(v));
.LBB0_1886:
	s_andn2_b64 vcc, exec, s[20:21]
	s_cbranch_vccnz .LBB0_1888
	s_waitcnt vmcnt(0)
	v_mul_f32_e32 v128, 0xbfb8aa3b, v48
	v_mul_f32_e32 v129, 0xbfb8aa3b, v49
	v_exp_f32_e32 v128, v128
	v_exp_f32_e32 v129, v129
	s_nop 0
	v_pk_add_f32 v[128:129], v[128:129], 1.0 op_sel_hi:[1,0]
	s_nop 0
	s_nop 0
	v_rcp_f32_e32 v130, v129
	s_nop 0
	v_rcp_f32_e32 v131, v128
	v_mul_f32_e32 v128, 0xbfb8aa3b, v50
	v_mul_f32_e32 v129, 0xbfb8aa3b, v51
	v_exp_f32_e32 v128, v128
	v_exp_f32_e32 v129, v129
	s_nop 0
	v_pk_add_f32 v[128:129], v[128:129], 1.0 op_sel_hi:[1,0]
	s_nop 0
	s_nop 0
	v_rcp_f32_e32 v129, v129
	s_nop 0
	v_rcp_f32_e32 v136, v128
	v_cvt_pk_bf16_f32 v128, v131, v130
	v_lshlrev_b32_e32 v130, 4, v154
	v_cvt_pk_bf16_f32 v129, v136, v129
	v_add3_u32 v130, v159, v130, v133
	ds_write_b64 v130, v[128:129]

; DEV u32x2 pk4(f32x4 v) { u32x2 r = {pk_bf16(v[0], v[1]), pk_bf16(v[2], v[3])}; return r; }
; DEV float fsigmoid(float x) { return 1.f / (1.f + __expf(-x)); }
;   DEV void operator()(f32x4 (&acc)[2][2][4][2], int brow, int bcol, int wr, int wc, int fr, int fq) const {
;     ...
;               for (int j = 0; j < 4; ++j) v[j] = v[j] * fsigmoid(v[j]);
;               tile_put4(rl, cl, pk4(v));
.LBB0_1889:
	s_andn2_b64 vcc, exec, s[20:21]
	s_cbranch_vccnz .LBB0_1891
	s_waitcnt vmcnt(0)
	v_mul_f32_e32 v128, 0xbfb8aa3b, v48
	v_mul_f32_e32 v129, 0xbfb8aa3b, v49
	v_exp_f32_e32 v128, v128
	v_exp_f32_e32 v129, v129
	s_nop 0
	v_pk_add_f32 v[128:129], v[128:129], 1.0 op_sel_hi:[1,0]
	s_nop 0
	s_nop 0
	v_rcp_f32_e32 v129, v129
	s_nop 0
	v_rcp_f32_e32 v128, v128
	v_mul_f32_e32 v130, 0xbfb8aa3b, v50
	v_mul_f32_e32 v131, 0xbfb8aa3b, v51
	v_exp_f32_e32 v130, v130
	v_exp_f32_e32 v131, v131
	v_pk_mul_f32 v[128:129], v[48:49], v[128:129]
	v_pk_add_f32 v[130:131], v[130:131], 1.0 op_sel_hi:[1,0]
	s_nop 0
	v_cvt_pk_bf16_f32 v128, v128, v129
	v_rcp_f32_e32 v131, v131
	s_nop 0
	v_rcp_f32_e32 v130, v130
	s_nop 0
	v_pk_mul_f32 v[130:131], v[50:51], v[130:131]
	s_nop 0
	v_cvt_pk_bf16_f32 v129, v130, v131
	v_lshlrev_b32_e32 v130, 4, v154
	v_add3_u32 v130, v159, v130, v133
	ds_write_b64 v130, v[128:129]

; DEV u32x2 pk4(f32x4 v) { u32x2 r = {pk_bf16(v[0], v[1]), pk_bf16(v[2], v[3])}; return r; }
; DEV float fsigmoid(float x) { return 1.f / (1.f + __expf(-x)); }
;   DEV void operator()(f32x4 (&acc)[2][2][4][2], int brow, int bcol, int wr, int wc, int fr, int fq) const {
;     ...
;               for (int j = 0; j < 4; ++j) v[j] = fsigmoid(v[j]);
;               tile_put4(rl, cl, pk4(v));
.LBB0_1908:
	s_andn2_b64 vcc, exec, s[20:21]
	s_cbranch_vccnz .LBB0_1910
	s_waitcnt vmcnt(0)
	v_mul_f32_e32 v128, 0xbfb8aa3b, v44
	v_mul_f32_e32 v129, 0xbfb8aa3b, v45
	v_exp_f32_e32 v128, v128
	v_exp_f32_e32 v129, v129
	s_nop 0
	v_pk_add_f32 v[128:129], v[128:129], 1.0 op_sel_hi:[1,0]
	s_nop 0
	s_nop 0
	v_rcp_f32_e32 v130, v129
	s_nop 0
	v_rcp_f32_e32 v131, v128
	v_mul_f32_e32 v128, 0xbfb8aa3b, v46
	v_mul_f32_e32 v129, 0xbfb8aa3b, v47
	v_exp_f32_e32 v128, v128
	v_exp_f32_e32 v129, v129
	s_nop 0
	v_pk_add_f32 v[128:129], v[128:129], 1.0 op_sel_hi:[1,0]
	s_nop 0
	s_nop 0
	v_rcp_f32_e32 v129, v129
	s_nop 0
	v_rcp_f32_e32 v160, v128
	v_cvt_pk_bf16_f32 v128, v131, v130
	v_lshlrev_b32_e32 v130, 4, v155
	v_cvt_pk_bf16_f32 v129, v160, v129
	v_add3_u32 v130, v159, v130, v133
	ds_write_b64 v130, v[128:129]

; DEV u32x2 pk4(f32x4 v) { u32x2 r = {pk_bf16(v[0], v[1]), pk_bf16(v[2], v[3])}; return r; }
; DEV float fsigmoid(float x) { return 1.f / (1.f + __expf(-x)); }
;   DEV void operator()(f32x4 (&acc)[2][2][4][2], int brow, int bcol, int wr, int wc, int fr, int fq) const {
;     ...
;               for (int j = 0; j < 4; ++j) v[j] = v[j] * fsigmoid(v[j]);
;               tile_put4(rl, cl, pk4(v));
.LBB0_1911:
	s_andn2_b64 vcc, exec, s[20:21]
	s_cbranch_vccnz .LBB0_1913
	s_waitcnt vmcnt(0)
	v_mul_f32_e32 v128, 0xbfb8aa3b, v44
	v_mul_f32_e32 v129, 0xbfb8aa3b, v45
	v_exp_f32_e32 v128, v128
	v_exp_f32_e32 v129, v129
	s_nop 0
	v_pk_add_f32 v[128:129], v[128:129], 1.0 op_sel_hi:[1,0]
	s_nop 0
	s_nop 0
	v_rcp_f32_e32 v129, v129
	s_nop 0
	v_rcp_f32_e32 v128, v128
	v_mul_f32_e32 v130, 0xbfb8aa3b, v46
	v_mul_f32_e32 v131, 0xbfb8aa3b, v47
	v_exp_f32_e32 v130, v130
	v_exp_f32_e32 v131, v131
	v_pk_mul_f32 v[128:129], v[44:45], v[128:129]
	v_pk_add_f32 v[130:131], v[130:131], 1.0 op_sel_hi:[1,0]
	s_nop 0
	v_cvt_pk_bf16_f32 v128, v128, v129
	v_rcp_f32_e32 v131, v131
	s_nop 0
	v_rcp_f32_e32 v130, v130
	s_nop 0
	v_pk_mul_f32 v[130:131], v[46:47], v[130:131]
	s_nop 0
	v_cvt_pk_bf16_f32 v129, v130, v131
	v_lshlrev_b32_e32 v130, 4, v155
	v_add3_u32 v130, v159, v130, v133
	ds_write_b64 v130, v[128:129]

; DEV u32x2 pk4(f32x4 v) { u32x2 r = {pk_bf16(v[0], v[1]), pk_bf16(v[2], v[3])}; return r; }
; DEV float fsigmoid(float x) { return 1.f / (1.f + __expf(-x)); }
;   DEV void operator()(f32x4 (&acc)[2][2][4][2], int brow, int bcol, int wr, int wc, int fr, int fq) const {
;     ...
;               for (int j = 0; j < 4; ++j) v[j] = fsigmoid(v[j]);
;               tile_put4(rl, cl, pk4(v));
.LBB0_1922:
	s_andn2_b64 vcc, exec, s[20:21]
	s_cbranch_vccnz .LBB0_1924
	s_waitcnt vmcnt(0)
	v_mul_f32_e32 v128, 0xbfb8aa3b, v40
	v_mul_f32_e32 v129, 0xbfb8aa3b, v41
	v_exp_f32_e32 v128, v128
	v_exp_f32_e32 v129, v129
	s_nop 0
	v_pk_add_f32 v[128:129], v[128:129], 1.0 op_sel_hi:[1,0]
	s_nop 0
	s_nop 0
	v_rcp_f32_e32 v130, v129
	s_nop 0
	v_rcp_f32_e32 v131, v128
	v_mul_f32_e32 v128, 0xbfb8aa3b, v42
	v_mul_f32_e32 v129, 0xbfb8aa3b, v43
	v_exp_f32_e32 v128, v128
	v_exp_f32_e32 v129, v129
	s_nop 0
	v_pk_add_f32 v[128:129], v[128:129], 1.0 op_sel_hi:[1,0]
	s_nop 0
	s_nop 0
	v_rcp_f32_e32 v129, v129
	s_nop 0
	v_rcp_f32_e32 v160, v128
	v_cvt_pk_bf16_f32 v128, v131, v130
	v_lshlrev_b32_e32 v130, 4, v156
	v_cvt_pk_bf16_f32 v129, v160, v129
	v_add3_u32 v130, v159, v130, v133
	ds_write_b64 v130, v[128:129]

; DEV u32x2 pk4(f32x4 v) { u32x2 r = {pk_bf16(v[0], v[1]), pk_bf16(v[2], v[3])}; return r; }
; DEV float fsigmoid(float x) { return 1.f / (1.f + __expf(-x)); }
;   DEV void operator()(f32x4 (&acc)[2][2][4][2], int brow, int bcol, int wr, int wc, int fr, int fq) const {
;     ...
;               for (int j = 0; j < 4; ++j) v[j] = v[j] * fsigmoid(v[j]);
;               tile_put4(rl, cl, pk4(v));
.LBB0_1925:
	s_andn2_b64 vcc, exec, s[20:21]
	s_cbranch_vccnz .LBB0_1927
	s_waitcnt vmcnt(0)
	v_mul_f32_e32 v128, 0xbfb8aa3b, v40
	v_mul_f32_e32 v129, 0xbfb8aa3b, v41
	v_exp_f32_e32 v128, v128
	v_exp_f32_e32 v129, v129
	s_nop 0
	v_pk_add_f32 v[128:129], v[128:129], 1.0 op_sel_hi:[1,0]
	s_nop 0
	s_nop 0
	v_rcp_f32_e32 v129, v129
	s_nop 0
	v_rcp_f32_e32 v128, v128
	v_mul_f32_e32 v130, 0xbfb8aa3b, v42
	v_mul_f32_e32 v131, 0xbfb8aa3b, v43
	v_exp_f32_e32 v130, v130
	v_exp_f32_e32 v131, v131
	v_pk_mul_f32 v[128:129], v[40:41], v[128:129]
	v_pk_add_f32 v[130:131], v[130:131], 1.0 op_sel_hi:[1,0]
	s_nop 0
	v_cvt_pk_bf16_f32 v128, v128, v129
	v_rcp_f32_e32 v131, v131
	s_nop 0
	v_rcp_f32_e32 v130, v130
	s_nop 0
	v_pk_mul_f32 v[130:131], v[42:43], v[130:131]
	s_nop 0
	v_cvt_pk_bf16_f32 v129, v130, v131
	v_lshlrev_b32_e32 v130, 4, v156
	v_add3_u32 v130, v159, v130, v133
	ds_write_b64 v130, v[128:129]

; DEV u32x2 pk4(f32x4 v) { u32x2 r = {pk_bf16(v[0], v[1]), pk_bf16(v[2], v[3])}; return r; }
; DEV float fsigmoid(float x) { return 1.f / (1.f + __expf(-x)); }
;   DEV void operator()(f32x4 (&acc)[2][2][4][2], int brow, int bcol, int wr, int wc, int fr, int fq) const {
;     ...
;               for (int j = 0; j < 4; ++j) v[j] = fsigmoid(v[j]);
;               tile_put4(rl, cl, pk4(v));
.LBB0_1936:
	s_andn2_b64 vcc, exec, s[20:21]
	s_cbranch_vccnz .LBB0_1938
	s_waitcnt vmcnt(0)
	v_mul_f32_e32 v128, 0xbfb8aa3b, v36
	v_mul_f32_e32 v129, 0xbfb8aa3b, v37
	v_exp_f32_e32 v128, v128
	v_exp_f32_e32 v129, v129
	s_nop 0
	v_pk_add_f32 v[128:129], v[128:129], 1.0 op_sel_hi:[1,0]
	s_nop 0
	s_nop 0
	v_rcp_f32_e32 v130, v129
	s_nop 0
	v_rcp_f32_e32 v131, v128
	v_mul_f32_e32 v128, 0xbfb8aa3b, v38
	v_mul_f32_e32 v129, 0xbfb8aa3b, v39
	v_exp_f32_e32 v128, v128
	v_exp_f32_e32 v129, v129
	s_nop 0
	v_pk_add_f32 v[128:129], v[128:129], 1.0 op_sel_hi:[1,0]
	s_nop 0
	s_nop 0
	v_rcp_f32_e32 v129, v129
	s_nop 0
	v_rcp_f32_e32 v160, v128
	v_cvt_pk_bf16_f32 v128, v131, v130
	v_lshlrev_b32_e32 v130, 4, v157
	v_cvt_pk_bf16_f32 v129, v160, v129
	v_add3_u32 v130, v159, v130, v133
	ds_write_b64 v130, v[128:129]

; DEV u32x2 pk4(f32x4 v) { u32x2 r = {pk_bf16(v[0], v[1]), pk_bf16(v[2], v[3])}; return r; }
; DEV float fsigmoid(float x) { return 1.f / (1.f + __expf(-x)); }
;   DEV void operator()(f32x4 (&acc)[2][2][4][2], int brow, int bcol, int wr, int wc, int fr, int fq) const {
;     ...
;               for (int j = 0; j < 4; ++j) v[j] = v[j] * fsigmoid(v[j]);
;               tile_put4(rl, cl, pk4(v));
.LBB0_1939:
	s_andn2_b64 vcc, exec, s[20:21]
	s_cbranch_vccnz .LBB0_1941
	s_waitcnt vmcnt(0)
	v_mul_f32_e32 v128, 0xbfb8aa3b, v36
	v_mul_f32_e32 v129, 0xbfb8aa3b, v37
	v_exp_f32_e32 v128, v128
	v_exp_f32_e32 v129, v129
	s_nop 0
	v_pk_add_f32 v[128:129], v[128:129], 1.0 op_sel_hi:[1,0]
	s_nop 0
	s_nop 0
	v_rcp_f32_e32 v129, v129
	s_nop 0
	v_rcp_f32_e32 v128, v128
	v_mul_f32_e32 v130, 0xbfb8aa3b, v38
	v_mul_f32_e32 v131, 0xbfb8aa3b, v39
	v_exp_f32_e32 v130, v130
	v_exp_f32_e32 v131, v131
	v_pk_mul_f32 v[128:129], v[36:37], v[128:129]
	v_pk_add_f32 v[130:131], v[130:131], 1.0 op_sel_hi:[1,0]
	s_nop 0
	v_cvt_pk_bf16_f32 v128, v128, v129
	v_rcp_f32_e32 v131, v131
	s_nop 0
	v_rcp_f32_e32 v130, v130
	s_nop 0
	v_pk_mul_f32 v[130:131], v[38:39], v[130:131]
	s_nop 0
	v_cvt_pk_bf16_f32 v129, v130, v131
	v_lshlrev_b32_e32 v130, 4, v157
	v_add3_u32 v130, v159, v130, v133
	ds_write_b64 v130, v[128:129]

; DEV u32x2 pk4(f32x4 v) { u32x2 r = {pk_bf16(v[0], v[1]), pk_bf16(v[2], v[3])}; return r; }
; DEV float fsigmoid(float x) { return 1.f / (1.f + __expf(-x)); }
;   DEV void operator()(f32x4 (&acc)[2][2][4][2], int brow, int bcol, int wr, int wc, int fr, int fq) const {
;     ...
;               for (int j = 0; j < 4; ++j) v[j] = fsigmoid(v[j]);
;               tile_put4(rl, cl, pk4(v));
.LBB0_1950:
	s_andn2_b64 vcc, exec, s[20:21]
	s_cbranch_vccnz .LBB0_1952
	s_waitcnt vmcnt(0)
	v_mul_f32_e32 v128, 0xbfb8aa3b, v32
	v_mul_f32_e32 v129, 0xbfb8aa3b, v33
	v_exp_f32_e32 v128, v128
	v_exp_f32_e32 v129, v129
	s_nop 0
	v_pk_add_f32 v[128:129], v[128:129], 1.0 op_sel_hi:[1,0]
	s_nop 0
	s_nop 0
	v_rcp_f32_e32 v130, v129
	s_nop 0
	v_rcp_f32_e32 v131, v128
	v_mul_f32_e32 v128, 0xbfb8aa3b, v34
	v_mul_f32_e32 v129, 0xbfb8aa3b, v35
	v_exp_f32_e32 v128, v128
	v_exp_f32_e32 v129, v129
	s_nop 0
	v_pk_add_f32 v[128:129], v[128:129], 1.0 op_sel_hi:[1,0]
	s_nop 0
	s_nop 0
	v_rcp_f32_e32 v129, v129
	s_nop 0
	v_rcp_f32_e32 v136, v128
	v_cvt_pk_bf16_f32 v128, v131, v130
	v_lshlrev_b32_e32 v130, 4, v158
	v_cvt_pk_bf16_f32 v129, v136, v129
	v_add3_u32 v130, v159, v130, v133
	ds_write_b64 v130, v[128:129]

; DEV u32x2 pk4(f32x4 v) { u32x2 r = {pk_bf16(v[0], v[1]), pk_bf16(v[2], v[3])}; return r; }
; DEV float fsigmoid(float x) { return 1.f / (1.f + __expf(-x)); }
;   DEV void operator()(f32x4 (&acc)[2][2][4][2], int brow, int bcol, int wr, int wc, int fr, int fq) const {
;     ...
;               for (int j = 0; j < 4; ++j) v[j] = v[j] * fsigmoid(v[j]);
;               tile_put4(rl, cl, pk4(v));
.LBB0_1953:
	s_andn2_b64 vcc, exec, s[20:21]
	s_cbranch_vccnz .LBB0_1955
	s_waitcnt vmcnt(0)
	v_mul_f32_e32 v128, 0xbfb8aa3b, v32
	v_mul_f32_e32 v129, 0xbfb8aa3b, v33
	v_exp_f32_e32 v128, v128
	v_exp_f32_e32 v129, v129
	s_nop 0
	v_pk_add_f32 v[128:129], v[128:129], 1.0 op_sel_hi:[1,0]
	s_nop 0
	s_nop 0
	v_rcp_f32_e32 v129, v129
	s_nop 0
	v_rcp_f32_e32 v128, v128
	v_mul_f32_e32 v130, 0xbfb8aa3b, v34
	v_mul_f32_e32 v131, 0xbfb8aa3b, v35
	v_exp_f32_e32 v130, v130
	v_exp_f32_e32 v131, v131
	v_pk_mul_f32 v[128:129], v[32:33], v[128:129]
	v_pk_add_f32 v[130:131], v[130:131], 1.0 op_sel_hi:[1,0]
	s_nop 0
	v_cvt_pk_bf16_f32 v128, v128, v129
	v_rcp_f32_e32 v131, v131
	s_nop 0
	v_rcp_f32_e32 v130, v130
	s_nop 0
	v_pk_mul_f32 v[130:131], v[34:35], v[130:131]
	s_nop 0
	v_cvt_pk_bf16_f32 v129, v130, v131
	v_lshlrev_b32_e32 v130, 4, v158
	v_add3_u32 v130, v159, v130, v133
	ds_write_b64 v130, v[128:129]

; DEV u32x2 pk4(f32x4 v) { u32x2 r = {pk_bf16(v[0], v[1]), pk_bf16(v[2], v[3])}; return r; }
; DEV float fsigmoid(float x) { return 1.f / (1.f + __expf(-x)); }
;   DEV void operator()(f32x4 (&acc)[2][2][4][2], int brow, int bcol, int wr, int wc, int fr, int fq) const {
;     ...
;               for (int j = 0; j < 4; ++j) v[j] = fsigmoid(v[j]);
;               tile_put4(rl, cl, pk4(v));
.LBB0_1972:
	s_andn2_b64 vcc, exec, s[20:21]
	s_cbranch_vccnz .LBB0_1974
	s_waitcnt vmcnt(0)
	v_mul_f32_e32 v128, 0xbfb8aa3b, v28
	v_mul_f32_e32 v129, 0xbfb8aa3b, v29
	v_exp_f32_e32 v128, v128
	v_exp_f32_e32 v129, v129
	s_nop 0
	v_pk_add_f32 v[128:129], v[128:129], 1.0 op_sel_hi:[1,0]
	s_nop 0
	s_nop 0
	v_rcp_f32_e32 v130, v129
	s_nop 0
	v_rcp_f32_e32 v131, v128
	v_mul_f32_e32 v128, 0xbfb8aa3b, v30
	v_mul_f32_e32 v129, 0xbfb8aa3b, v31
	v_exp_f32_e32 v128, v128
	v_exp_f32_e32 v129, v129
	s_nop 0
	v_pk_add_f32 v[128:129], v[128:129], 1.0 op_sel_hi:[1,0]
	s_nop 0
	s_nop 0
	v_rcp_f32_e32 v129, v129
	s_nop 0
	v_rcp_f32_e32 v160, v128
	v_cvt_pk_bf16_f32 v128, v131, v130
	v_lshlrev_b32_e32 v130, 4, v151
	v_cvt_pk_bf16_f32 v129, v160, v129
	v_add3_u32 v130, v159, v130, v133
	ds_write_b64 v130, v[128:129]

; DEV u32x2 pk4(f32x4 v) { u32x2 r = {pk_bf16(v[0], v[1]), pk_bf16(v[2], v[3])}; return r; }
; DEV float fsigmoid(float x) { return 1.f / (1.f + __expf(-x)); }
;   DEV void operator()(f32x4 (&acc)[2][2][4][2], int brow, int bcol, int wr, int wc, int fr, int fq) const {
;     ...
;               for (int j = 0; j < 4; ++j) v[j] = v[j] * fsigmoid(v[j]);
;               tile_put4(rl, cl, pk4(v));
.LBB0_1975:
	s_andn2_b64 vcc, exec, s[20:21]
	s_cbranch_vccnz .LBB0_1977
	s_waitcnt vmcnt(0)
	v_mul_f32_e32 v128, 0xbfb8aa3b, v28
	v_mul_f32_e32 v129, 0xbfb8aa3b, v29
	v_exp_f32_e32 v128, v128
	v_exp_f32_e32 v129, v129
	s_nop 0
	v_pk_add_f32 v[128:129], v[128:129], 1.0 op_sel_hi:[1,0]
	s_nop 0
	s_nop 0
	v_rcp_f32_e32 v129, v129
	s_nop 0
	v_rcp_f32_e32 v128, v128
	v_mul_f32_e32 v130, 0xbfb8aa3b, v30
	v_mul_f32_e32 v131, 0xbfb8aa3b, v31
	v_exp_f32_e32 v130, v130
	v_exp_f32_e32 v131, v131
	v_pk_mul_f32 v[128:129], v[28:29], v[128:129]
	v_pk_add_f32 v[130:131], v[130:131], 1.0 op_sel_hi:[1,0]
	s_nop 0
	v_cvt_pk_bf16_f32 v128, v128, v129
	v_rcp_f32_e32 v131, v131
	s_nop 0
	v_rcp_f32_e32 v130, v130
	s_nop 0
	v_pk_mul_f32 v[130:131], v[30:31], v[130:131]
	s_nop 0
	v_cvt_pk_bf16_f32 v129, v130, v131
	v_lshlrev_b32_e32 v130, 4, v151
	v_add3_u32 v130, v159, v130, v133
	ds_write_b64 v130, v[128:129]

; DEV u32x2 pk4(f32x4 v) { u32x2 r = {pk_bf16(v[0], v[1]), pk_bf16(v[2], v[3])}; return r; }
; DEV float fsigmoid(float x) { return 1.f / (1.f + __expf(-x)); }
;   DEV void operator()(f32x4 (&acc)[2][2][4][2], int brow, int bcol, int wr, int wc, int fr, int fq) const {
;     ...
;               for (int j = 0; j < 4; ++j) v[j] = fsigmoid(v[j]);
;               tile_put4(rl, cl, pk4(v));
.LBB0_1986:
	s_andn2_b64 vcc, exec, s[20:21]
	s_cbranch_vccnz .LBB0_1988
	s_waitcnt vmcnt(0)
	v_mul_f32_e32 v128, 0xbfb8aa3b, v24
	v_mul_f32_e32 v129, 0xbfb8aa3b, v25
	v_exp_f32_e32 v128, v128
	v_exp_f32_e32 v129, v129
	s_nop 0
	v_pk_add_f32 v[128:129], v[128:129], 1.0 op_sel_hi:[1,0]
	s_nop 0
	s_nop 0
	v_rcp_f32_e32 v130, v129
	s_nop 0
	v_rcp_f32_e32 v131, v128
	v_mul_f32_e32 v128, 0xbfb8aa3b, v26
	v_mul_f32_e32 v129, 0xbfb8aa3b, v27
	v_exp_f32_e32 v128, v128
	v_exp_f32_e32 v129, v129
	s_nop 0
	v_pk_add_f32 v[128:129], v[128:129], 1.0 op_sel_hi:[1,0]
	s_nop 0
	s_nop 0
	v_rcp_f32_e32 v129, v129
	s_nop 0
	v_rcp_f32_e32 v151, v128
	v_cvt_pk_bf16_f32 v128, v131, v130
	v_lshlrev_b32_e32 v130, 4, v152
	v_cvt_pk_bf16_f32 v129, v151, v129
	v_add3_u32 v130, v159, v130, v133
	ds_write_b64 v130, v[128:129]

; DEV u32x2 pk4(f32x4 v) { u32x2 r = {pk_bf16(v[0], v[1]), pk_bf16(v[2], v[3])}; return r; }
; DEV float fsigmoid(float x) { return 1.f / (1.f + __expf(-x)); }
;   DEV void operator()(f32x4 (&acc)[2][2][4][2], int brow, int bcol, int wr, int wc, int fr, int fq) const {
;     ...
;               for (int j = 0; j < 4; ++j) v[j] = v[j] * fsigmoid(v[j]);
;               tile_put4(rl, cl, pk4(v));
.LBB0_1989:
	s_andn2_b64 vcc, exec, s[20:21]
	s_cbranch_vccnz .LBB0_1991
	s_waitcnt vmcnt(0)
	v_mul_f32_e32 v128, 0xbfb8aa3b, v24
	v_mul_f32_e32 v129, 0xbfb8aa3b, v25
	v_exp_f32_e32 v128, v128
	v_exp_f32_e32 v129, v129
	s_nop 0
	v_pk_add_f32 v[128:129], v[128:129], 1.0 op_sel_hi:[1,0]
	s_nop 0
	s_nop 0
	v_rcp_f32_e32 v129, v129
	s_nop 0
	v_rcp_f32_e32 v128, v128
	v_mul_f32_e32 v130, 0xbfb8aa3b, v26
	v_mul_f32_e32 v131, 0xbfb8aa3b, v27
	v_exp_f32_e32 v130, v130
	v_exp_f32_e32 v131, v131
	v_pk_mul_f32 v[128:129], v[24:25], v[128:129]
	v_pk_add_f32 v[130:131], v[130:131], 1.0 op_sel_hi:[1,0]
	s_nop 0
	v_cvt_pk_bf16_f32 v128, v128, v129
	v_rcp_f32_e32 v131, v131
	s_nop 0
	v_rcp_f32_e32 v130, v130
	s_nop 0
	v_pk_mul_f32 v[130:131], v[26:27], v[130:131]
	s_nop 0
	v_cvt_pk_bf16_f32 v129, v130, v131
	v_lshlrev_b32_e32 v130, 4, v152
	v_add3_u32 v130, v159, v130, v133
	ds_write_b64 v130, v[128:129]

; DEV u32x2 pk4(f32x4 v) { u32x2 r = {pk_bf16(v[0], v[1]), pk_bf16(v[2], v[3])}; return r; }
; DEV float fsigmoid(float x) { return 1.f / (1.f + __expf(-x)); }
;   DEV void operator()(f32x4 (&acc)[2][2][4][2], int brow, int bcol, int wr, int wc, int fr, int fq) const {
;     ...
;               for (int j = 0; j < 4; ++j) v[j] = fsigmoid(v[j]);
;               tile_put4(rl, cl, pk4(v));
.LBB0_2000:
	s_andn2_b64 vcc, exec, s[20:21]
	s_cbranch_vccnz .LBB0_2002
	s_waitcnt vmcnt(0)
	v_mul_f32_e32 v128, 0xbfb8aa3b, v20
	v_mul_f32_e32 v129, 0xbfb8aa3b, v21
	v_exp_f32_e32 v128, v128
	v_exp_f32_e32 v129, v129
	s_nop 0
	v_pk_add_f32 v[128:129], v[128:129], 1.0 op_sel_hi:[1,0]
	s_nop 0
	s_nop 0
	v_rcp_f32_e32 v130, v129
	s_nop 0
	v_rcp_f32_e32 v131, v128
	v_mul_f32_e32 v128, 0xbfb8aa3b, v22
	v_mul_f32_e32 v129, 0xbfb8aa3b, v23
	v_exp_f32_e32 v128, v128
	v_exp_f32_e32 v129, v129
	s_nop 0
	v_pk_add_f32 v[128:129], v[128:129], 1.0 op_sel_hi:[1,0]
	s_nop 0
	s_nop 0
	v_rcp_f32_e32 v129, v129
	s_nop 0
	v_rcp_f32_e32 v151, v128
	v_cvt_pk_bf16_f32 v128, v131, v130
	v_lshlrev_b32_e32 v130, 4, v153
	v_cvt_pk_bf16_f32 v129, v151, v129
	v_add3_u32 v130, v159, v130, v133
	ds_write_b64 v130, v[128:129]

; DEV u32x2 pk4(f32x4 v) { u32x2 r = {pk_bf16(v[0], v[1]), pk_bf16(v[2], v[3])}; return r; }
; DEV float fsigmoid(float x) { return 1.f / (1.f + __expf(-x)); }
;   DEV void operator()(f32x4 (&acc)[2][2][4][2], int brow, int bcol, int wr, int wc, int fr, int fq) const {
;     ...
;               for (int j = 0; j < 4; ++j) v[j] = v[j] * fsigmoid(v[j]);
;               tile_put4(rl, cl, pk4(v));
.LBB0_2003:
	s_andn2_b64 vcc, exec, s[20:21]
	s_cbranch_vccnz .LBB0_2005
	s_waitcnt vmcnt(0)
	v_mul_f32_e32 v128, 0xbfb8aa3b, v20
	v_mul_f32_e32 v129, 0xbfb8aa3b, v21
	v_exp_f32_e32 v128, v128
	v_exp_f32_e32 v129, v129
	s_nop 0
	v_pk_add_f32 v[128:129], v[128:129], 1.0 op_sel_hi:[1,0]
	s_nop 0
	s_nop 0
	v_rcp_f32_e32 v129, v129
	s_nop 0
	v_rcp_f32_e32 v128, v128
	v_mul_f32_e32 v130, 0xbfb8aa3b, v22
	v_mul_f32_e32 v131, 0xbfb8aa3b, v23
	v_exp_f32_e32 v130, v130
	v_exp_f32_e32 v131, v131
	v_pk_mul_f32 v[128:129], v[20:21], v[128:129]
	v_pk_add_f32 v[130:131], v[130:131], 1.0 op_sel_hi:[1,0]
	s_nop 0
	v_cvt_pk_bf16_f32 v128, v128, v129
	v_rcp_f32_e32 v131, v131
	s_nop 0
	v_rcp_f32_e32 v130, v130
	s_nop 0
	v_pk_mul_f32 v[130:131], v[22:23], v[130:131]
	s_nop 0
	v_cvt_pk_bf16_f32 v129, v130, v131
	v_lshlrev_b32_e32 v130, 4, v153
	v_add3_u32 v130, v159, v130, v133
	ds_write_b64 v130, v[128:129]

; DEV u32x2 pk4(f32x4 v) { u32x2 r = {pk_bf16(v[0], v[1]), pk_bf16(v[2], v[3])}; return r; }
; DEV float fsigmoid(float x) { return 1.f / (1.f + __expf(-x)); }
;   DEV void operator()(f32x4 (&acc)[2][2][4][2], int brow, int bcol, int wr, int wc, int fr, int fq) const {
;     ...
;               for (int j = 0; j < 4; ++j) v[j] = fsigmoid(v[j]);
;               tile_put4(rl, cl, pk4(v));
.LBB0_2014:
	s_andn2_b64 vcc, exec, s[20:21]
	s_cbranch_vccnz .LBB0_2016
	s_waitcnt vmcnt(0)
	v_mul_f32_e32 v128, 0xbfb8aa3b, v16
	v_mul_f32_e32 v129, 0xbfb8aa3b, v17
	v_exp_f32_e32 v128, v128
	v_exp_f32_e32 v129, v129
	s_nop 0
	v_pk_add_f32 v[128:129], v[128:129], 1.0 op_sel_hi:[1,0]
	s_nop 0
	s_nop 0
	v_rcp_f32_e32 v130, v129
	s_nop 0
	v_rcp_f32_e32 v131, v128
	v_mul_f32_e32 v128, 0xbfb8aa3b, v18
	v_mul_f32_e32 v129, 0xbfb8aa3b, v19
	v_exp_f32_e32 v128, v128
	v_exp_f32_e32 v129, v129
	s_nop 0
	v_pk_add_f32 v[128:129], v[128:129], 1.0 op_sel_hi:[1,0]
	s_nop 0
	s_nop 0
	v_rcp_f32_e32 v129, v129
	s_nop 0
	v_rcp_f32_e32 v136, v128
	v_cvt_pk_bf16_f32 v128, v131, v130
	v_lshlrev_b32_e32 v130, 4, v154
	v_cvt_pk_bf16_f32 v129, v136, v129
	v_add3_u32 v130, v159, v130, v133
	ds_write_b64 v130, v[128:129]

; DEV u32x2 pk4(f32x4 v) { u32x2 r = {pk_bf16(v[0], v[1]), pk_bf16(v[2], v[3])}; return r; }
; DEV float fsigmoid(float x) { return 1.f / (1.f + __expf(-x)); }
;   DEV void operator()(f32x4 (&acc)[2][2][4][2], int brow, int bcol, int wr, int wc, int fr, int fq) const {
;     ...
;               for (int j = 0; j < 4; ++j) v[j] = v[j] * fsigmoid(v[j]);
;               tile_put4(rl, cl, pk4(v));
.LBB0_2017:
	s_andn2_b64 vcc, exec, s[20:21]
	s_cbranch_vccnz .LBB0_2019
	s_waitcnt vmcnt(0)
	v_mul_f32_e32 v128, 0xbfb8aa3b, v16
	v_mul_f32_e32 v129, 0xbfb8aa3b, v17
	v_exp_f32_e32 v128, v128
	v_exp_f32_e32 v129, v129
	s_nop 0
	v_pk_add_f32 v[128:129], v[128:129], 1.0 op_sel_hi:[1,0]
	s_nop 0
	s_nop 0
	v_rcp_f32_e32 v129, v129
	s_nop 0
	v_rcp_f32_e32 v128, v128
	v_mul_f32_e32 v130, 0xbfb8aa3b, v18
	v_mul_f32_e32 v131, 0xbfb8aa3b, v19
	v_exp_f32_e32 v130, v130
	v_exp_f32_e32 v131, v131
	v_pk_mul_f32 v[128:129], v[16:17], v[128:129]
	v_pk_add_f32 v[130:131], v[130:131], 1.0 op_sel_hi:[1,0]
	s_nop 0
	v_cvt_pk_bf16_f32 v128, v128, v129
	v_rcp_f32_e32 v131, v131
	s_nop 0
	v_rcp_f32_e32 v130, v130
	s_nop 0
	v_pk_mul_f32 v[130:131], v[18:19], v[130:131]
	s_nop 0
	v_cvt_pk_bf16_f32 v129, v130, v131
	v_lshlrev_b32_e32 v130, 4, v154
	v_add3_u32 v130, v159, v130, v133
	ds_write_b64 v130, v[128:129]

; DEV u32x2 pk4(f32x4 v) { u32x2 r = {pk_bf16(v[0], v[1]), pk_bf16(v[2], v[3])}; return r; }
; DEV float fsigmoid(float x) { return 1.f / (1.f + __expf(-x)); }
;   DEV void operator()(f32x4 (&acc)[2][2][4][2], int brow, int bcol, int wr, int wc, int fr, int fq) const {
;     ...
;               for (int j = 0; j < 4; ++j) v[j] = fsigmoid(v[j]);
;               tile_put4(rl, cl, pk4(v));
.LBB0_2036:
	s_andn2_b64 vcc, exec, s[20:21]
	s_cbranch_vccnz .LBB0_2038
	s_waitcnt vmcnt(0)
	v_mul_f32_e32 v128, 0xbfb8aa3b, v12
	v_mul_f32_e32 v129, 0xbfb8aa3b, v13
	v_exp_f32_e32 v128, v128
	v_exp_f32_e32 v129, v129
	s_nop 0
	v_pk_add_f32 v[128:129], v[128:129], 1.0 op_sel_hi:[1,0]
	s_nop 0
	s_nop 0
	v_rcp_f32_e32 v130, v129
	s_nop 0
	v_rcp_f32_e32 v131, v128
	v_mul_f32_e32 v128, 0xbfb8aa3b, v14
	v_mul_f32_e32 v129, 0xbfb8aa3b, v15
	v_exp_f32_e32 v128, v128
	v_exp_f32_e32 v129, v129
	s_nop 0
	v_pk_add_f32 v[128:129], v[128:129], 1.0 op_sel_hi:[1,0]
	s_nop 0
	s_nop 0
	v_rcp_f32_e32 v129, v129
	s_nop 0
	v_rcp_f32_e32 v142, v128
	v_cvt_pk_bf16_f32 v128, v131, v130
	v_lshlrev_b32_e32 v130, 4, v155
	v_cvt_pk_bf16_f32 v129, v142, v129
	v_add3_u32 v130, v144, v130, v133
	ds_write_b64 v130, v[128:129]

; DEV u32x2 pk4(f32x4 v) { u32x2 r = {pk_bf16(v[0], v[1]), pk_bf16(v[2], v[3])}; return r; }
; DEV float fsigmoid(float x) { return 1.f / (1.f + __expf(-x)); }
;   DEV void operator()(f32x4 (&acc)[2][2][4][2], int brow, int bcol, int wr, int wc, int fr, int fq) const {
;     ...
;               for (int j = 0; j < 4; ++j) v[j] = v[j] * fsigmoid(v[j]);
;               tile_put4(rl, cl, pk4(v));
.LBB0_2039:
	s_andn2_b64 vcc, exec, s[20:21]
	s_cbranch_vccnz .LBB0_2041
	s_waitcnt vmcnt(0)
	v_mul_f32_e32 v128, 0xbfb8aa3b, v12
	v_mul_f32_e32 v129, 0xbfb8aa3b, v13
	v_exp_f32_e32 v128, v128
	v_exp_f32_e32 v129, v129
	s_nop 0
	v_pk_add_f32 v[128:129], v[128:129], 1.0 op_sel_hi:[1,0]
	s_nop 0
	s_nop 0
	v_rcp_f32_e32 v129, v129
	s_nop 0
	v_rcp_f32_e32 v128, v128
	v_mul_f32_e32 v130, 0xbfb8aa3b, v14
	v_mul_f32_e32 v131, 0xbfb8aa3b, v15
	v_exp_f32_e32 v130, v130
	v_exp_f32_e32 v131, v131
	v_pk_mul_f32 v[128:129], v[12:13], v[128:129]
	v_pk_add_f32 v[130:131], v[130:131], 1.0 op_sel_hi:[1,0]
	s_nop 0
	v_cvt_pk_bf16_f32 v128, v128, v129
	v_rcp_f32_e32 v131, v131
	s_nop 0
	v_rcp_f32_e32 v130, v130
	s_nop 0
	v_pk_mul_f32 v[130:131], v[14:15], v[130:131]
	s_nop 0
	v_cvt_pk_bf16_f32 v129, v130, v131
	v_lshlrev_b32_e32 v130, 4, v155
	v_add3_u32 v130, v144, v130, v133
	ds_write_b64 v130, v[128:129]

; DEV u32x2 pk4(f32x4 v) { u32x2 r = {pk_bf16(v[0], v[1]), pk_bf16(v[2], v[3])}; return r; }
; DEV float fsigmoid(float x) { return 1.f / (1.f + __expf(-x)); }
;   DEV void operator()(f32x4 (&acc)[2][2][4][2], int brow, int bcol, int wr, int wc, int fr, int fq) const {
;     ...
;               for (int j = 0; j < 4; ++j) v[j] = fsigmoid(v[j]);
;               tile_put4(rl, cl, pk4(v));
.LBB0_2050:
	s_andn2_b64 vcc, exec, s[20:21]
	s_cbranch_vccnz .LBB0_2052
	s_waitcnt vmcnt(0)
	v_mul_f32_e32 v128, 0xbfb8aa3b, v8
	v_mul_f32_e32 v129, 0xbfb8aa3b, v9
	v_exp_f32_e32 v128, v128
	v_exp_f32_e32 v129, v129
	s_nop 0
	v_pk_add_f32 v[128:129], v[128:129], 1.0 op_sel_hi:[1,0]
	s_nop 0
	s_nop 0
	v_rcp_f32_e32 v130, v129
	s_nop 0
	v_rcp_f32_e32 v131, v128
	v_mul_f32_e32 v128, 0xbfb8aa3b, v10
	v_mul_f32_e32 v129, 0xbfb8aa3b, v11
	v_exp_f32_e32 v128, v128
	v_exp_f32_e32 v129, v129
	s_nop 0
	v_pk_add_f32 v[128:129], v[128:129], 1.0 op_sel_hi:[1,0]
	s_nop 0
	s_nop 0
	v_rcp_f32_e32 v129, v129
	s_nop 0
	v_rcp_f32_e32 v142, v128
	v_cvt_pk_bf16_f32 v128, v131, v130
	v_lshlrev_b32_e32 v130, 4, v156
	v_cvt_pk_bf16_f32 v129, v142, v129
	v_add3_u32 v130, v144, v130, v133
	ds_write_b64 v130, v[128:129]

; DEV u32x2 pk4(f32x4 v) { u32x2 r = {pk_bf16(v[0], v[1]), pk_bf16(v[2], v[3])}; return r; }
; DEV float fsigmoid(float x) { return 1.f / (1.f + __expf(-x)); }
;   DEV void operator()(f32x4 (&acc)[2][2][4][2], int brow, int bcol, int wr, int wc, int fr, int fq) const {
;     ...
;               for (int j = 0; j < 4; ++j) v[j] = v[j] * fsigmoid(v[j]);
;               tile_put4(rl, cl, pk4(v));
.LBB0_2053:
	s_andn2_b64 vcc, exec, s[20:21]
	s_cbranch_vccnz .LBB0_2055
	s_waitcnt vmcnt(0)
	v_mul_f32_e32 v128, 0xbfb8aa3b, v8
	v_mul_f32_e32 v129, 0xbfb8aa3b, v9
	v_exp_f32_e32 v128, v128
	v_exp_f32_e32 v129, v129
	s_nop 0
	v_pk_add_f32 v[128:129], v[128:129], 1.0 op_sel_hi:[1,0]
	s_nop 0
	s_nop 0
	v_rcp_f32_e32 v129, v129
	s_nop 0
	v_rcp_f32_e32 v128, v128
	v_mul_f32_e32 v130, 0xbfb8aa3b, v10
	v_mul_f32_e32 v131, 0xbfb8aa3b, v11
	v_exp_f32_e32 v130, v130
	v_exp_f32_e32 v131, v131
	v_pk_mul_f32 v[128:129], v[8:9], v[128:129]
	v_pk_add_f32 v[130:131], v[130:131], 1.0 op_sel_hi:[1,0]
	s_nop 0
	v_cvt_pk_bf16_f32 v128, v128, v129
	v_rcp_f32_e32 v131, v131
	s_nop 0
	v_rcp_f32_e32 v130, v130
	s_nop 0
	v_pk_mul_f32 v[130:131], v[10:11], v[130:131]
	s_nop 0
	v_cvt_pk_bf16_f32 v129, v130, v131
	v_lshlrev_b32_e32 v130, 4, v156
	v_add3_u32 v130, v144, v130, v133
	ds_write_b64 v130, v[128:129]

; DEV u32x2 pk4(f32x4 v) { u32x2 r = {pk_bf16(v[0], v[1]), pk_bf16(v[2], v[3])}; return r; }
; DEV float fsigmoid(float x) { return 1.f / (1.f + __expf(-x)); }
;   DEV void operator()(f32x4 (&acc)[2][2][4][2], int brow, int bcol, int wr, int wc, int fr, int fq) const {
;     ...
;               for (int j = 0; j < 4; ++j) v[j] = fsigmoid(v[j]);
;               tile_put4(rl, cl, pk4(v));
.LBB0_2064:
	s_andn2_b64 vcc, exec, s[20:21]
	s_cbranch_vccnz .LBB0_2066
	s_waitcnt vmcnt(0)
	v_mul_f32_e32 v128, 0xbfb8aa3b, v4
	v_mul_f32_e32 v129, 0xbfb8aa3b, v5
	v_exp_f32_e32 v128, v128
	v_exp_f32_e32 v129, v129
	s_nop 0
	v_pk_add_f32 v[128:129], v[128:129], 1.0 op_sel_hi:[1,0]
	s_nop 0
	s_nop 0
	v_rcp_f32_e32 v130, v129
	s_nop 0
	v_rcp_f32_e32 v131, v128
	v_mul_f32_e32 v128, 0xbfb8aa3b, v6
	v_mul_f32_e32 v129, 0xbfb8aa3b, v7
	v_exp_f32_e32 v128, v128
	v_exp_f32_e32 v129, v129
	s_nop 0
	v_pk_add_f32 v[128:129], v[128:129], 1.0 op_sel_hi:[1,0]
	s_nop 0
	s_nop 0
	v_rcp_f32_e32 v129, v129
	s_nop 0
	v_rcp_f32_e32 v142, v128
	v_cvt_pk_bf16_f32 v128, v131, v130
	v_lshlrev_b32_e32 v130, 4, v157
	v_cvt_pk_bf16_f32 v129, v142, v129
	v_add3_u32 v130, v144, v130, v133
	ds_write_b64 v130, v[128:129]

; DEV u32x2 pk4(f32x4 v) { u32x2 r = {pk_bf16(v[0], v[1]), pk_bf16(v[2], v[3])}; return r; }
; DEV float fsigmoid(float x) { return 1.f / (1.f + __expf(-x)); }
;   DEV void operator()(f32x4 (&acc)[2][2][4][2], int brow, int bcol, int wr, int wc, int fr, int fq) const {
;     ...
;               for (int j = 0; j < 4; ++j) v[j] = v[j] * fsigmoid(v[j]);
;               tile_put4(rl, cl, pk4(v));
.LBB0_2067:
	s_andn2_b64 vcc, exec, s[20:21]
	s_cbranch_vccnz .LBB0_2069
	s_waitcnt vmcnt(0)
	v_mul_f32_e32 v128, 0xbfb8aa3b, v4
	v_mul_f32_e32 v129, 0xbfb8aa3b, v5
	v_exp_f32_e32 v128, v128
	v_exp_f32_e32 v129, v129
	s_nop 0
	v_pk_add_f32 v[128:129], v[128:129], 1.0 op_sel_hi:[1,0]
	s_nop 0
	s_nop 0
	v_rcp_f32_e32 v129, v129
	s_nop 0
	v_rcp_f32_e32 v128, v128
	v_mul_f32_e32 v130, 0xbfb8aa3b, v6
	v_mul_f32_e32 v131, 0xbfb8aa3b, v7
	v_exp_f32_e32 v130, v130
	v_exp_f32_e32 v131, v131
	v_pk_mul_f32 v[128:129], v[4:5], v[128:129]
	v_pk_add_f32 v[130:131], v[130:131], 1.0 op_sel_hi:[1,0]
	s_nop 0
	v_cvt_pk_bf16_f32 v128, v128, v129
	v_rcp_f32_e32 v131, v131
	s_nop 0
	v_rcp_f32_e32 v130, v130
	s_nop 0
	v_pk_mul_f32 v[130:131], v[6:7], v[130:131]
	s_nop 0
	v_cvt_pk_bf16_f32 v129, v130, v131
	v_lshlrev_b32_e32 v130, 4, v157
	v_add3_u32 v130, v144, v130, v133
	ds_write_b64 v130, v[128:129]

; DEV u32x2 pk4(f32x4 v) { u32x2 r = {pk_bf16(v[0], v[1]), pk_bf16(v[2], v[3])}; return r; }
; DEV float fsigmoid(float x) { return 1.f / (1.f + __expf(-x)); }
;   DEV void operator()(f32x4 (&acc)[2][2][4][2], int brow, int bcol, int wr, int wc, int fr, int fq) const {
;     ...
;               for (int j = 0; j < 4; ++j) v[j] = fsigmoid(v[j]);
;               tile_put4(rl, cl, pk4(v));
.LBB0_2078:
	s_andn2_b64 vcc, exec, s[20:21]
	s_cbranch_vccnz .LBB0_2080
	s_waitcnt vmcnt(0)
	v_mul_f32_e32 v128, 0xbfb8aa3b, v0
	v_mul_f32_e32 v129, 0xbfb8aa3b, v1
	v_exp_f32_e32 v128, v128
	v_exp_f32_e32 v129, v129
	s_nop 0
	v_pk_add_f32 v[128:129], v[128:129], 1.0 op_sel_hi:[1,0]
	s_nop 0
	s_nop 0
	v_rcp_f32_e32 v130, v129
	s_nop 0
	v_rcp_f32_e32 v131, v128
	v_mul_f32_e32 v128, 0xbfb8aa3b, v2
	v_mul_f32_e32 v129, 0xbfb8aa3b, v3
	v_exp_f32_e32 v128, v128
	v_exp_f32_e32 v129, v129
	s_nop 0
	v_pk_add_f32 v[128:129], v[128:129], 1.0 op_sel_hi:[1,0]
	s_nop 0
	s_nop 0
	v_rcp_f32_e32 v129, v129
	s_nop 0
	v_rcp_f32_e32 v136, v128
	v_cvt_pk_bf16_f32 v128, v131, v130
	v_lshlrev_b32_e32 v130, 4, v158
	v_cvt_pk_bf16_f32 v129, v136, v129
	v_add3_u32 v130, v144, v130, v133
	ds_write_b64 v130, v[128:129]

; DEV u32x2 pk4(f32x4 v) { u32x2 r = {pk_bf16(v[0], v[1]), pk_bf16(v[2], v[3])}; return r; }
; DEV float fsigmoid(float x) { return 1.f / (1.f + __expf(-x)); }
;   DEV void operator()(f32x4 (&acc)[2][2][4][2], int brow, int bcol, int wr, int wc, int fr, int fq) const {
;     ...
;               for (int j = 0; j < 4; ++j) v[j] = v[j] * fsigmoid(v[j]);
;               tile_put4(rl, cl, pk4(v));
.LBB0_2081:
	s_andn2_b64 vcc, exec, s[20:21]
	s_cbranch_vccnz .LBB0_2083
	s_waitcnt vmcnt(0)
	v_mul_f32_e32 v128, 0xbfb8aa3b, v0
	v_mul_f32_e32 v129, 0xbfb8aa3b, v1
	v_exp_f32_e32 v128, v128
	v_exp_f32_e32 v129, v129
	s_nop 0
	v_pk_add_f32 v[128:129], v[128:129], 1.0 op_sel_hi:[1,0]
	s_nop 0
	s_nop 0
	v_rcp_f32_e32 v129, v129
	s_nop 0
	v_rcp_f32_e32 v128, v128
	v_mul_f32_e32 v130, 0xbfb8aa3b, v2
	v_mul_f32_e32 v131, 0xbfb8aa3b, v3
	v_exp_f32_e32 v130, v130
	v_exp_f32_e32 v131, v131
	v_pk_mul_f32 v[128:129], v[0:1], v[128:129]
	v_pk_add_f32 v[130:131], v[130:131], 1.0 op_sel_hi:[1,0]
	s_nop 0
	v_cvt_pk_bf16_f32 v128, v128, v129
	v_rcp_f32_e32 v131, v131
	s_nop 0
	v_rcp_f32_e32 v130, v130
	s_nop 0
	v_pk_mul_f32 v[130:131], v[2:3], v[130:131]
	s_nop 0
	v_cvt_pk_bf16_f32 v129, v130, v131
	v_lshlrev_b32_e32 v130, 4, v158
	v_add3_u32 v130, v144, v130, v133
	ds_write_b64 v130, v[128:129]
